# GEMM loops: all per-segment s_setprio flips deleted, one static s_setprio 1 for waves 4-7 at each gemm phase prologue (on top of v34)
# speedup vs baseline: 1.0038x; 1.0038x over previous
; __device__ __forceinline__ void xcd_barrier(const XcdBarrier& b) {
;     asm volatile("s_waitcnt vmcnt(0)" ::: "memory");
;     __syncthreads();
;     if (threadIdx.x == 0) {
;         unsigned* bar = b.bar;
;         __builtin_amdgcn_s_waitcnt(0);
;         unsigned nloc = b.st[0], nx = b.st[1];
;         if (nloc == 0u) { xcd_barrier_complete(bar, b.x, nloc, nx); b.st[0] = nloc; b.st[1] = nx; }
.LBB0_109:
	s_mov_b64 s[4:5], s[66:67]
	s_waitcnt vmcnt(0) lgkmcnt(0)
	s_setprio 0
	s_getreg_b32 s6, hwreg(HW_REG_XCC_ID, 0, 4)
	s_waitcnt vmcnt(0)
	s_barrier
	s_and_saveexec_b64 s[0:1], s[26:27]
	s_cbranch_execz .LBB0_161
	v_mov_b32_e32 v0, s96
	s_load_dwordx2 s[4:5], s[4:5], 0xc0
	s_waitcnt vmcnt(0) expcnt(0) lgkmcnt(0)
	ds_read_b32 v3, v0
	v_mov_b32_e32 v0, s97
	ds_read_b32 v2, v0
	s_and_b32 s30, s6, 15
	s_waitcnt lgkmcnt(1)
	v_cmp_ne_u32_e32 vcc, 0, v3
	s_cbranch_vccnz .LBB0_125
	s_add_u32 s6, s4, 0x1200
	s_addc_u32 s7, s5, 0
	s_add_u32 s8, s4, 0x1400
	s_addc_u32 s9, s5, 0
	s_add_u32 s10, s4, 0x1500
	s_addc_u32 s11, s5, 0
	s_add_u32 s12, s4, 0x1600
	s_addc_u32 s13, s5, 0
	s_add_u32 s14, s4, 0x1700
	s_addc_u32 s15, s5, 0
	s_add_u32 s16, s4, 0x1800
	s_addc_u32 s17, s5, 0
	s_add_u32 s18, s4, 0x1900
	s_addc_u32 s19, s5, 0
	s_add_u32 s20, s4, 0x1a00
	s_addc_u32 s21, s5, 0
	s_add_u32 s22, s4, 0x1b00
	s_addc_u32 s23, s5, 0
	s_add_u32 s24, s4, 0x1c00
	s_addc_u32 s25, s5, 0
	s_add_u32 s38, s4, 0x1d00
	s_addc_u32 s39, s5, 0
	s_add_u32 s48, s4, 0x1e00
	s_addc_u32 s49, s5, 0
	s_add_u32 s52, s4, 0x1f00
	s_addc_u32 s53, s5, 0
	s_add_u32 s76, s4, 0x2000
	s_addc_u32 s77, s5, 0
	s_add_u32 s78, s4, 0x2100
	s_addc_u32 s79, s5, 0
	s_add_u32 s80, s4, 0x2200
	s_addc_u32 s81, s5, 0
	s_add_u32 s84, s4, 0x2300
	s_addc_u32 s85, s5, 0
	s_mov_b32 s35, 1
	s_branch .LBB0_113

; #define PG8_STAGE(bufoff, gbase, rows) do { _Pragma("unroll") for (int _i = 0; _i < 2; ++_i) \
;         __builtin_amdgcn_global_load_lds((const unsigned*)((const char*)(gbase) + (rows)[_i]), (LAS unsigned*)(lds + (bufoff) + ldsw + _i * 8192), 16, 0, 0); } while (0)
; #define PG8_BAR __builtin_amdgcn_s_barrier()
; template <class Epi, class Sched>
; __device__ __forceinline__ void gemm_phase(LAS unsigned char* lds, const Sched& S, const Epi& E, const int tid) {
;     const int wid = __builtin_amdgcn_readfirstlane(tid >> 6), lane = tid & 63, wr = wid >> 2, wc = wid & 3, fr = lane & 15, fq = lane >> 4;
;     int sR[2], sC[2], sRbi[2];
; #pragma unroll
;     for (int i = 0; i < 2; ++i) { stage_rc(tid * 16 + i * 8192, sR[i], sC[i]); sRbi[i] = (sR[i] & ~31) + perm32(sR[i] & 31); }
;     const unsigned ldsw = (unsigned)wid * 1024u;
;     const int aoff = lds_byte(wr * 64 + fr, fq * 8), boff = lds_byte(wc * 32 + fr, fq * 8);
;     ...
;     GUnit cur, nxt; int ui = 0;
;     if (!S.next(0, cur)) return;
;     f32x4 acc[2][2][4][2];
; #pragma unroll
;     for (int a = 0; a < 2; ++a)
; #pragma unroll
;         for (int b = 0; b < 2; ++b)
; #pragma unroll
;             for (int m = 0; m < 4; ++m)
; #pragma unroll
;                 for (int n = 0; n < 2; ++n) acc[a][b][m][n] = (f32x4){0.f, 0.f, 0.f, 0.f};
;     bf16x8 At[4][2], B0[2][2], B1[2][2];
;     const char* cA = cur.A; const char* cB = cur.B;
;     constexpr unsigned kstep = (unsigned)(BK * 2);
;     const unsigned lda = cur.lda, ldb = cur.ldb, hA = HALF * lda, hB = HALF * ldb;
;     unsigned vA[2], vB[2];
; #pragma unroll
;     for (int i = 0; i < 2; ++i) { vA[i] = (unsigned)sR[i] * lda + (unsigned)sC[i] * 2u; vB[i] = (unsigned)sRbi[i] * ldb + (unsigned)sC[i] * 2u; }
;     PG8_STAGE(PG8_SB(0, 0), cB, vB); PG8_STAGE(PG8_SB(0, 1), cB + hB, vB); PG8_STAGE(PG8_SA(0, 0), cA, vA); PG8_STAGE(PG8_SA(0, 1), cA + hA, vA);
;     if (wr == 1) PG8_BAR;
.LBB0_171:
.LBB0_172:
	v_ashrrev_i32_e32 v3, 31, v0
	v_lshrrev_b32_e32 v3, 26, v3
	v_add_u32_e32 v3, v0, v3
	v_ashrrev_i32_e32 v10, 6, v3
	v_bfe_i32 v3, v0, 27, 1
	v_lshlrev_b32_e32 v2, 4, v0
	v_lshrrev_b32_e32 v3, 22, v3
	v_add_u32_e32 v3, v2, v3
	v_and_b32_e32 v3, 0xfffffc00, v3
	v_sub_u32_e32 v3, v2, v3
	v_lshrrev_b32_e32 v4, 4, v3
	v_bitop3_b32 v3, v4, v3, 32 bitop3:0x6c
	v_ashrrev_i32_e32 v5, 31, v3
	v_lshrrev_b32_e32 v5, 26, v5
	v_add_u32_e32 v5, v3, v5
	v_lshlrev_b32_e32 v4, 3, v10
	v_ashrrev_i32_e32 v11, 6, v5
	v_and_b32_e32 v5, 0xc0, v5
	v_and_b32_e32 v4, -16, v4
	v_sub_u32_e32 v3, v3, v5
	v_add_u32_e32 v4, v11, v4
	v_ashrrev_i16_sdwa v3, v231, sext(v3) dst_sel:DWORD dst_unused:UNUSED_PAD src0_sel:DWORD src1_sel:BYTE_0
	v_bfe_i32 v12, v3, 0, 16
	v_lshlrev_b32_e32 v3, 1, v4
	v_lshrrev_b32_e32 v5, 2, v4
	v_and_b32_e32 v7, 3, v11
	v_and_b32_e32 v3, 24, v3
	v_and_b32_e32 v5, 4, v5
	v_and_or_b32 v7, v4, s55, v7
	v_add_u32_e32 v2, 0x2000, v2
	v_or3_b32 v3, v7, v5, v3
	v_ashrrev_i32_e32 v5, 31, v2
	v_lshrrev_b32_e32 v5, 22, v5
	v_add_u32_e32 v5, v2, v5
	v_ashrrev_i32_e32 v13, 10, v5
	v_mul_i32_i24_e32 v5, 0x400, v13
	v_sub_u32_e32 v2, v2, v5
	v_lshrrev_b32_e32 v5, 4, v2
	v_bitop3_b32 v2, v5, v2, 32 bitop3:0x6c
	v_ashrrev_i32_e32 v7, 31, v2
	v_lshrrev_b32_e32 v7, 26, v7
	v_add_u32_e32 v7, v2, v7
	v_lshlrev_b32_e32 v5, 3, v13
	v_ashrrev_i32_e32 v14, 6, v7
	v_and_b32_e32 v7, 0xc0, v7
	v_lshlrev_b32_e32 v6, 5, v10
	v_and_b32_e32 v5, -16, v5
	v_sub_u32_e32 v2, v2, v7
	s_ashr_i32 s12, s14, 6
	v_and_b32_e32 v6, 32, v6
	v_add_u32_e32 v5, v14, v5
	v_ashrrev_i16_sdwa v2, v231, sext(v2) dst_sel:DWORD dst_unused:UNUSED_PAD src0_sel:DWORD src1_sel:BYTE_0
	s_lshl_b32 s40, s12, 10
	v_lshlrev_b32_e32 v8, 5, v13
	v_bfe_i32 v15, v2, 0, 16
	v_lshlrev_b32_e32 v2, 1, v5
	v_lshrrev_b32_e32 v7, 2, v5
	v_and_b32_e32 v9, 3, v14
	v_add_lshl_u32 v6, v6, v12, 1
	s_add_i32 s41, s40, 0
	v_and_b32_e32 v8, 32, v8
	v_and_b32_e32 v2, 24, v2
	v_and_b32_e32 v7, 4, v7
	v_and_or_b32 v9, v5, s55, v9
	v_lshl_add_u32 v132, v3, 12, v6
	s_add_i32 m0, s41, 0x10000
	s_ashr_i32 s7, s14, 8
	v_or3_b32 v2, v9, v7, v2
	v_add_lshl_u32 v3, v8, v15, 1
	global_load_lds_dwordx4 v132, s[22:23]
	s_add_i32 m0, s41, 0x12000
	v_lshl_add_u32 v136, v2, 12, v3
	s_add_u32 s8, s22, 0x80000
	global_load_lds_dwordx4 v136, s[22:23]
	s_addc_u32 s9, s23, 0
	s_add_i32 m0, s41, 0x14000
	s_add_i32 s48, s41, 0x2000
	global_load_lds_dwordx4 v132, s[8:9]
	s_add_i32 m0, s41, 0x16000
	v_lshl_add_u32 v130, v4, 12, v6
	global_load_lds_dwordx4 v136, s[8:9]
	s_mov_b32 m0, s41
	s_add_u32 s8, s4, 0x80000
	v_lshl_add_u32 v134, v5, 12, v3
	global_load_lds_dwordx4 v130, s[4:5]
	s_mov_b32 m0, s48
	s_addc_u32 s9, s5, 0
	s_add_i32 s49, s41, 0x4000
	global_load_lds_dwordx4 v134, s[4:5]
	s_mov_b32 m0, s49
	s_add_i32 s52, s41, 0x6000
	global_load_lds_dwordx4 v130, s[8:9]
	s_mov_b32 m0, s52
	v_mov_b32_e32 v133, v1
	global_load_lds_dwordx4 v134, s[8:9]
	v_mov_b32_e32 v137, v1
	v_mov_b32_e32 v131, v1
	v_mov_b32_e32 v135, v1
	s_cmp_eq_u32 s7, 1
	v_lshl_add_u64 v[8:9], s[22:23], 0, v[132:133]
	v_lshl_add_u64 v[6:7], s[22:23], 0, v[136:137]
	v_lshl_add_u64 v[2:3], s[4:5], 0, v[130:131]
	s_cselect_b64 s[8:9], -1, 0
	s_cmp_lg_u32 s7, 1
	v_lshl_add_u64 v[4:5], s[4:5], 0, v[134:135]
	s_cbranch_scc1 .LBB0_174
	s_setprio 1
	s_barrier

; #define PG8_STAGE(bufoff, gbase, rows) do { _Pragma("unroll") for (int _i = 0; _i < 2; ++_i) \
;         __builtin_amdgcn_global_load_lds((const unsigned*)((const char*)(gbase) + (rows)[_i]), (LAS unsigned*)(lds + (bufoff) + ldsw + _i * 8192), 16, 0, 0); } while (0)
; #define PG8_LDA(dst, b, h) do { _Pragma("unroll") for (int m = 0; m < 4; ++m) _Pragma("unroll") for (int k = 0; k < 2; ++k) dst[m][k] = *(const LAS bf16x8*)(lds + PG8_SA(b, h) + aoff + m * 2048 + k * 1024); } while (0)
; #define PG8_LDB(dst, b, h) do { _Pragma("unroll") for (int n = 0; n < 2; ++n) _Pragma("unroll") for (int k = 0; k < 2; ++k) dst[n][k] = *(const LAS bf16x8*)(lds + PG8_SB(b, h) + boff + n * 2048 + k * 1024); } while (0)
; #define PG8_WAIT_V(n) asm volatile("s_waitcnt vmcnt(" #n ")" ::: "memory")
; #define PG8_WAIT_L(n) asm volatile("s_waitcnt lgkmcnt(" #n ")" ::: "memory")
; template <class Epi, class Sched>
; __device__ __forceinline__ void gemm_phase(LAS unsigned char* lds, const Sched& S, const Epi& E, const int tid) {
;     ...
;         for (int t = 0; t < nt; t += 2) {
;             const bool last = (t == nt - 2);
;             const char* a1 = cA + (size_t)(t + 1) * kstep;
;             const char* a2 = last ? nA : cA + (size_t)(t + 2) * kstep; const char* b2 = last ? nB : cB + (size_t)(t + 2) * kstep;
;             const char* a3 = a2 + kstep; const char* b3 = b2 + kstep;
;             PG8_LDB(B0, 0, 0); PG8_LDB(B1, 0, 1); PG8_SCHED; PG8_LDA(At, 0, 0); PG8_STAGE(PG8_SA(1, 1), a1 + hA, vA);
;             PG8_WAIT_V(8); PG8_WAIT_L(0); PG8_BAR; PG8_MMA(0, 0, At, B0); PG8_MMA(0, 1, At, B1); PG8_BAR; PG8_SCHED;
;             PG8_LDA(At, 0, 1); PG8_STAGE(PG8_SB(0, 0), b2, vB); PG8_STAGE(PG8_SB(0, 1), b2 + hB, vB); PG8_STAGE(PG8_SA(0, 0), a2, vA);
;             PG8_WAIT_V(8); PG8_WAIT_L(0); PG8_BAR; PG8_MMA(1, 0, At, B0); PG8_MMA(1, 1, At, B1); PG8_BAR; PG8_SCHED;
;             PG8_LDB(B0, 1, 0); PG8_LDB(B1, 1, 1); PG8_SCHED; PG8_LDA(At, 1, 0); PG8_STAGE(PG8_SA(0, 1), a2 + hA, vA);
;             PG8_WAIT_V(8); PG8_WAIT_L(0); PG8_BAR; PG8_MMA(0, 0, At, B0); PG8_MMA(0, 1, At, B1); PG8_BAR; PG8_SCHED;
;             PG8_LDA(At, 1, 1); PG8_STAGE(PG8_SB(1, 0), b3, vB); PG8_STAGE(PG8_SB(1, 1), b3 + hB, vB); PG8_STAGE(PG8_SA(1, 0), a3, vA);
;             PG8_WAIT_V(8); PG8_WAIT_L(0); PG8_BAR; PG8_MMA(1, 0, At, B0); PG8_MMA(1, 1, At, B1); PG8_BAR; PG8_SCHED;
.LBB0_192:
	s_add_u32 s22, s4, 0xfff80080
	s_addc_u32 s23, s5, -1
	s_add_i32 s87, 0, 0x10000
	s_cmp_eq_u32 s86, 28
	s_cselect_b32 s25, s7, s23
	s_cselect_b32 s24, s21, s22
	v_add_u32_e32 v0, s87, v142
	s_cselect_b32 s23, s38, s85
	s_cselect_b32 s22, s39, s84
	s_add_i32 s50, 0, 0x14000
	ds_read_b128 v[144:147], v0
	ds_read_b128 v[148:151], v0 offset:1024
	ds_read_b128 v[152:155], v0 offset:2048
	ds_read_b128 v[156:159], v0 offset:3072
	v_add_u32_e32 v0, s50, v142
	ds_read_b128 v[160:163], v0
	ds_read_b128 v[164:167], v0 offset:1024
	ds_read_b128 v[168:171], v0 offset:2048
	ds_read_b128 v[172:175], v0 offset:3072
	v_lshl_add_u64 v[208:209], s[4:5], 0, v[138:139]
	s_add_i32 m0, s41, 0xc000
	ds_read_b128 v[176:179], v143
	ds_read_b128 v[180:183], v143 offset:1024
	ds_read_b128 v[184:187], v143 offset:2048
	ds_read_b128 v[188:191], v143 offset:3072
	ds_read_b128 v[192:195], v143 offset:4096
	ds_read_b128 v[196:199], v143 offset:5120
	ds_read_b128 v[200:203], v143 offset:6144
	ds_read_b128 v[204:207], v143 offset:7168
	global_load_lds_dwordx4 v[208:209], off
	v_lshl_add_u64 v[208:209], s[4:5], 0, v[140:141]
	s_add_i32 m0, s41, 0xe000
	s_nop 0
	global_load_lds_dwordx4 v[208:209], off
	s_waitcnt vmcnt(8)
	s_waitcnt lgkmcnt(0)
	s_barrier
	s_waitcnt lgkmcnt(0)
	v_mfma_f32_16x16x32_bf16 v[126:129], v[144:147], v[176:179], v[126:129]
	v_mfma_f32_16x16x32_bf16 v[122:125], v[152:155], v[176:179], v[122:125]
	v_mfma_f32_16x16x32_bf16 v[110:113], v[144:147], v[184:187], v[110:113]
	v_mfma_f32_16x16x32_bf16 v[106:109], v[152:155], v[184:187], v[106:109]
	v_mfma_f32_16x16x32_bf16 v[94:97], v[144:147], v[192:195], v[94:97]
	v_mfma_f32_16x16x32_bf16 v[90:93], v[152:155], v[192:195], v[90:93]
	v_mfma_f32_16x16x32_bf16 v[78:81], v[144:147], v[200:203], v[78:81]
	v_mfma_f32_16x16x32_bf16 v[74:77], v[152:155], v[200:203], v[74:77]
	v_mfma_f32_16x16x32_bf16 v[126:129], v[148:151], v[180:183], v[126:129]
	v_mfma_f32_16x16x32_bf16 v[122:125], v[156:159], v[180:183], v[122:125]
	v_mfma_f32_16x16x32_bf16 v[110:113], v[148:151], v[188:191], v[110:113]
	v_mfma_f32_16x16x32_bf16 v[106:109], v[156:159], v[188:191], v[106:109]
	v_mfma_f32_16x16x32_bf16 v[94:97], v[148:151], v[196:199], v[94:97]
	v_mfma_f32_16x16x32_bf16 v[90:93], v[156:159], v[196:199], v[90:93]
	v_mfma_f32_16x16x32_bf16 v[78:81], v[148:151], v[204:207], v[78:81]
	v_mfma_f32_16x16x32_bf16 v[74:77], v[156:159], v[204:207], v[74:77]
	v_mfma_f32_16x16x32_bf16 v[118:121], v[160:163], v[176:179], v[118:121]
	v_mfma_f32_16x16x32_bf16 v[114:117], v[168:171], v[176:179], v[114:117]
	v_mfma_f32_16x16x32_bf16 v[102:105], v[160:163], v[184:187], v[102:105]
	v_mfma_f32_16x16x32_bf16 v[98:101], v[168:171], v[184:187], v[98:101]
	v_mfma_f32_16x16x32_bf16 v[86:89], v[160:163], v[192:195], v[86:89]
	v_mfma_f32_16x16x32_bf16 v[82:85], v[168:171], v[192:195], v[82:85]
	v_mfma_f32_16x16x32_bf16 v[70:73], v[160:163], v[200:203], v[70:73]
	v_mfma_f32_16x16x32_bf16 v[66:69], v[168:171], v[200:203], v[66:69]
	v_mfma_f32_16x16x32_bf16 v[118:121], v[164:167], v[180:183], v[118:121]
	v_mfma_f32_16x16x32_bf16 v[114:117], v[172:175], v[180:183], v[114:117]
	v_mfma_f32_16x16x32_bf16 v[102:105], v[164:167], v[188:191], v[102:105]
	v_mfma_f32_16x16x32_bf16 v[98:101], v[172:175], v[188:191], v[98:101]
	v_mfma_f32_16x16x32_bf16 v[86:89], v[164:167], v[196:199], v[86:89]
	v_mfma_f32_16x16x32_bf16 v[82:85], v[172:175], v[196:199], v[82:85]
	v_mfma_f32_16x16x32_bf16 v[70:73], v[164:167], v[204:207], v[70:73]
	v_mfma_f32_16x16x32_bf16 v[66:69], v[172:175], v[204:207], v[66:69]
	s_barrier
	s_add_i32 s51, s87, s40
	v_lshl_add_u64 v[208:209], s[22:23], 0, v[132:133]
	s_mov_b32 m0, s51
	ds_read_b128 v[176:179], v143 offset:16384
	ds_read_b128 v[180:183], v143 offset:17408
	ds_read_b128 v[184:187], v143 offset:18432
	ds_read_b128 v[188:191], v143 offset:19456
	ds_read_b128 v[192:195], v143 offset:20480
	ds_read_b128 v[196:199], v143 offset:21504
	ds_read_b128 v[200:203], v143 offset:22528
	ds_read_b128 v[204:207], v143 offset:23552
	global_load_lds_dwordx4 v[208:209], off
	s_add_i32 m0, s51, 0x2000
	s_add_u32 vcc_lo, s22, 0x80000
	v_lshl_add_u64 v[210:211], s[22:23], 0, v[136:137]
	s_addc_u32 vcc_hi, s23, 0
	s_add_i32 s50, s50, s40
	global_load_lds_dwordx4 v[210:211], off
	v_lshl_add_u64 v[212:213], vcc, 0, v[132:133]
	s_mov_b32 m0, s50
	v_lshl_add_u64 v[214:215], s[24:25], 0, v[134:135]
	global_load_lds_dwordx4 v[212:213], off
	v_lshl_add_u64 v[212:213], vcc, 0, v[136:137]
	s_add_i32 m0, s50, 0x2000
	s_nop 0
	global_load_lds_dwordx4 v[212:213], off
	v_lshl_add_u64 v[212:213], s[24:25], 0, v[130:131]
	s_mov_b32 m0, s41
	s_nop 0
	global_load_lds_dwordx4 v[212:213], off
	s_mov_b32 m0, s48
	s_nop 0
	global_load_lds_dwordx4 v[214:215], off
	s_waitcnt vmcnt(8)
	s_waitcnt lgkmcnt(0)
	s_barrier
; #define PG8_STAGE(bufoff, gbase, rows) do { _Pragma("unroll") for (int _i = 0; _i < 2; ++_i) \
;         __builtin_amdgcn_global_load_lds((const unsigned*)((const char*)(gbase) + (rows)[_i]), (LAS unsigned*)(lds + (bufoff) + ldsw + _i * 8192), 16, 0, 0); } while (0)
; #define PG8_LDA(dst, b, h) do { _Pragma("unroll") for (int m = 0; m < 4; ++m) _Pragma("unroll") for (int k = 0; k < 2; ++k) dst[m][k] = *(const LAS bf16x8*)(lds + PG8_SA(b, h) + aoff + m * 2048 + k * 1024); } while (0)
; #define PG8_LDB(dst, b, h) do { _Pragma("unroll") for (int n = 0; n < 2; ++n) _Pragma("unroll") for (int k = 0; k < 2; ++k) dst[n][k] = *(const LAS bf16x8*)(lds + PG8_SB(b, h) + boff + n * 2048 + k * 1024); } while (0)
; #define PG8_MMA(ai, bj, At, Bt) do { __builtin_amdgcn_s_setprio(1); _Pragma("unroll") for (int m = 0; m < 4; ++m) _Pragma("unroll") for (int n = 0; n < 2; ++n) _Pragma("unroll") for (int k = 0; k < 2; ++k) \
;         acc[ai][bj][m][n] = __builtin_amdgcn_mfma_f32_16x16x32_bf16(Bt[n][k], At[m][k], acc[ai][bj][m][n], 0, 0, 0); __builtin_amdgcn_s_setprio(0); } while (0)
; #define PG8_WAIT_V(n) asm volatile("s_waitcnt vmcnt(" #n ")" ::: "memory")
; #define PG8_WAIT_L(n) asm volatile("s_waitcnt lgkmcnt(" #n ")" ::: "memory")
; #define PG8_BAR __builtin_amdgcn_s_barrier()
; #define PG8_SCHED __builtin_amdgcn_sched_barrier(0)
; template <class Epi, class Sched>
; __device__ __forceinline__ void gemm_phase(LAS unsigned char* lds, const Sched& S, const Epi& E, const int tid) {
;     ...
;             PG8_WAIT_V(8); PG8_WAIT_L(0); PG8_BAR; PG8_MMA(1, 0, At, B0); PG8_MMA(1, 1, At, B1); PG8_BAR; PG8_SCHED;
;             PG8_LDB(B0, 1, 0); PG8_LDB(B1, 1, 1); PG8_SCHED; PG8_LDA(At, 1, 0); PG8_STAGE(PG8_SA(0, 1), a2 + hA, vA);
;             PG8_WAIT_V(8); PG8_WAIT_L(0); PG8_BAR; PG8_MMA(0, 0, At, B0); PG8_MMA(0, 1, At, B1); PG8_BAR; PG8_SCHED;
;             PG8_LDA(At, 1, 1); PG8_STAGE(PG8_SB(1, 0), b3, vB); PG8_STAGE(PG8_SB(1, 1), b3 + hB, vB); PG8_STAGE(PG8_SA(1, 0), a3, vA);
;             PG8_WAIT_V(8); PG8_WAIT_L(0); PG8_BAR; PG8_MMA(1, 0, At, B0); PG8_MMA(1, 1, At, B1); PG8_BAR; PG8_SCHED;
	s_waitcnt lgkmcnt(0)
	v_mfma_f32_16x16x32_bf16 v[62:65], v[144:147], v[176:179], v[62:65]
	v_mfma_f32_16x16x32_bf16 v[58:61], v[152:155], v[176:179], v[58:61]
	v_mfma_f32_16x16x32_bf16 v[46:49], v[144:147], v[184:187], v[46:49]
	v_mfma_f32_16x16x32_bf16 v[42:45], v[152:155], v[184:187], v[42:45]
	v_mfma_f32_16x16x32_bf16 v[30:33], v[144:147], v[192:195], v[30:33]
	v_mfma_f32_16x16x32_bf16 v[26:29], v[152:155], v[192:195], v[26:29]
	v_mfma_f32_16x16x32_bf16 v[14:17], v[144:147], v[200:203], v[14:17]
	v_mfma_f32_16x16x32_bf16 v[2:5], v[152:155], v[200:203], v[2:5]
	v_mfma_f32_16x16x32_bf16 v[62:65], v[148:151], v[180:183], v[62:65]
	v_mfma_f32_16x16x32_bf16 v[58:61], v[156:159], v[180:183], v[58:61]
	v_mfma_f32_16x16x32_bf16 v[46:49], v[148:151], v[188:191], v[46:49]
	v_mfma_f32_16x16x32_bf16 v[42:45], v[156:159], v[188:191], v[42:45]
	v_mfma_f32_16x16x32_bf16 v[30:33], v[148:151], v[196:199], v[30:33]
	v_mfma_f32_16x16x32_bf16 v[26:29], v[156:159], v[196:199], v[26:29]
	v_mfma_f32_16x16x32_bf16 v[14:17], v[148:151], v[204:207], v[14:17]
	v_mfma_f32_16x16x32_bf16 v[2:5], v[156:159], v[204:207], v[2:5]
	v_mfma_f32_16x16x32_bf16 v[54:57], v[160:163], v[176:179], v[54:57]
	v_mfma_f32_16x16x32_bf16 v[50:53], v[168:171], v[176:179], v[50:53]
	v_mfma_f32_16x16x32_bf16 v[38:41], v[160:163], v[184:187], v[38:41]
	v_mfma_f32_16x16x32_bf16 v[34:37], v[168:171], v[184:187], v[34:37]
	v_mfma_f32_16x16x32_bf16 v[18:21], v[160:163], v[192:195], v[18:21]
	v_mfma_f32_16x16x32_bf16 v[22:25], v[168:171], v[192:195], v[22:25]
	v_mfma_f32_16x16x32_bf16 v[6:9], v[160:163], v[200:203], v[6:9]
	v_mfma_f32_16x16x32_bf16 v[10:13], v[168:171], v[200:203], v[10:13]
	v_mfma_f32_16x16x32_bf16 v[54:57], v[164:167], v[180:183], v[54:57]
	v_mfma_f32_16x16x32_bf16 v[50:53], v[172:175], v[180:183], v[50:53]
	v_mfma_f32_16x16x32_bf16 v[38:41], v[164:167], v[188:191], v[38:41]
	v_mfma_f32_16x16x32_bf16 v[34:37], v[172:175], v[188:191], v[34:37]
	v_mfma_f32_16x16x32_bf16 v[18:21], v[164:167], v[196:199], v[18:21]
	v_mfma_f32_16x16x32_bf16 v[22:25], v[172:175], v[196:199], v[22:25]
	v_mfma_f32_16x16x32_bf16 v[6:9], v[164:167], v[204:207], v[6:9]
	v_mfma_f32_16x16x32_bf16 v[10:13], v[172:175], v[204:207], v[10:13]
	s_barrier
	s_add_i32 s50, 0, 0x18000
	v_add_u32_e32 v0, s50, v142
	s_add_i32 s51, 0, 0x1c000
	ds_read_b128 v[144:147], v0
	ds_read_b128 v[148:151], v0 offset:1024
	ds_read_b128 v[152:155], v0 offset:2048
	ds_read_b128 v[156:159], v0 offset:3072
	v_add_u32_e32 v0, s51, v142
	ds_read_b128 v[160:163], v0
	ds_read_b128 v[164:167], v0 offset:1024
	ds_read_b128 v[168:171], v0 offset:2048
	ds_read_b128 v[172:175], v0 offset:3072
	s_add_u32 s24, s24, 0x80000
	s_addc_u32 s25, s25, 0
	s_mov_b32 m0, s49
	v_lshl_add_u64 v[216:217], s[24:25], 0, v[130:131]
	ds_read_b128 v[176:179], v143 offset:32768
	ds_read_b128 v[180:183], v143 offset:33792
	ds_read_b128 v[184:187], v143 offset:34816
	ds_read_b128 v[188:191], v143 offset:35840
	ds_read_b128 v[192:195], v143 offset:36864
	ds_read_b128 v[196:199], v143 offset:37888
	ds_read_b128 v[200:203], v143 offset:38912
	ds_read_b128 v[204:207], v143 offset:39936
	global_load_lds_dwordx4 v[216:217], off
	v_lshl_add_u64 v[216:217], s[24:25], 0, v[134:135]
	s_mov_b32 m0, s52
	s_nop 0
	global_load_lds_dwordx4 v[216:217], off
	s_waitcnt vmcnt(8)
	s_waitcnt lgkmcnt(0)
	s_barrier
	s_waitcnt lgkmcnt(0)
	v_mfma_f32_16x16x32_bf16 v[126:129], v[144:147], v[176:179], v[126:129]
	v_mfma_f32_16x16x32_bf16 v[122:125], v[152:155], v[176:179], v[122:125]
	v_mfma_f32_16x16x32_bf16 v[110:113], v[144:147], v[184:187], v[110:113]
	v_mfma_f32_16x16x32_bf16 v[106:109], v[152:155], v[184:187], v[106:109]
	v_mfma_f32_16x16x32_bf16 v[94:97], v[144:147], v[192:195], v[94:97]
	v_mfma_f32_16x16x32_bf16 v[90:93], v[152:155], v[192:195], v[90:93]
	v_mfma_f32_16x16x32_bf16 v[78:81], v[144:147], v[200:203], v[78:81]
	v_mfma_f32_16x16x32_bf16 v[74:77], v[152:155], v[200:203], v[74:77]
	v_mfma_f32_16x16x32_bf16 v[126:129], v[148:151], v[180:183], v[126:129]
	v_mfma_f32_16x16x32_bf16 v[122:125], v[156:159], v[180:183], v[122:125]
	v_mfma_f32_16x16x32_bf16 v[110:113], v[148:151], v[188:191], v[110:113]
	v_mfma_f32_16x16x32_bf16 v[106:109], v[156:159], v[188:191], v[106:109]
	v_mfma_f32_16x16x32_bf16 v[94:97], v[148:151], v[196:199], v[94:97]
	v_mfma_f32_16x16x32_bf16 v[90:93], v[156:159], v[196:199], v[90:93]
	v_mfma_f32_16x16x32_bf16 v[78:81], v[148:151], v[204:207], v[78:81]
	v_mfma_f32_16x16x32_bf16 v[74:77], v[156:159], v[204:207], v[74:77]
	v_mfma_f32_16x16x32_bf16 v[118:121], v[160:163], v[176:179], v[118:121]
	v_mfma_f32_16x16x32_bf16 v[114:117], v[168:171], v[176:179], v[114:117]
	v_mfma_f32_16x16x32_bf16 v[102:105], v[160:163], v[184:187], v[102:105]
	v_mfma_f32_16x16x32_bf16 v[98:101], v[168:171], v[184:187], v[98:101]
	v_mfma_f32_16x16x32_bf16 v[86:89], v[160:163], v[192:195], v[86:89]
	v_mfma_f32_16x16x32_bf16 v[82:85], v[168:171], v[192:195], v[82:85]
	v_mfma_f32_16x16x32_bf16 v[70:73], v[160:163], v[200:203], v[70:73]
	v_mfma_f32_16x16x32_bf16 v[66:69], v[168:171], v[200:203], v[66:69]
	v_mfma_f32_16x16x32_bf16 v[118:121], v[164:167], v[180:183], v[118:121]
	v_mfma_f32_16x16x32_bf16 v[114:117], v[172:175], v[180:183], v[114:117]
	v_mfma_f32_16x16x32_bf16 v[102:105], v[164:167], v[188:191], v[102:105]
	v_mfma_f32_16x16x32_bf16 v[98:101], v[172:175], v[188:191], v[98:101]
	v_mfma_f32_16x16x32_bf16 v[86:89], v[164:167], v[196:199], v[86:89]
	v_mfma_f32_16x16x32_bf16 v[82:85], v[172:175], v[196:199], v[82:85]
	v_mfma_f32_16x16x32_bf16 v[70:73], v[164:167], v[204:207], v[70:73]
	v_mfma_f32_16x16x32_bf16 v[66:69], v[172:175], v[204:207], v[66:69]
	s_barrier
; #define PG8_STAGE(bufoff, gbase, rows) do { _Pragma("unroll") for (int _i = 0; _i < 2; ++_i) \
;         __builtin_amdgcn_global_load_lds((const unsigned*)((const char*)(gbase) + (rows)[_i]), (LAS unsigned*)(lds + (bufoff) + ldsw + _i * 8192), 16, 0, 0); } while (0)
; #define PG8_LDA(dst, b, h) do { _Pragma("unroll") for (int m = 0; m < 4; ++m) _Pragma("unroll") for (int k = 0; k < 2; ++k) dst[m][k] = *(const LAS bf16x8*)(lds + PG8_SA(b, h) + aoff + m * 2048 + k * 1024); } while (0)
; #define PG8_LDB(dst, b, h) do { _Pragma("unroll") for (int n = 0; n < 2; ++n) _Pragma("unroll") for (int k = 0; k < 2; ++k) dst[n][k] = *(const LAS bf16x8*)(lds + PG8_SB(b, h) + boff + n * 2048 + k * 1024); } while (0)
; #define PG8_MMA(ai, bj, At, Bt) do { __builtin_amdgcn_s_setprio(1); _Pragma("unroll") for (int m = 0; m < 4; ++m) _Pragma("unroll") for (int n = 0; n < 2; ++n) _Pragma("unroll") for (int k = 0; k < 2; ++k) \
;         acc[ai][bj][m][n] = __builtin_amdgcn_mfma_f32_16x16x32_bf16(Bt[n][k], At[m][k], acc[ai][bj][m][n], 0, 0, 0); __builtin_amdgcn_s_setprio(0); } while (0)
; #define PG8_WAIT_V(n) asm volatile("s_waitcnt vmcnt(" #n ")" ::: "memory")
; #define PG8_WAIT_L(n) asm volatile("s_waitcnt lgkmcnt(" #n ")" ::: "memory")
; #define PG8_BAR __builtin_amdgcn_s_barrier()
; #define PG8_SCHED __builtin_amdgcn_sched_barrier(0)
; template <class Epi, class Sched>
; __device__ __forceinline__ void gemm_phase(LAS unsigned char* lds, const Sched& S, const Epi& E, const int tid) {
;     ...
;             PG8_LDB(B0, 1, 0); PG8_LDB(B1, 1, 1); PG8_SCHED; PG8_LDA(At, 1, 0); PG8_STAGE(PG8_SA(0, 1), a2 + hA, vA);
;             PG8_WAIT_V(8); PG8_WAIT_L(0); PG8_BAR; PG8_MMA(0, 0, At, B0); PG8_MMA(0, 1, At, B1); PG8_BAR; PG8_SCHED;
;             PG8_LDA(At, 1, 1); PG8_STAGE(PG8_SB(1, 0), b3, vB); PG8_STAGE(PG8_SB(1, 1), b3 + hB, vB); PG8_STAGE(PG8_SA(1, 0), a3, vA);
;             PG8_WAIT_V(8); PG8_WAIT_L(0); PG8_BAR; PG8_MMA(1, 0, At, B0); PG8_MMA(1, 1, At, B1); PG8_BAR; PG8_SCHED;
;         }
	s_add_i32 s24, s50, s40
	v_lshl_add_u64 v[208:209], v[208:209], 0, s[82:83]
	s_mov_b32 m0, s24
	ds_read_b128 v[176:179], v143 offset:49152
	ds_read_b128 v[180:183], v143 offset:50176
	ds_read_b128 v[184:187], v143 offset:51200
	ds_read_b128 v[188:191], v143 offset:52224
	ds_read_b128 v[192:195], v143 offset:53248
	ds_read_b128 v[196:199], v143 offset:54272
	ds_read_b128 v[200:203], v143 offset:55296
	ds_read_b128 v[204:207], v143 offset:56320
	global_load_lds_dwordx4 v[208:209], off
	s_add_i32 m0, s24, 0x2000
	s_add_u32 s22, s22, 0x80080
	v_lshl_add_u64 v[208:209], v[210:211], 0, s[82:83]
	s_addc_u32 s23, s23, 0
	s_add_i32 s24, s51, s40
	global_load_lds_dwordx4 v[208:209], off
	v_lshl_add_u64 v[208:209], s[22:23], 0, v[132:133]
	s_mov_b32 m0, s24
	s_nop 0
	global_load_lds_dwordx4 v[208:209], off
	v_lshl_add_u64 v[208:209], s[22:23], 0, v[136:137]
	s_add_i32 m0, s24, 0x2000
	s_nop 0
	global_load_lds_dwordx4 v[208:209], off
	v_lshl_add_u64 v[208:209], v[212:213], 0, s[82:83]
	s_mov_b32 m0, s79
	s_nop 0
	global_load_lds_dwordx4 v[208:209], off
	v_lshl_add_u64 v[208:209], v[214:215], 0, s[82:83]
	s_mov_b32 m0, s80
	s_nop 0
	global_load_lds_dwordx4 v[208:209], off
	s_waitcnt vmcnt(8)
	s_waitcnt lgkmcnt(0)
	s_barrier
	s_waitcnt lgkmcnt(0)
	v_mfma_f32_16x16x32_bf16 v[62:65], v[144:147], v[176:179], v[62:65]
	v_mfma_f32_16x16x32_bf16 v[58:61], v[152:155], v[176:179], v[58:61]
	v_mfma_f32_16x16x32_bf16 v[46:49], v[144:147], v[184:187], v[46:49]
	v_mfma_f32_16x16x32_bf16 v[42:45], v[152:155], v[184:187], v[42:45]
	v_mfma_f32_16x16x32_bf16 v[30:33], v[144:147], v[192:195], v[30:33]
	v_mfma_f32_16x16x32_bf16 v[26:29], v[152:155], v[192:195], v[26:29]
	v_mfma_f32_16x16x32_bf16 v[14:17], v[144:147], v[200:203], v[14:17]
	v_mfma_f32_16x16x32_bf16 v[2:5], v[152:155], v[200:203], v[2:5]
	v_mfma_f32_16x16x32_bf16 v[62:65], v[148:151], v[180:183], v[62:65]
	v_mfma_f32_16x16x32_bf16 v[58:61], v[156:159], v[180:183], v[58:61]
	v_mfma_f32_16x16x32_bf16 v[46:49], v[148:151], v[188:191], v[46:49]
	v_mfma_f32_16x16x32_bf16 v[42:45], v[156:159], v[188:191], v[42:45]
	v_mfma_f32_16x16x32_bf16 v[30:33], v[148:151], v[196:199], v[30:33]
	v_mfma_f32_16x16x32_bf16 v[26:29], v[156:159], v[196:199], v[26:29]
	v_mfma_f32_16x16x32_bf16 v[14:17], v[148:151], v[204:207], v[14:17]
	v_mfma_f32_16x16x32_bf16 v[2:5], v[156:159], v[204:207], v[2:5]
	v_mfma_f32_16x16x32_bf16 v[54:57], v[160:163], v[176:179], v[54:57]
	v_mfma_f32_16x16x32_bf16 v[50:53], v[168:171], v[176:179], v[50:53]
	v_mfma_f32_16x16x32_bf16 v[38:41], v[160:163], v[184:187], v[38:41]
	v_mfma_f32_16x16x32_bf16 v[34:37], v[168:171], v[184:187], v[34:37]
	v_mfma_f32_16x16x32_bf16 v[18:21], v[160:163], v[192:195], v[18:21]
	v_mfma_f32_16x16x32_bf16 v[22:25], v[168:171], v[192:195], v[22:25]
	v_mfma_f32_16x16x32_bf16 v[6:9], v[160:163], v[200:203], v[6:9]
	v_mfma_f32_16x16x32_bf16 v[10:13], v[168:171], v[200:203], v[10:13]
	v_mfma_f32_16x16x32_bf16 v[54:57], v[164:167], v[180:183], v[54:57]
	v_mfma_f32_16x16x32_bf16 v[50:53], v[172:175], v[180:183], v[50:53]
	v_mfma_f32_16x16x32_bf16 v[38:41], v[164:167], v[188:191], v[38:41]
	v_mfma_f32_16x16x32_bf16 v[34:37], v[172:175], v[188:191], v[34:37]
	v_mfma_f32_16x16x32_bf16 v[18:21], v[164:167], v[196:199], v[18:21]
	v_mfma_f32_16x16x32_bf16 v[22:25], v[172:175], v[196:199], v[22:25]
	v_mfma_f32_16x16x32_bf16 v[6:9], v[164:167], v[204:207], v[6:9]
	v_mfma_f32_16x16x32_bf16 v[10:13], v[172:175], v[204:207], v[10:13]
	s_barrier
	s_add_i32 s86, s86, 2
	s_add_u32 s4, s4, 0x100
	s_addc_u32 s5, s5, 0
	s_add_u32 s84, s84, 0x100
	s_addc_u32 s85, s85, 0
	s_cmp_gt_u32 s86, 29
	s_cbranch_scc0 .LBB0_192
	s_and_b64 vcc, exec, s[10:11]
	s_cbranch_vccz .LBB0_195
	s_barrier

; __device__ __forceinline__ void xcd_barrier(const XcdBarrier& b) {
;     asm volatile("s_waitcnt vmcnt(0)" ::: "memory");
;     __syncthreads();
;     if (threadIdx.x == 0) {
;         unsigned* bar = b.bar;
;         __builtin_amdgcn_s_waitcnt(0);
;         unsigned nloc = b.st[0], nx = b.st[1];
;         if (nloc == 0u) { xcd_barrier_complete(bar, b.x, nloc, nx); b.st[0] = nloc; b.st[1] = nx; }
.LBB0_273:
	s_mov_b64 s[4:5], s[66:67]
	s_waitcnt vmcnt(0) lgkmcnt(0)
	s_setprio 0
	s_getreg_b32 s6, hwreg(HW_REG_XCC_ID, 0, 4)
	s_waitcnt vmcnt(0)
	s_waitcnt vmcnt(0) lgkmcnt(0)
	s_barrier
	s_and_saveexec_b64 s[0:1], s[26:27]
	s_cbranch_execz .LBB0_325
	v_mov_b32_e32 v0, s96
	s_load_dwordx2 s[4:5], s[4:5], 0xc0
	s_waitcnt vmcnt(0) expcnt(0) lgkmcnt(0)
	ds_read_b32 v3, v0
	v_mov_b32_e32 v0, s97
	ds_read_b32 v2, v0
	s_and_b32 s30, s6, 15
	s_waitcnt lgkmcnt(1)
	v_cmp_ne_u32_e32 vcc, 0, v3
	s_cbranch_vccnz .LBB0_289
	s_add_u32 s6, s4, 0x1200
	s_addc_u32 s7, s5, 0
	s_add_u32 s8, s4, 0x1400
	s_addc_u32 s9, s5, 0
	s_add_u32 s10, s4, 0x1500
	s_addc_u32 s11, s5, 0
	s_add_u32 s12, s4, 0x1600
	s_addc_u32 s13, s5, 0
	s_add_u32 s14, s4, 0x1700
	s_addc_u32 s15, s5, 0
	s_add_u32 s16, s4, 0x1800
	s_addc_u32 s17, s5, 0
	s_add_u32 s18, s4, 0x1900
	s_addc_u32 s19, s5, 0
	s_add_u32 s20, s4, 0x1a00
	s_addc_u32 s21, s5, 0
	s_add_u32 s22, s4, 0x1b00
	s_addc_u32 s23, s5, 0
	s_add_u32 s24, s4, 0x1c00
	s_addc_u32 s25, s5, 0
	s_add_u32 s38, s4, 0x1d00
	s_addc_u32 s39, s5, 0
	s_add_u32 s48, s4, 0x1e00
	s_addc_u32 s49, s5, 0
	s_add_u32 s52, s4, 0x1f00
	s_addc_u32 s53, s5, 0
	s_add_u32 s76, s4, 0x2000
	s_addc_u32 s77, s5, 0
	s_add_u32 s78, s4, 0x2100
	s_addc_u32 s79, s5, 0
	s_add_u32 s80, s4, 0x2200
	s_addc_u32 s81, s5, 0
	s_add_u32 s84, s4, 0x2300
	s_addc_u32 s85, s5, 0
	s_mov_b32 s35, 1
	s_branch .LBB0_277

; __device__ __forceinline__ void xcd_barrier(const XcdBarrier& b) {
;     asm volatile("s_waitcnt vmcnt(0)" ::: "memory");
;     __syncthreads();
;     if (threadIdx.x == 0) {
;         unsigned* bar = b.bar;
;         __builtin_amdgcn_s_waitcnt(0);
;         unsigned nloc = b.st[0], nx = b.st[1];
;         if (nloc == 0u) { xcd_barrier_complete(bar, b.x, nloc, nx); b.st[0] = nloc; b.st[1] = nx; }
.LBB0_328:
	s_mov_b64 s[4:5], s[66:67]
	s_waitcnt vmcnt(0) lgkmcnt(0)
	s_setprio 0
	s_getreg_b32 s6, hwreg(HW_REG_XCC_ID, 0, 4)
	s_waitcnt vmcnt(0)
	s_barrier
	s_and_saveexec_b64 s[0:1], s[26:27]
	s_mov_b32 s50, 0x3b800000
	s_cbranch_execz .LBB0_380
	v_mov_b32_e32 v0, s96
	s_load_dwordx2 s[4:5], s[4:5], 0xc0
	s_waitcnt vmcnt(0) expcnt(0) lgkmcnt(0)
	ds_read_b32 v3, v0
	v_mov_b32_e32 v0, s97
	ds_read_b32 v2, v0
	s_and_b32 s30, s6, 15
	s_waitcnt lgkmcnt(1)
	v_cmp_ne_u32_e32 vcc, 0, v3
	s_cbranch_vccnz .LBB0_344
	s_add_u32 s6, s4, 0x1200
	s_addc_u32 s7, s5, 0
	s_add_u32 s8, s4, 0x1400
	s_addc_u32 s9, s5, 0
	s_add_u32 s10, s4, 0x1500
	s_addc_u32 s11, s5, 0
	s_add_u32 s12, s4, 0x1600
	s_addc_u32 s13, s5, 0
	s_add_u32 s14, s4, 0x1700
	s_addc_u32 s15, s5, 0
	s_add_u32 s16, s4, 0x1800
	s_addc_u32 s17, s5, 0
	s_add_u32 s18, s4, 0x1900
	s_addc_u32 s19, s5, 0
	s_add_u32 s20, s4, 0x1a00
	s_addc_u32 s21, s5, 0
	s_add_u32 s22, s4, 0x1b00
	s_addc_u32 s23, s5, 0
	s_add_u32 s24, s4, 0x1c00
	s_addc_u32 s25, s5, 0
	s_add_u32 s38, s4, 0x1d00
	s_addc_u32 s39, s5, 0
	s_add_u32 s48, s4, 0x1e00
	s_addc_u32 s49, s5, 0
	s_add_u32 s52, s4, 0x1f00
	s_addc_u32 s53, s5, 0
	s_add_u32 s76, s4, 0x2000
	s_addc_u32 s77, s5, 0
	s_add_u32 s78, s4, 0x2100
	s_addc_u32 s79, s5, 0
	s_add_u32 s80, s4, 0x2200
	s_addc_u32 s81, s5, 0
	s_add_u32 s84, s4, 0x2300
	s_addc_u32 s85, s5, 0
	s_mov_b32 s35, 1
	s_branch .LBB0_332

; __device__ __forceinline__ void xcd_barrier(const XcdBarrier& b) {
;     asm volatile("s_waitcnt vmcnt(0)" ::: "memory");
;     __syncthreads();
;     if (threadIdx.x == 0) {
;         unsigned* bar = b.bar;
;         __builtin_amdgcn_s_waitcnt(0);
;         unsigned nloc = b.st[0], nx = b.st[1];
;         if (nloc == 0u) { xcd_barrier_complete(bar, b.x, nloc, nx); b.st[0] = nloc; b.st[1] = nx; }
.LBB0_483:
	s_mov_b64 s[4:5], s[66:67]
	s_waitcnt vmcnt(0) lgkmcnt(0)
	s_setprio 0
	s_getreg_b32 s6, hwreg(HW_REG_XCC_ID, 0, 4)
	s_waitcnt vmcnt(0)
	s_waitcnt lgkmcnt(0)
	s_barrier
	s_and_saveexec_b64 s[0:1], s[26:27]
	s_cbranch_execz .LBB0_535
	v_mov_b32_e32 v0, s96
	s_load_dwordx2 s[4:5], s[4:5], 0xc0
	s_waitcnt vmcnt(0) expcnt(0) lgkmcnt(0)
	ds_read_b32 v3, v0
	v_mov_b32_e32 v0, s97
	ds_read_b32 v2, v0
	s_and_b32 s30, s6, 15
	s_waitcnt lgkmcnt(1)
	v_cmp_ne_u32_e32 vcc, 0, v3
	s_cbranch_vccnz .LBB0_499
	s_add_u32 s6, s4, 0x1200
	s_addc_u32 s7, s5, 0
	s_add_u32 s8, s4, 0x1400
	s_addc_u32 s9, s5, 0
	s_add_u32 s10, s4, 0x1500
	s_addc_u32 s11, s5, 0
	s_add_u32 s12, s4, 0x1600
	s_addc_u32 s13, s5, 0
	s_add_u32 s14, s4, 0x1700
	s_addc_u32 s15, s5, 0
	s_add_u32 s16, s4, 0x1800
	s_addc_u32 s17, s5, 0
	s_add_u32 s18, s4, 0x1900
	s_addc_u32 s19, s5, 0
	s_add_u32 s20, s4, 0x1a00
	s_addc_u32 s21, s5, 0
	s_add_u32 s22, s4, 0x1b00
	s_addc_u32 s23, s5, 0
	s_add_u32 s24, s4, 0x1c00
	s_addc_u32 s25, s5, 0
	s_add_u32 s38, s4, 0x1d00
	s_addc_u32 s39, s5, 0
	s_add_u32 s48, s4, 0x1e00
	s_addc_u32 s49, s5, 0
	s_add_u32 s76, s4, 0x1f00
	s_addc_u32 s77, s5, 0
	s_add_u32 s78, s4, 0x2000
	s_addc_u32 s79, s5, 0
	s_add_u32 s80, s4, 0x2100
	s_addc_u32 s81, s5, 0
	s_add_u32 s84, s4, 0x2200
	s_addc_u32 s85, s5, 0
	s_add_u32 s86, s4, 0x2300
	s_addc_u32 s87, s5, 0
	s_mov_b32 s35, 1
	s_branch .LBB0_487

; __device__ __forceinline__ void xcd_barrier(const XcdBarrier& b) {
;     asm volatile("s_waitcnt vmcnt(0)" ::: "memory");
;     __syncthreads();
;     if (threadIdx.x == 0) {
;         unsigned* bar = b.bar;
;         __builtin_amdgcn_s_waitcnt(0);
;         unsigned nloc = b.st[0], nx = b.st[1];
;         if (nloc == 0u) { xcd_barrier_complete(bar, b.x, nloc, nx); b.st[0] = nloc; b.st[1] = nx; }
.LBB0_541:
	s_mov_b64 s[4:5], s[66:67]
	s_waitcnt vmcnt(0) lgkmcnt(0)
	s_setprio 0
	s_getreg_b32 s6, hwreg(HW_REG_XCC_ID, 0, 4)
	s_waitcnt vmcnt(0)
	s_waitcnt lgkmcnt(0)
	s_barrier
	s_and_saveexec_b64 s[0:1], s[26:27]
	s_cbranch_execz .LBB0_593
	v_mov_b32_e32 v0, s96
	s_load_dwordx2 s[4:5], s[4:5], 0xc0
	s_waitcnt vmcnt(0) expcnt(0) lgkmcnt(0)
	ds_read_b32 v3, v0
	v_mov_b32_e32 v0, s97
	ds_read_b32 v2, v0
	s_and_b32 s30, s6, 15
	s_waitcnt lgkmcnt(1)
	v_cmp_ne_u32_e32 vcc, 0, v3
	s_cbranch_vccnz .LBB0_557
	s_add_u32 s6, s4, 0x1200
	s_addc_u32 s7, s5, 0
	s_add_u32 s8, s4, 0x1400
	s_addc_u32 s9, s5, 0
	s_add_u32 s10, s4, 0x1500
	s_addc_u32 s11, s5, 0
	s_add_u32 s12, s4, 0x1600
	s_addc_u32 s13, s5, 0
	s_add_u32 s14, s4, 0x1700
	s_addc_u32 s15, s5, 0
	s_add_u32 s16, s4, 0x1800
	s_addc_u32 s17, s5, 0
	s_add_u32 s18, s4, 0x1900
	s_addc_u32 s19, s5, 0
	s_add_u32 s20, s4, 0x1a00
	s_addc_u32 s21, s5, 0
	s_add_u32 s22, s4, 0x1b00
	s_addc_u32 s23, s5, 0
	s_add_u32 s24, s4, 0x1c00
	s_addc_u32 s25, s5, 0
	s_add_u32 s38, s4, 0x1d00
	s_addc_u32 s39, s5, 0
	s_add_u32 s48, s4, 0x1e00
	s_addc_u32 s49, s5, 0
	s_add_u32 s52, s4, 0x1f00
	s_addc_u32 s53, s5, 0
	s_add_u32 s76, s4, 0x2000
	s_addc_u32 s77, s5, 0
	s_add_u32 s78, s4, 0x2100
	s_addc_u32 s79, s5, 0
	s_add_u32 s80, s4, 0x2200
	s_addc_u32 s81, s5, 0
	s_add_u32 s84, s4, 0x2300
	s_addc_u32 s85, s5, 0
	s_mov_b32 s35, 1
	s_branch .LBB0_545

; #define PG8_STAGE(bufoff, gbase, rows) do { _Pragma("unroll") for (int _i = 0; _i < 2; ++_i) \
;         __builtin_amdgcn_global_load_lds((const unsigned*)((const char*)(gbase) + (rows)[_i]), (LAS unsigned*)(lds + (bufoff) + ldsw + _i * 8192), 16, 0, 0); } while (0)
; #define PG8_BAR __builtin_amdgcn_s_barrier()
; template <class Epi, class Sched>
; __device__ __forceinline__ void gemm_phase(LAS unsigned char* lds, const Sched& S, const Epi& E, const int tid) {
;     const int wid = __builtin_amdgcn_readfirstlane(tid >> 6), lane = tid & 63, wr = wid >> 2, wc = wid & 3, fr = lane & 15, fq = lane >> 4;
;     int sR[2], sC[2], sRbi[2];
; #pragma unroll
;     for (int i = 0; i < 2; ++i) { stage_rc(tid * 16 + i * 8192, sR[i], sC[i]); sRbi[i] = (sR[i] & ~31) + perm32(sR[i] & 31); }
;     const unsigned ldsw = (unsigned)wid * 1024u;
;     const int aoff = lds_byte(wr * 64 + fr, fq * 8), boff = lds_byte(wc * 32 + fr, fq * 8);
;     ...
;     GUnit cur, nxt; int ui = 0;
;     if (!S.next(0, cur)) return;
;     f32x4 acc[2][2][4][2];
; #pragma unroll
;     for (int a = 0; a < 2; ++a)
; #pragma unroll
;         for (int b = 0; b < 2; ++b)
; #pragma unroll
;             for (int m = 0; m < 4; ++m)
; #pragma unroll
;                 for (int n = 0; n < 2; ++n) acc[a][b][m][n] = (f32x4){0.f, 0.f, 0.f, 0.f};
;     bf16x8 At[4][2], B0[2][2], B1[2][2];
;     const char* cA = cur.A; const char* cB = cur.B;
;     constexpr unsigned kstep = (unsigned)(BK * 2);
;     const unsigned lda = cur.lda, ldb = cur.ldb, hA = HALF * lda, hB = HALF * ldb;
;     unsigned vA[2], vB[2];
; #pragma unroll
;     for (int i = 0; i < 2; ++i) { vA[i] = (unsigned)sR[i] * lda + (unsigned)sC[i] * 2u; vB[i] = (unsigned)sRbi[i] * ldb + (unsigned)sC[i] * 2u; }
;     PG8_STAGE(PG8_SB(0, 0), cB, vB); PG8_STAGE(PG8_SB(0, 1), cB + hB, vB); PG8_STAGE(PG8_SA(0, 0), cA, vA); PG8_STAGE(PG8_SA(0, 1), cA + hA, vA);
;     if (wr == 1) PG8_BAR;
.LBB0_596:
	v_mov_b32_e32 v15, v222
	v_cndmask_b32_e64 v0, 0, 1, s[44:45]
	s_mov_b64 s[0:1], s[66:67]
	v_cmp_ne_u32_e64 s[6:7], 1, v0
	s_andn2_b64 vcc, exec, s[44:45]
	v_readfirstlane_b32 s10, v15
	s_cbranch_vccnz .LBB0_616
	v_lshlrev_b32_e32 v2, 4, v15
	v_add_u32_e32 v3, 0x2000, v2
	v_ashrrev_i32_e32 v0, 31, v3
	v_lshrrev_b32_e32 v0, 22, v0
	v_add_u32_e32 v0, v3, v0
	v_ashrrev_i32_e32 v0, 10, v0
	v_mul_i32_i24_e32 v4, 0x400, v0
	v_sub_u32_e32 v3, v3, v4
	v_lshrrev_b32_e32 v4, 4, v3
	v_bitop3_b32 v3, v4, v3, 32 bitop3:0x6c
	v_ashrrev_i32_e32 v4, 31, v3
	v_lshrrev_b32_e32 v4, 26, v4
	v_add_u32_e32 v4, v3, v4
	v_ashrrev_i32_e32 v10, 6, v4
	v_and_b32_e32 v4, 0xc0, v4
	v_lshlrev_b32_e32 v5, 3, v0
	v_sub_u32_e32 v3, v3, v4
	v_bfe_i32 v4, v15, 27, 1
	s_load_dwordx2 s[8:9], s[0:1], 0xc0
	v_and_b32_e32 v5, -16, v5
	v_lshrrev_b32_e32 v4, 22, v4
	v_add_u32_e32 v5, v10, v5
	v_add_u32_e32 v4, v2, v4
	v_and_b32_e32 v6, 3, v10
	v_lshrrev_b32_e32 v7, 2, v5
	v_lshlrev_b32_e32 v8, 1, v5
	v_and_b32_e32 v4, 0xfffffc00, v4
	v_and_or_b32 v6, v5, s55, v6
	v_and_b32_e32 v7, 4, v7
	v_and_b32_e32 v8, 24, v8
	v_sub_u32_e32 v2, v2, v4
	v_or3_b32 v6, v6, v7, v8
	v_lshrrev_b32_e32 v4, 4, v2
	v_ashrrev_i32_e32 v7, 31, v15
	s_waitcnt lgkmcnt(0)
	s_add_u32 s35, s8, 0xa480000
	v_bitop3_b32 v2, v4, v2, 32 bitop3:0x6c
	v_lshrrev_b32_e32 v7, 26, v7
	s_addc_u32 s37, s9, 0
	s_lshl_b32 s0, s30, 23
	v_ashrrev_i32_e32 v4, 31, v2
	v_add_u32_e32 v7, v15, v7
	s_add_u32 s0, s8, s0
	v_lshrrev_b32_e32 v4, 26, v4
	v_ashrrev_i32_e32 v13, 6, v7
	s_addc_u32 s1, s9, 0
	v_add_u32_e32 v4, v2, v4
	v_lshlrev_b32_e32 v7, 3, v13
	s_add_u32 s38, s0, 0x2c00000
	v_ashrrev_i32_e32 v12, 6, v4
	v_and_b32_e32 v7, -16, v7
	s_addc_u32 s39, s1, 0
	s_ashr_i32 s11, s10, 6
	v_add_u32_e32 v7, v12, v7
	v_and_b32_e32 v4, 0xc0, v4
	s_ashr_i32 s12, s10, 8
	s_lshl_b32 s40, s11, 10
	v_and_b32_e32 v8, 3, v12
	v_lshrrev_b32_e32 v9, 2, v7
	v_lshlrev_b32_e32 v14, 1, v7
	v_sub_u32_e32 v2, v2, v4
	v_and_or_b32 v8, v7, s55, v8
	v_and_b32_e32 v9, 4, v9
	v_and_b32_e32 v14, 24, v14
	v_ashrrev_i16_sdwa v2, v231, sext(v2) dst_sel:DWORD dst_unused:UNUSED_PAD src0_sel:DWORD src1_sel:BYTE_0
	s_add_u32 s4, s35, s56
	v_or3_b32 v8, v8, v9, v14
	v_bfe_i32 v14, v2, 0, 16
	v_lshlrev_b32_e32 v2, 5, v13
	s_addc_u32 s5, s37, s57
	v_ashrrev_i16_sdwa v3, v231, sext(v3) dst_sel:DWORD dst_unused:UNUSED_PAD src0_sel:DWORD src1_sel:BYTE_0
	v_and_b32_e32 v2, 32, v2
	s_add_u32 s22, s38, s58
	v_bfe_i32 v11, v3, 0, 16
	v_lshlrev_b32_e32 v3, 5, v0
	s_addc_u32 s23, s39, s59
	v_add_lshl_u32 v2, v2, v14, 1
	s_add_i32 s41, s40, 0
	v_and_b32_e32 v3, 32, v3
	v_lshl_add_u32 v132, v8, 12, v2
	s_add_i32 m0, s41, 0x10000
	v_lshl_add_u32 v130, v7, 12, v2
	v_add_lshl_u32 v2, v3, v11, 1
	global_load_lds_dwordx4 v132, s[22:23]
	s_add_i32 m0, s41, 0x12000
	v_lshl_add_u32 v136, v6, 12, v2
	s_add_u32 s0, s22, 0x80000
	global_load_lds_dwordx4 v136, s[22:23]
	s_addc_u32 s1, s23, 0
	s_add_i32 m0, s41, 0x14000
	s_add_i32 s48, s41, 0x2000
	global_load_lds_dwordx4 v132, s[0:1]
	s_add_i32 m0, s41, 0x16000
	v_lshl_add_u32 v134, v5, 12, v2
	global_load_lds_dwordx4 v136, s[0:1]
	s_mov_b32 m0, s41
	s_add_u32 s0, s4, 0x80000
	global_load_lds_dwordx4 v130, s[4:5]
	s_mov_b32 m0, s48
	s_addc_u32 s1, s5, 0
	s_add_i32 s49, s41, 0x4000
	global_load_lds_dwordx4 v134, s[4:5]
	s_mov_b32 m0, s49
	s_add_i32 s52, s41, 0x6000
	global_load_lds_dwordx4 v130, s[0:1]
	s_mov_b32 m0, s52
	v_mov_b32_e32 v133, v1
	global_load_lds_dwordx4 v134, s[0:1]
	v_mov_b32_e32 v137, v1
	v_mov_b32_e32 v131, v1
	v_mov_b32_e32 v135, v1
	s_cmp_eq_u32 s12, 1
	v_lshl_add_u64 v[8:9], s[22:23], 0, v[132:133]
	v_lshl_add_u64 v[6:7], s[22:23], 0, v[136:137]
	v_lshl_add_u64 v[2:3], s[4:5], 0, v[130:131]
	s_cselect_b64 s[0:1], -1, 0
	s_cmp_lg_u32 s12, 1
	v_lshl_add_u64 v[4:5], s[4:5], 0, v[134:135]
	s_cbranch_scc1 .LBB0_599
	s_setprio 1
	s_barrier

; #define PG8_STAGE(bufoff, gbase, rows) do { _Pragma("unroll") for (int _i = 0; _i < 2; ++_i) \
;         __builtin_amdgcn_global_load_lds((const unsigned*)((const char*)(gbase) + (rows)[_i]), (LAS unsigned*)(lds + (bufoff) + ldsw + _i * 8192), 16, 0, 0); } while (0)
; #define PG8_LDA(dst, b, h) do { _Pragma("unroll") for (int m = 0; m < 4; ++m) _Pragma("unroll") for (int k = 0; k < 2; ++k) dst[m][k] = *(const LAS bf16x8*)(lds + PG8_SA(b, h) + aoff + m * 2048 + k * 1024); } while (0)
; #define PG8_LDB(dst, b, h) do { _Pragma("unroll") for (int n = 0; n < 2; ++n) _Pragma("unroll") for (int k = 0; k < 2; ++k) dst[n][k] = *(const LAS bf16x8*)(lds + PG8_SB(b, h) + boff + n * 2048 + k * 1024); } while (0)
; #define PG8_MMA(ai, bj, At, Bt) do { __builtin_amdgcn_s_setprio(1); _Pragma("unroll") for (int m = 0; m < 4; ++m) _Pragma("unroll") for (int n = 0; n < 2; ++n) _Pragma("unroll") for (int k = 0; k < 2; ++k) \
;         acc[ai][bj][m][n] = __builtin_amdgcn_mfma_f32_16x16x32_bf16(Bt[n][k], At[m][k], acc[ai][bj][m][n], 0, 0, 0); __builtin_amdgcn_s_setprio(0); } while (0)
; #define PG8_WAIT_V(n) asm volatile("s_waitcnt vmcnt(" #n ")" ::: "memory")
; #define PG8_WAIT_L(n) asm volatile("s_waitcnt lgkmcnt(" #n ")" ::: "memory")
; #define PG8_BAR __builtin_amdgcn_s_barrier()
; #define PG8_SCHED __builtin_amdgcn_sched_barrier(0)
; template <class Epi, class Sched>
; __device__ __forceinline__ void gemm_phase(LAS unsigned char* lds, const Sched& S, const Epi& E, const int tid) {
;     ...
;         for (int t = 0; t < nt; t += 2) {
;             const bool last = (t == nt - 2);
;             const char* a1 = cA + (size_t)(t + 1) * kstep;
;             const char* a2 = last ? nA : cA + (size_t)(t + 2) * kstep; const char* b2 = last ? nB : cB + (size_t)(t + 2) * kstep;
;             const char* a3 = a2 + kstep; const char* b3 = b2 + kstep;
;             PG8_LDB(B0, 0, 0); PG8_LDB(B1, 0, 1); PG8_SCHED; PG8_LDA(At, 0, 0); PG8_STAGE(PG8_SA(1, 1), a1 + hA, vA);
;             PG8_WAIT_V(8); PG8_WAIT_L(0); PG8_BAR; PG8_MMA(0, 0, At, B0); PG8_MMA(0, 1, At, B1); PG8_BAR; PG8_SCHED;
;             PG8_LDA(At, 0, 1); PG8_STAGE(PG8_SB(0, 0), b2, vB); PG8_STAGE(PG8_SB(0, 1), b2 + hB, vB); PG8_STAGE(PG8_SA(0, 0), a2, vA);
;             PG8_WAIT_V(8); PG8_WAIT_L(0); PG8_BAR; PG8_MMA(1, 0, At, B0); PG8_MMA(1, 1, At, B1); PG8_BAR; PG8_SCHED;
.LBB0_609:
	s_add_u32 s22, s4, 0xfff80080
	s_addc_u32 s23, s5, -1
	s_add_i32 s50, 0, 0x10000
	s_cmp_eq_u32 s21, 28
	s_cselect_b32 s25, s15, s23
	s_cselect_b32 s24, s14, s22
	v_add_u32_e32 v0, s50, v142
	s_cselect_b32 s23, s17, s19
	s_cselect_b32 s22, s16, s13
	s_add_i32 s51, 0, 0x14000
	ds_read_b128 v[144:147], v0
	ds_read_b128 v[148:151], v0 offset:1024
	ds_read_b128 v[152:155], v0 offset:2048
	ds_read_b128 v[156:159], v0 offset:3072
	v_add_u32_e32 v0, s51, v142
	ds_read_b128 v[160:163], v0
	ds_read_b128 v[164:167], v0 offset:1024
	ds_read_b128 v[168:171], v0 offset:2048
	ds_read_b128 v[172:175], v0 offset:3072
	v_lshl_add_u64 v[208:209], s[4:5], 0, v[138:139]
	s_add_i32 m0, s41, 0xc000
	ds_read_b128 v[176:179], v143
	ds_read_b128 v[180:183], v143 offset:1024
	ds_read_b128 v[184:187], v143 offset:2048
	ds_read_b128 v[188:191], v143 offset:3072
	ds_read_b128 v[192:195], v143 offset:4096
	ds_read_b128 v[196:199], v143 offset:5120
	ds_read_b128 v[200:203], v143 offset:6144
	ds_read_b128 v[204:207], v143 offset:7168
	global_load_lds_dwordx4 v[208:209], off
	v_lshl_add_u64 v[208:209], s[4:5], 0, v[140:141]
	s_add_i32 m0, s41, 0xe000
	s_nop 0
	global_load_lds_dwordx4 v[208:209], off
	s_waitcnt vmcnt(8)
	s_waitcnt lgkmcnt(0)
	s_barrier
	s_waitcnt lgkmcnt(0)
	v_mfma_f32_16x16x32_bf16 v[126:129], v[144:147], v[176:179], v[126:129]
	v_mfma_f32_16x16x32_bf16 v[122:125], v[152:155], v[176:179], v[122:125]
	v_mfma_f32_16x16x32_bf16 v[110:113], v[144:147], v[184:187], v[110:113]
	v_mfma_f32_16x16x32_bf16 v[106:109], v[152:155], v[184:187], v[106:109]
	v_mfma_f32_16x16x32_bf16 v[94:97], v[144:147], v[192:195], v[94:97]
	v_mfma_f32_16x16x32_bf16 v[90:93], v[152:155], v[192:195], v[90:93]
	v_mfma_f32_16x16x32_bf16 v[78:81], v[144:147], v[200:203], v[78:81]
	v_mfma_f32_16x16x32_bf16 v[74:77], v[152:155], v[200:203], v[74:77]
	v_mfma_f32_16x16x32_bf16 v[126:129], v[148:151], v[180:183], v[126:129]
	v_mfma_f32_16x16x32_bf16 v[122:125], v[156:159], v[180:183], v[122:125]
	v_mfma_f32_16x16x32_bf16 v[110:113], v[148:151], v[188:191], v[110:113]
	v_mfma_f32_16x16x32_bf16 v[106:109], v[156:159], v[188:191], v[106:109]
	v_mfma_f32_16x16x32_bf16 v[94:97], v[148:151], v[196:199], v[94:97]
	v_mfma_f32_16x16x32_bf16 v[90:93], v[156:159], v[196:199], v[90:93]
	v_mfma_f32_16x16x32_bf16 v[78:81], v[148:151], v[204:207], v[78:81]
	v_mfma_f32_16x16x32_bf16 v[74:77], v[156:159], v[204:207], v[74:77]
	v_mfma_f32_16x16x32_bf16 v[118:121], v[160:163], v[176:179], v[118:121]
	v_mfma_f32_16x16x32_bf16 v[114:117], v[168:171], v[176:179], v[114:117]
	v_mfma_f32_16x16x32_bf16 v[102:105], v[160:163], v[184:187], v[102:105]
	v_mfma_f32_16x16x32_bf16 v[98:101], v[168:171], v[184:187], v[98:101]
	v_mfma_f32_16x16x32_bf16 v[86:89], v[160:163], v[192:195], v[86:89]
	v_mfma_f32_16x16x32_bf16 v[82:85], v[168:171], v[192:195], v[82:85]
	v_mfma_f32_16x16x32_bf16 v[70:73], v[160:163], v[200:203], v[70:73]
	v_mfma_f32_16x16x32_bf16 v[66:69], v[168:171], v[200:203], v[66:69]
	v_mfma_f32_16x16x32_bf16 v[118:121], v[164:167], v[180:183], v[118:121]
	v_mfma_f32_16x16x32_bf16 v[114:117], v[172:175], v[180:183], v[114:117]
	v_mfma_f32_16x16x32_bf16 v[102:105], v[164:167], v[188:191], v[102:105]
	v_mfma_f32_16x16x32_bf16 v[98:101], v[172:175], v[188:191], v[98:101]
	v_mfma_f32_16x16x32_bf16 v[86:89], v[164:167], v[196:199], v[86:89]
	v_mfma_f32_16x16x32_bf16 v[82:85], v[172:175], v[196:199], v[82:85]
	v_mfma_f32_16x16x32_bf16 v[70:73], v[164:167], v[204:207], v[70:73]
	v_mfma_f32_16x16x32_bf16 v[66:69], v[172:175], v[204:207], v[66:69]
	s_barrier
	s_add_i32 s50, s50, s40
	v_lshl_add_u64 v[208:209], s[22:23], 0, v[132:133]
	s_mov_b32 m0, s50
	ds_read_b128 v[176:179], v143 offset:16384
	ds_read_b128 v[180:183], v143 offset:17408
	ds_read_b128 v[184:187], v143 offset:18432
	ds_read_b128 v[188:191], v143 offset:19456
	ds_read_b128 v[192:195], v143 offset:20480
	ds_read_b128 v[196:199], v143 offset:21504
	ds_read_b128 v[200:203], v143 offset:22528
	ds_read_b128 v[204:207], v143 offset:23552
	global_load_lds_dwordx4 v[208:209], off
	s_add_i32 m0, s50, 0x2000
	s_add_u32 s78, s22, 0x80000
	v_lshl_add_u64 v[210:211], s[22:23], 0, v[136:137]
	s_addc_u32 s79, s23, 0
	s_add_i32 s50, s51, s40
	global_load_lds_dwordx4 v[210:211], off
	v_lshl_add_u64 v[212:213], s[78:79], 0, v[132:133]
	s_mov_b32 m0, s50
	v_lshl_add_u64 v[214:215], s[24:25], 0, v[134:135]
	global_load_lds_dwordx4 v[212:213], off
	v_lshl_add_u64 v[212:213], s[78:79], 0, v[136:137]
	s_add_i32 m0, s50, 0x2000
	s_nop 0
	global_load_lds_dwordx4 v[212:213], off
	v_lshl_add_u64 v[212:213], s[24:25], 0, v[130:131]
	s_mov_b32 m0, s41
	s_nop 0
	global_load_lds_dwordx4 v[212:213], off
	s_mov_b32 m0, s48
	s_nop 0
	global_load_lds_dwordx4 v[214:215], off
	s_waitcnt vmcnt(8)
	s_waitcnt lgkmcnt(0)
	s_barrier
; #define PG8_STAGE(bufoff, gbase, rows) do { _Pragma("unroll") for (int _i = 0; _i < 2; ++_i) \
;         __builtin_amdgcn_global_load_lds((const unsigned*)((const char*)(gbase) + (rows)[_i]), (LAS unsigned*)(lds + (bufoff) + ldsw + _i * 8192), 16, 0, 0); } while (0)
; #define PG8_LDA(dst, b, h) do { _Pragma("unroll") for (int m = 0; m < 4; ++m) _Pragma("unroll") for (int k = 0; k < 2; ++k) dst[m][k] = *(const LAS bf16x8*)(lds + PG8_SA(b, h) + aoff + m * 2048 + k * 1024); } while (0)
; #define PG8_LDB(dst, b, h) do { _Pragma("unroll") for (int n = 0; n < 2; ++n) _Pragma("unroll") for (int k = 0; k < 2; ++k) dst[n][k] = *(const LAS bf16x8*)(lds + PG8_SB(b, h) + boff + n * 2048 + k * 1024); } while (0)
; #define PG8_MMA(ai, bj, At, Bt) do { __builtin_amdgcn_s_setprio(1); _Pragma("unroll") for (int m = 0; m < 4; ++m) _Pragma("unroll") for (int n = 0; n < 2; ++n) _Pragma("unroll") for (int k = 0; k < 2; ++k) \
;         acc[ai][bj][m][n] = __builtin_amdgcn_mfma_f32_16x16x32_bf16(Bt[n][k], At[m][k], acc[ai][bj][m][n], 0, 0, 0); __builtin_amdgcn_s_setprio(0); } while (0)
; #define PG8_WAIT_V(n) asm volatile("s_waitcnt vmcnt(" #n ")" ::: "memory")
; #define PG8_WAIT_L(n) asm volatile("s_waitcnt lgkmcnt(" #n ")" ::: "memory")
; #define PG8_BAR __builtin_amdgcn_s_barrier()
; #define PG8_SCHED __builtin_amdgcn_sched_barrier(0)
; template <class Epi, class Sched>
; __device__ __forceinline__ void gemm_phase(LAS unsigned char* lds, const Sched& S, const Epi& E, const int tid) {
;     ...
;             PG8_WAIT_V(8); PG8_WAIT_L(0); PG8_BAR; PG8_MMA(1, 0, At, B0); PG8_MMA(1, 1, At, B1); PG8_BAR; PG8_SCHED;
;             PG8_LDB(B0, 1, 0); PG8_LDB(B1, 1, 1); PG8_SCHED; PG8_LDA(At, 1, 0); PG8_STAGE(PG8_SA(0, 1), a2 + hA, vA);
;             PG8_WAIT_V(8); PG8_WAIT_L(0); PG8_BAR; PG8_MMA(0, 0, At, B0); PG8_MMA(0, 1, At, B1); PG8_BAR; PG8_SCHED;
	s_waitcnt lgkmcnt(0)
	v_mfma_f32_16x16x32_bf16 v[62:65], v[144:147], v[176:179], v[62:65]
	v_mfma_f32_16x16x32_bf16 v[58:61], v[152:155], v[176:179], v[58:61]
	v_mfma_f32_16x16x32_bf16 v[46:49], v[144:147], v[184:187], v[46:49]
	v_mfma_f32_16x16x32_bf16 v[42:45], v[152:155], v[184:187], v[42:45]
	v_mfma_f32_16x16x32_bf16 v[22:25], v[144:147], v[192:195], v[22:25]
	v_mfma_f32_16x16x32_bf16 v[18:21], v[152:155], v[192:195], v[18:21]
	v_mfma_f32_16x16x32_bf16 v[6:9], v[144:147], v[200:203], v[6:9]
	v_mfma_f32_16x16x32_bf16 v[2:5], v[152:155], v[200:203], v[2:5]
	v_mfma_f32_16x16x32_bf16 v[62:65], v[148:151], v[180:183], v[62:65]
	v_mfma_f32_16x16x32_bf16 v[58:61], v[156:159], v[180:183], v[58:61]
	v_mfma_f32_16x16x32_bf16 v[46:49], v[148:151], v[188:191], v[46:49]
	v_mfma_f32_16x16x32_bf16 v[42:45], v[156:159], v[188:191], v[42:45]
	v_mfma_f32_16x16x32_bf16 v[22:25], v[148:151], v[196:199], v[22:25]
	v_mfma_f32_16x16x32_bf16 v[18:21], v[156:159], v[196:199], v[18:21]
	v_mfma_f32_16x16x32_bf16 v[6:9], v[148:151], v[204:207], v[6:9]
	v_mfma_f32_16x16x32_bf16 v[2:5], v[156:159], v[204:207], v[2:5]
	v_mfma_f32_16x16x32_bf16 v[54:57], v[160:163], v[176:179], v[54:57]
	v_mfma_f32_16x16x32_bf16 v[50:53], v[168:171], v[176:179], v[50:53]
	v_mfma_f32_16x16x32_bf16 v[38:41], v[160:163], v[184:187], v[38:41]
	v_mfma_f32_16x16x32_bf16 v[26:29], v[168:171], v[184:187], v[26:29]
	v_mfma_f32_16x16x32_bf16 v[34:37], v[160:163], v[192:195], v[34:37]
	v_mfma_f32_16x16x32_bf16 v[30:33], v[168:171], v[192:195], v[30:33]
	v_mfma_f32_16x16x32_bf16 v[14:17], v[160:163], v[200:203], v[14:17]
	v_mfma_f32_16x16x32_bf16 v[10:13], v[168:171], v[200:203], v[10:13]
	v_mfma_f32_16x16x32_bf16 v[54:57], v[164:167], v[180:183], v[54:57]
	v_mfma_f32_16x16x32_bf16 v[50:53], v[172:175], v[180:183], v[50:53]
	v_mfma_f32_16x16x32_bf16 v[38:41], v[164:167], v[188:191], v[38:41]
	v_mfma_f32_16x16x32_bf16 v[26:29], v[172:175], v[188:191], v[26:29]
	v_mfma_f32_16x16x32_bf16 v[34:37], v[164:167], v[196:199], v[34:37]
	v_mfma_f32_16x16x32_bf16 v[30:33], v[172:175], v[196:199], v[30:33]
	v_mfma_f32_16x16x32_bf16 v[14:17], v[164:167], v[204:207], v[14:17]
	v_mfma_f32_16x16x32_bf16 v[10:13], v[172:175], v[204:207], v[10:13]
	s_barrier
	s_add_i32 s50, 0, 0x18000
	v_add_u32_e32 v0, s50, v142
	s_add_i32 s51, 0, 0x1c000
	ds_read_b128 v[144:147], v0
	ds_read_b128 v[148:151], v0 offset:1024
	ds_read_b128 v[152:155], v0 offset:2048
	ds_read_b128 v[156:159], v0 offset:3072
	v_add_u32_e32 v0, s51, v142
	ds_read_b128 v[160:163], v0
	ds_read_b128 v[164:167], v0 offset:1024
	ds_read_b128 v[168:171], v0 offset:2048
	ds_read_b128 v[172:175], v0 offset:3072
	s_add_u32 s24, s24, 0x80000
	s_addc_u32 s25, s25, 0
	s_mov_b32 m0, s49
	v_lshl_add_u64 v[216:217], s[24:25], 0, v[130:131]
	ds_read_b128 v[176:179], v143 offset:32768
	ds_read_b128 v[180:183], v143 offset:33792
	ds_read_b128 v[184:187], v143 offset:34816
	ds_read_b128 v[188:191], v143 offset:35840
	ds_read_b128 v[192:195], v143 offset:36864
	ds_read_b128 v[196:199], v143 offset:37888
	ds_read_b128 v[200:203], v143 offset:38912
	ds_read_b128 v[204:207], v143 offset:39936
	global_load_lds_dwordx4 v[216:217], off
	v_lshl_add_u64 v[216:217], s[24:25], 0, v[134:135]
	s_mov_b32 m0, s52
	s_nop 0
	global_load_lds_dwordx4 v[216:217], off
	s_waitcnt vmcnt(8)
	s_waitcnt lgkmcnt(0)
	s_barrier
	s_waitcnt lgkmcnt(0)
	v_mfma_f32_16x16x32_bf16 v[126:129], v[144:147], v[176:179], v[126:129]
	v_mfma_f32_16x16x32_bf16 v[122:125], v[152:155], v[176:179], v[122:125]
	v_mfma_f32_16x16x32_bf16 v[110:113], v[144:147], v[184:187], v[110:113]
	v_mfma_f32_16x16x32_bf16 v[106:109], v[152:155], v[184:187], v[106:109]
	v_mfma_f32_16x16x32_bf16 v[94:97], v[144:147], v[192:195], v[94:97]
	v_mfma_f32_16x16x32_bf16 v[90:93], v[152:155], v[192:195], v[90:93]
	v_mfma_f32_16x16x32_bf16 v[78:81], v[144:147], v[200:203], v[78:81]
	v_mfma_f32_16x16x32_bf16 v[74:77], v[152:155], v[200:203], v[74:77]
	v_mfma_f32_16x16x32_bf16 v[126:129], v[148:151], v[180:183], v[126:129]
	v_mfma_f32_16x16x32_bf16 v[122:125], v[156:159], v[180:183], v[122:125]
	v_mfma_f32_16x16x32_bf16 v[110:113], v[148:151], v[188:191], v[110:113]
	v_mfma_f32_16x16x32_bf16 v[106:109], v[156:159], v[188:191], v[106:109]
	v_mfma_f32_16x16x32_bf16 v[94:97], v[148:151], v[196:199], v[94:97]
	v_mfma_f32_16x16x32_bf16 v[90:93], v[156:159], v[196:199], v[90:93]
	v_mfma_f32_16x16x32_bf16 v[78:81], v[148:151], v[204:207], v[78:81]
	v_mfma_f32_16x16x32_bf16 v[74:77], v[156:159], v[204:207], v[74:77]
	v_mfma_f32_16x16x32_bf16 v[118:121], v[160:163], v[176:179], v[118:121]
	v_mfma_f32_16x16x32_bf16 v[114:117], v[168:171], v[176:179], v[114:117]
	v_mfma_f32_16x16x32_bf16 v[102:105], v[160:163], v[184:187], v[102:105]
	v_mfma_f32_16x16x32_bf16 v[98:101], v[168:171], v[184:187], v[98:101]
	v_mfma_f32_16x16x32_bf16 v[86:89], v[160:163], v[192:195], v[86:89]
	v_mfma_f32_16x16x32_bf16 v[82:85], v[168:171], v[192:195], v[82:85]
	v_mfma_f32_16x16x32_bf16 v[70:73], v[160:163], v[200:203], v[70:73]
	v_mfma_f32_16x16x32_bf16 v[66:69], v[168:171], v[200:203], v[66:69]
	v_mfma_f32_16x16x32_bf16 v[118:121], v[164:167], v[180:183], v[118:121]
	v_mfma_f32_16x16x32_bf16 v[114:117], v[172:175], v[180:183], v[114:117]
	v_mfma_f32_16x16x32_bf16 v[102:105], v[164:167], v[188:191], v[102:105]
	v_mfma_f32_16x16x32_bf16 v[98:101], v[172:175], v[188:191], v[98:101]
	v_mfma_f32_16x16x32_bf16 v[86:89], v[164:167], v[196:199], v[86:89]
	v_mfma_f32_16x16x32_bf16 v[82:85], v[172:175], v[196:199], v[82:85]
	v_mfma_f32_16x16x32_bf16 v[70:73], v[164:167], v[204:207], v[70:73]
	v_mfma_f32_16x16x32_bf16 v[66:69], v[172:175], v[204:207], v[66:69]
	s_barrier
; #define PG8_STAGE(bufoff, gbase, rows) do { _Pragma("unroll") for (int _i = 0; _i < 2; ++_i) \
;         __builtin_amdgcn_global_load_lds((const unsigned*)((const char*)(gbase) + (rows)[_i]), (LAS unsigned*)(lds + (bufoff) + ldsw + _i * 8192), 16, 0, 0); } while (0)
; #define PG8_LDA(dst, b, h) do { _Pragma("unroll") for (int m = 0; m < 4; ++m) _Pragma("unroll") for (int k = 0; k < 2; ++k) dst[m][k] = *(const LAS bf16x8*)(lds + PG8_SA(b, h) + aoff + m * 2048 + k * 1024); } while (0)
; #define PG8_MMA(ai, bj, At, Bt) do { __builtin_amdgcn_s_setprio(1); _Pragma("unroll") for (int m = 0; m < 4; ++m) _Pragma("unroll") for (int n = 0; n < 2; ++n) _Pragma("unroll") for (int k = 0; k < 2; ++k) \
;         acc[ai][bj][m][n] = __builtin_amdgcn_mfma_f32_16x16x32_bf16(Bt[n][k], At[m][k], acc[ai][bj][m][n], 0, 0, 0); __builtin_amdgcn_s_setprio(0); } while (0)
; #define PG8_WAIT_V(n) asm volatile("s_waitcnt vmcnt(" #n ")" ::: "memory")
; #define PG8_WAIT_L(n) asm volatile("s_waitcnt lgkmcnt(" #n ")" ::: "memory")
; #define PG8_BAR __builtin_amdgcn_s_barrier()
; #define PG8_SCHED __builtin_amdgcn_sched_barrier(0)
; template <class Epi, class Sched>
; __device__ __forceinline__ void gemm_phase(LAS unsigned char* lds, const Sched& S, const Epi& E, const int tid) {
;     ...
;             PG8_LDA(At, 1, 1); PG8_STAGE(PG8_SB(1, 0), b3, vB); PG8_STAGE(PG8_SB(1, 1), b3 + hB, vB); PG8_STAGE(PG8_SA(1, 0), a3, vA);
;             PG8_WAIT_V(8); PG8_WAIT_L(0); PG8_BAR; PG8_MMA(1, 0, At, B0); PG8_MMA(1, 1, At, B1); PG8_BAR; PG8_SCHED;
;         }
;         if (wr == 0) PG8_BAR;
	s_add_i32 s24, s50, s40
	v_lshl_add_u64 v[208:209], v[208:209], 0, s[82:83]
	s_mov_b32 m0, s24
	ds_read_b128 v[176:179], v143 offset:49152
	ds_read_b128 v[180:183], v143 offset:50176
	ds_read_b128 v[184:187], v143 offset:51200
	ds_read_b128 v[188:191], v143 offset:52224
	ds_read_b128 v[192:195], v143 offset:53248
	ds_read_b128 v[196:199], v143 offset:54272
	ds_read_b128 v[200:203], v143 offset:55296
	ds_read_b128 v[204:207], v143 offset:56320
	global_load_lds_dwordx4 v[208:209], off
	s_add_i32 m0, s24, 0x2000
	s_add_u32 s22, s22, 0x80080
	v_lshl_add_u64 v[208:209], v[210:211], 0, s[82:83]
	s_addc_u32 s23, s23, 0
	s_add_i32 s24, s51, s40
	global_load_lds_dwordx4 v[208:209], off
	v_lshl_add_u64 v[208:209], s[22:23], 0, v[132:133]
	s_mov_b32 m0, s24
	s_nop 0
	global_load_lds_dwordx4 v[208:209], off
	v_lshl_add_u64 v[208:209], s[22:23], 0, v[136:137]
	s_add_i32 m0, s24, 0x2000
	s_nop 0
	global_load_lds_dwordx4 v[208:209], off
	v_lshl_add_u64 v[208:209], v[212:213], 0, s[82:83]
	s_mov_b32 m0, s61
	s_nop 0
	global_load_lds_dwordx4 v[208:209], off
	v_lshl_add_u64 v[208:209], v[214:215], 0, s[82:83]
	s_mov_b32 m0, s64
	s_nop 0
	global_load_lds_dwordx4 v[208:209], off
	s_waitcnt vmcnt(8)
	s_waitcnt lgkmcnt(0)
	s_barrier
	s_waitcnt lgkmcnt(0)
	v_mfma_f32_16x16x32_bf16 v[62:65], v[144:147], v[176:179], v[62:65]
	v_mfma_f32_16x16x32_bf16 v[58:61], v[152:155], v[176:179], v[58:61]
	v_mfma_f32_16x16x32_bf16 v[46:49], v[144:147], v[184:187], v[46:49]
	v_mfma_f32_16x16x32_bf16 v[42:45], v[152:155], v[184:187], v[42:45]
	v_mfma_f32_16x16x32_bf16 v[22:25], v[144:147], v[192:195], v[22:25]
	v_mfma_f32_16x16x32_bf16 v[18:21], v[152:155], v[192:195], v[18:21]
	v_mfma_f32_16x16x32_bf16 v[6:9], v[144:147], v[200:203], v[6:9]
	v_mfma_f32_16x16x32_bf16 v[2:5], v[152:155], v[200:203], v[2:5]
	v_mfma_f32_16x16x32_bf16 v[62:65], v[148:151], v[180:183], v[62:65]
	v_mfma_f32_16x16x32_bf16 v[58:61], v[156:159], v[180:183], v[58:61]
	v_mfma_f32_16x16x32_bf16 v[46:49], v[148:151], v[188:191], v[46:49]
	v_mfma_f32_16x16x32_bf16 v[42:45], v[156:159], v[188:191], v[42:45]
	v_mfma_f32_16x16x32_bf16 v[22:25], v[148:151], v[196:199], v[22:25]
	v_mfma_f32_16x16x32_bf16 v[18:21], v[156:159], v[196:199], v[18:21]
	v_mfma_f32_16x16x32_bf16 v[6:9], v[148:151], v[204:207], v[6:9]
	v_mfma_f32_16x16x32_bf16 v[2:5], v[156:159], v[204:207], v[2:5]
	v_mfma_f32_16x16x32_bf16 v[54:57], v[160:163], v[176:179], v[54:57]
	v_mfma_f32_16x16x32_bf16 v[50:53], v[168:171], v[176:179], v[50:53]
	v_mfma_f32_16x16x32_bf16 v[38:41], v[160:163], v[184:187], v[38:41]
	v_mfma_f32_16x16x32_bf16 v[26:29], v[168:171], v[184:187], v[26:29]
	v_mfma_f32_16x16x32_bf16 v[34:37], v[160:163], v[192:195], v[34:37]
	v_mfma_f32_16x16x32_bf16 v[30:33], v[168:171], v[192:195], v[30:33]
	v_mfma_f32_16x16x32_bf16 v[14:17], v[160:163], v[200:203], v[14:17]
	v_mfma_f32_16x16x32_bf16 v[10:13], v[168:171], v[200:203], v[10:13]
	v_mfma_f32_16x16x32_bf16 v[54:57], v[164:167], v[180:183], v[54:57]
	v_mfma_f32_16x16x32_bf16 v[50:53], v[172:175], v[180:183], v[50:53]
	v_mfma_f32_16x16x32_bf16 v[38:41], v[164:167], v[188:191], v[38:41]
	v_mfma_f32_16x16x32_bf16 v[26:29], v[172:175], v[188:191], v[26:29]
	v_mfma_f32_16x16x32_bf16 v[34:37], v[164:167], v[196:199], v[34:37]
	v_mfma_f32_16x16x32_bf16 v[30:33], v[172:175], v[196:199], v[30:33]
	v_mfma_f32_16x16x32_bf16 v[14:17], v[164:167], v[204:207], v[14:17]
	v_mfma_f32_16x16x32_bf16 v[10:13], v[172:175], v[204:207], v[10:13]
	s_barrier
	s_add_i32 s21, s21, 2
	s_add_u32 s4, s4, 0x100
	s_addc_u32 s5, s5, 0
	s_add_u32 s13, s13, 0x100
	s_addc_u32 s19, s19, 0
	s_cmp_gt_u32 s21, 29
	s_cbranch_scc0 .LBB0_609
	s_and_b64 vcc, exec, s[8:9]
	s_cbranch_vccz .LBB0_612
	s_barrier

; __device__ __forceinline__ void xcd_barrier(const XcdBarrier& b) {
;     asm volatile("s_waitcnt vmcnt(0)" ::: "memory");
;     __syncthreads();
;     if (threadIdx.x == 0) {
;         unsigned* bar = b.bar;
;         __builtin_amdgcn_s_waitcnt(0);
;         unsigned nloc = b.st[0], nx = b.st[1];
;         if (nloc == 0u) { xcd_barrier_complete(bar, b.x, nloc, nx); b.st[0] = nloc; b.st[1] = nx; }
.LBB0_616:
	s_mov_b64 s[4:5], s[66:67]
	s_waitcnt vmcnt(0) lgkmcnt(0)
	s_setprio 0
	s_getreg_b32 s8, hwreg(HW_REG_XCC_ID, 0, 4)
	s_waitcnt vmcnt(0)
	s_waitcnt vmcnt(0) lgkmcnt(0)
	s_barrier
	s_and_saveexec_b64 s[0:1], s[26:27]
	s_cbranch_execz .LBB0_668
	v_mov_b32_e32 v0, s96
	s_load_dwordx2 s[4:5], s[4:5], 0xc0
	s_waitcnt vmcnt(0) expcnt(0) lgkmcnt(0)
	ds_read_b32 v3, v0
	v_mov_b32_e32 v0, s97
	ds_read_b32 v2, v0
	s_and_b32 s35, s8, 15
	s_waitcnt lgkmcnt(1)
	v_cmp_ne_u32_e32 vcc, 0, v3
	s_cbranch_vccnz .LBB0_632
	s_add_u32 s8, s4, 0x1200
	s_addc_u32 s9, s5, 0
	s_add_u32 s10, s4, 0x1400
	s_addc_u32 s11, s5, 0
	s_add_u32 s12, s4, 0x1500
	s_addc_u32 s13, s5, 0
	s_add_u32 s14, s4, 0x1600
	s_addc_u32 s15, s5, 0
	s_add_u32 s16, s4, 0x1700
	s_addc_u32 s17, s5, 0
	s_add_u32 s18, s4, 0x1800
	s_addc_u32 s19, s5, 0
	s_add_u32 s20, s4, 0x1900
	s_addc_u32 s21, s5, 0
	s_add_u32 s22, s4, 0x1a00
	s_addc_u32 s23, s5, 0
	s_add_u32 s24, s4, 0x1b00
	s_addc_u32 s25, s5, 0
	s_add_u32 s38, s4, 0x1c00
	s_addc_u32 s39, s5, 0
	s_add_u32 s48, s4, 0x1d00
	s_addc_u32 s49, s5, 0
	s_add_u32 s52, s4, 0x1e00
	s_addc_u32 s53, s5, 0
	s_add_u32 s76, s4, 0x1f00
	s_addc_u32 s77, s5, 0
	s_add_u32 s78, s4, 0x2000
	s_addc_u32 s79, s5, 0
	s_add_u32 s80, s4, 0x2100
	s_addc_u32 s81, s5, 0
	s_add_u32 s84, s4, 0x2200
	s_addc_u32 s85, s5, 0
	s_add_u32 s86, s4, 0x2300
	s_addc_u32 s87, s5, 0
	s_mov_b32 s37, 1
	s_branch .LBB0_620

; #define PG8_STAGE(bufoff, gbase, rows) do { _Pragma("unroll") for (int _i = 0; _i < 2; ++_i) \
;         __builtin_amdgcn_global_load_lds((const unsigned*)((const char*)(gbase) + (rows)[_i]), (LAS unsigned*)(lds + (bufoff) + ldsw + _i * 8192), 16, 0, 0); } while (0)
; #define PG8_BAR __builtin_amdgcn_s_barrier()
; template <class Epi, class Sched>
; __device__ __forceinline__ void gemm_phase(LAS unsigned char* lds, const Sched& S, const Epi& E, const int tid) {
;     const int wid = __builtin_amdgcn_readfirstlane(tid >> 6), lane = tid & 63, wr = wid >> 2, wc = wid & 3, fr = lane & 15, fq = lane >> 4;
;     int sR[2], sC[2], sRbi[2];
; #pragma unroll
;     for (int i = 0; i < 2; ++i) { stage_rc(tid * 16 + i * 8192, sR[i], sC[i]); sRbi[i] = (sR[i] & ~31) + perm32(sR[i] & 31); }
;     const unsigned ldsw = (unsigned)wid * 1024u;
;     const int aoff = lds_byte(wr * 64 + fr, fq * 8), boff = lds_byte(wc * 32 + fr, fq * 8);
;     ...
;     GUnit cur, nxt; int ui = 0;
;     if (!S.next(0, cur)) return;
;     f32x4 acc[2][2][4][2];
; #pragma unroll
;     for (int a = 0; a < 2; ++a)
; #pragma unroll
;         for (int b = 0; b < 2; ++b)
; #pragma unroll
;             for (int m = 0; m < 4; ++m)
; #pragma unroll
;                 for (int n = 0; n < 2; ++n) acc[a][b][m][n] = (f32x4){0.f, 0.f, 0.f, 0.f};
;     bf16x8 At[4][2], B0[2][2], B1[2][2];
;     const char* cA = cur.A; const char* cB = cur.B;
;     constexpr unsigned kstep = (unsigned)(BK * 2);
;     const unsigned lda = cur.lda, ldb = cur.ldb, hA = HALF * lda, hB = HALF * ldb;
;     unsigned vA[2], vB[2];
; #pragma unroll
;     for (int i = 0; i < 2; ++i) { vA[i] = (unsigned)sR[i] * lda + (unsigned)sC[i] * 2u; vB[i] = (unsigned)sRbi[i] * ldb + (unsigned)sC[i] * 2u; }
;     PG8_STAGE(PG8_SB(0, 0), cB, vB); PG8_STAGE(PG8_SB(0, 1), cB + hB, vB); PG8_STAGE(PG8_SA(0, 0), cA, vA); PG8_STAGE(PG8_SA(0, 1), cA + hA, vA);
;     if (wr == 1) PG8_BAR;
.LBB0_670:
	s_and_b64 vcc, exec, s[8:9]
	s_cbranch_vccnz .LBB0_718
	v_bfe_i32 v3, v13, 27, 1
	v_lshlrev_b32_e32 v2, 4, v13
	v_lshrrev_b32_e32 v3, 22, v3
	v_add_u32_e32 v3, v2, v3
	v_and_b32_e32 v3, 0xfffffc00, v3
	v_sub_u32_e32 v3, v2, v3
	v_lshrrev_b32_e32 v4, 4, v3
	v_ashrrev_i32_e32 v0, 31, v13
	v_bitop3_b32 v3, v4, v3, 32 bitop3:0x6c
	v_lshrrev_b32_e32 v0, 26, v0
	v_ashrrev_i32_e32 v5, 31, v3
	v_add_u32_e32 v0, v13, v0
	v_lshrrev_b32_e32 v5, 26, v5
	v_ashrrev_i32_e32 v0, 6, v0
	v_add_u32_e32 v5, v3, v5
	v_lshlrev_b32_e32 v4, 3, v0
	v_ashrrev_i32_e32 v10, 6, v5
	v_and_b32_e32 v5, 0xc0, v5
	v_and_b32_e32 v4, -16, v4
	v_sub_u32_e32 v3, v3, v5
	v_add_u32_e32 v4, v10, v4
	v_ashrrev_i16_sdwa v3, v231, sext(v3) dst_sel:DWORD dst_unused:UNUSED_PAD src0_sel:DWORD src1_sel:BYTE_0
	v_bfe_i32 v11, v3, 0, 16
	v_lshlrev_b32_e32 v3, 1, v4
	v_lshrrev_b32_e32 v5, 2, v4
	v_and_b32_e32 v7, 3, v10
	v_and_b32_e32 v3, 24, v3
	v_and_b32_e32 v5, 4, v5
	v_and_or_b32 v7, v4, s55, v7
	v_add_u32_e32 v2, 0x2000, v2
	v_or3_b32 v3, v7, v5, v3
	v_ashrrev_i32_e32 v5, 31, v2
	v_lshrrev_b32_e32 v5, 22, v5
	v_add_u32_e32 v5, v2, v5
	v_ashrrev_i32_e32 v12, 10, v5
	v_mul_i32_i24_e32 v5, 0x400, v12
	v_sub_u32_e32 v2, v2, v5
	v_lshrrev_b32_e32 v5, 4, v2
	v_bitop3_b32 v2, v5, v2, 32 bitop3:0x6c
	v_ashrrev_i32_e32 v7, 31, v2
	v_lshrrev_b32_e32 v7, 26, v7
	v_add_u32_e32 v7, v2, v7
	v_lshlrev_b32_e32 v5, 3, v12
	v_ashrrev_i32_e32 v14, 6, v7
	v_and_b32_e32 v7, 0xc0, v7
	v_lshlrev_b32_e32 v6, 5, v0
	v_and_b32_e32 v5, -16, v5
	v_sub_u32_e32 v2, v2, v7
	s_ashr_i32 s9, s14, 6
	v_and_b32_e32 v6, 32, v6
	v_add_u32_e32 v5, v14, v5
	v_ashrrev_i16_sdwa v2, v231, sext(v2) dst_sel:DWORD dst_unused:UNUSED_PAD src0_sel:DWORD src1_sel:BYTE_0
	s_lshl_b32 s52, s9, 10
	v_lshlrev_b32_e32 v8, 5, v12
	v_bfe_i32 v15, v2, 0, 16
	v_lshlrev_b32_e32 v2, 1, v5
	v_lshrrev_b32_e32 v7, 2, v5
	v_and_b32_e32 v9, 3, v14
	v_add_lshl_u32 v6, v6, v11, 1
	s_add_i32 s53, s52, 0
	v_and_b32_e32 v8, 32, v8
	v_and_b32_e32 v2, 24, v2
	v_and_b32_e32 v7, 4, v7
	v_and_or_b32 v9, v5, s55, v9
	v_lshl_add_u32 v198, v3, 12, v6
	s_add_i32 m0, s53, 0x10000
	s_ashr_i32 s8, s14, 8
	v_or3_b32 v2, v9, v7, v2
	v_add_lshl_u32 v3, v8, v15, 1
	global_load_lds_dwordx4 v198, s[48:49]
	s_add_i32 m0, s53, 0x12000
	v_lshl_add_u32 v202, v2, 12, v3
	s_add_u32 s10, s48, 0x80000
	global_load_lds_dwordx4 v202, s[48:49]
	s_addc_u32 s11, s49, 0
	s_add_i32 m0, s53, 0x14000
	s_add_i32 s60, s53, 0x2000
	global_load_lds_dwordx4 v198, s[10:11]
	s_add_i32 m0, s53, 0x16000
	v_lshl_add_u32 v196, v4, 12, v6
	global_load_lds_dwordx4 v202, s[10:11]
	s_mov_b32 m0, s53
	s_add_u32 s10, s4, 0x80000
	v_lshl_add_u32 v200, v5, 12, v3
	global_load_lds_dwordx4 v196, s[4:5]
	s_mov_b32 m0, s60
	s_addc_u32 s11, s5, 0
	s_add_i32 s61, s53, 0x4000
	global_load_lds_dwordx4 v200, s[4:5]
	s_mov_b32 m0, s61
	s_add_i32 s76, s53, 0x6000
	global_load_lds_dwordx4 v196, s[10:11]
	s_mov_b32 m0, s76
	v_mov_b32_e32 v199, v1
	global_load_lds_dwordx4 v200, s[10:11]
	v_mov_b32_e32 v203, v1
	v_mov_b32_e32 v197, v1
	v_mov_b32_e32 v201, v1
	s_cmp_eq_u32 s8, 1
	v_lshl_add_u64 v[8:9], s[48:49], 0, v[198:199]
	v_lshl_add_u64 v[6:7], s[48:49], 0, v[202:203]
	v_lshl_add_u64 v[2:3], s[4:5], 0, v[196:197]
	s_cselect_b64 s[10:11], -1, 0
	s_cmp_lg_u32 s8, 1
	v_lshl_add_u64 v[4:5], s[4:5], 0, v[200:201]
	s_cbranch_scc1 .LBB0_673
	s_setprio 1
	s_barrier

; #define PG8_STAGE(bufoff, gbase, rows) do { _Pragma("unroll") for (int _i = 0; _i < 2; ++_i) \
;         __builtin_amdgcn_global_load_lds((const unsigned*)((const char*)(gbase) + (rows)[_i]), (LAS unsigned*)(lds + (bufoff) + ldsw + _i * 8192), 16, 0, 0); } while (0)
; #define PG8_LDA(dst, b, h) do { _Pragma("unroll") for (int m = 0; m < 4; ++m) _Pragma("unroll") for (int k = 0; k < 2; ++k) dst[m][k] = *(const LAS bf16x8*)(lds + PG8_SA(b, h) + aoff + m * 2048 + k * 1024); } while (0)
; #define PG8_LDB(dst, b, h) do { _Pragma("unroll") for (int n = 0; n < 2; ++n) _Pragma("unroll") for (int k = 0; k < 2; ++k) dst[n][k] = *(const LAS bf16x8*)(lds + PG8_SB(b, h) + boff + n * 2048 + k * 1024); } while (0)
; #define PG8_MMA(ai, bj, At, Bt) do { __builtin_amdgcn_s_setprio(1); _Pragma("unroll") for (int m = 0; m < 4; ++m) _Pragma("unroll") for (int n = 0; n < 2; ++n) _Pragma("unroll") for (int k = 0; k < 2; ++k) \
;         acc[ai][bj][m][n] = __builtin_amdgcn_mfma_f32_16x16x32_bf16(Bt[n][k], At[m][k], acc[ai][bj][m][n], 0, 0, 0); __builtin_amdgcn_s_setprio(0); } while (0)
; #define PG8_WAIT_V(n) asm volatile("s_waitcnt vmcnt(" #n ")" ::: "memory")
; #define PG8_WAIT_L(n) asm volatile("s_waitcnt lgkmcnt(" #n ")" ::: "memory")
; #define PG8_BAR __builtin_amdgcn_s_barrier()
; #define PG8_SCHED __builtin_amdgcn_sched_barrier(0)
; template <class Epi, class Sched>
; __device__ __forceinline__ void gemm_phase(LAS unsigned char* lds, const Sched& S, const Epi& E, const int tid) {
;     ...
;         for (int t = 0; t < nt; t += 2) {
;             const bool last = (t == nt - 2);
;             const char* a1 = cA + (size_t)(t + 1) * kstep;
;             const char* a2 = last ? nA : cA + (size_t)(t + 2) * kstep; const char* b2 = last ? nB : cB + (size_t)(t + 2) * kstep;
;             const char* a3 = a2 + kstep; const char* b3 = b2 + kstep;
;             PG8_LDB(B0, 0, 0); PG8_LDB(B1, 0, 1); PG8_SCHED; PG8_LDA(At, 0, 0); PG8_STAGE(PG8_SA(1, 1), a1 + hA, vA);
;             PG8_WAIT_V(8); PG8_WAIT_L(0); PG8_BAR; PG8_MMA(0, 0, At, B0); PG8_MMA(0, 1, At, B1); PG8_BAR; PG8_SCHED;
;             PG8_LDA(At, 0, 1); PG8_STAGE(PG8_SB(0, 0), b2, vB); PG8_STAGE(PG8_SB(0, 1), b2 + hB, vB); PG8_STAGE(PG8_SA(0, 0), a2, vA);
;             PG8_WAIT_V(8); PG8_WAIT_L(0); PG8_BAR; PG8_MMA(1, 0, At, B0); PG8_MMA(1, 1, At, B1); PG8_BAR; PG8_SCHED;
.LBB0_679:
	s_add_u32 s8, s4, 0xfff80080
	s_addc_u32 s9, s5, -1
	s_add_i32 s48, 0, 0x10000
	s_cmp_eq_u32 s25, 12
	s_cselect_b32 s39, s17, s9
	s_cselect_b32 s38, s16, s8
	v_add_u32_e32 v0, s48, v242
	s_cselect_b32 s9, s21, s23
	s_cselect_b32 s8, s20, s15
	s_add_i32 s50, 0, 0x14000
	ds_read_b128 v[130:133], v0
	ds_read_b128 v[134:137], v0 offset:1024
	ds_read_b128 v[138:141], v0 offset:2048
	ds_read_b128 v[142:145], v0 offset:3072
	v_add_u32_e32 v0, s50, v242
	ds_read_b128 v[146:149], v0
	ds_read_b128 v[150:153], v0 offset:1024
	ds_read_b128 v[154:157], v0 offset:2048
	ds_read_b128 v[158:161], v0 offset:3072
	v_lshl_add_u64 v[194:195], s[4:5], 0, v[204:205]
	s_add_i32 m0, s53, 0xc000
	ds_read_b128 v[162:165], v243
	ds_read_b128 v[166:169], v243 offset:1024
	ds_read_b128 v[170:173], v243 offset:2048
	ds_read_b128 v[174:177], v243 offset:3072
	ds_read_b128 v[178:181], v243 offset:4096
	ds_read_b128 v[182:185], v243 offset:5120
	ds_read_b128 v[186:189], v243 offset:6144
	ds_read_b128 v[190:193], v243 offset:7168
	global_load_lds_dwordx4 v[194:195], off
	v_lshl_add_u64 v[194:195], s[4:5], 0, v[206:207]
	s_add_i32 m0, s53, 0xe000
	s_nop 0
	global_load_lds_dwordx4 v[194:195], off
	s_waitcnt vmcnt(8)
	s_waitcnt lgkmcnt(0)
	s_barrier
	s_waitcnt lgkmcnt(0)
	v_mfma_f32_16x16x32_bf16 v[126:129], v[130:133], v[162:165], v[126:129]
	v_mfma_f32_16x16x32_bf16 v[122:125], v[138:141], v[162:165], v[122:125]
	v_mfma_f32_16x16x32_bf16 v[110:113], v[130:133], v[170:173], v[110:113]
	v_mfma_f32_16x16x32_bf16 v[106:109], v[138:141], v[170:173], v[106:109]
	v_mfma_f32_16x16x32_bf16 v[94:97], v[130:133], v[178:181], v[94:97]
	v_mfma_f32_16x16x32_bf16 v[90:93], v[138:141], v[178:181], v[90:93]
	v_mfma_f32_16x16x32_bf16 v[78:81], v[130:133], v[186:189], v[78:81]
	v_mfma_f32_16x16x32_bf16 v[74:77], v[138:141], v[186:189], v[74:77]
	v_mfma_f32_16x16x32_bf16 v[126:129], v[134:137], v[166:169], v[126:129]
	v_mfma_f32_16x16x32_bf16 v[122:125], v[142:145], v[166:169], v[122:125]
	v_mfma_f32_16x16x32_bf16 v[110:113], v[134:137], v[174:177], v[110:113]
	v_mfma_f32_16x16x32_bf16 v[106:109], v[142:145], v[174:177], v[106:109]
	v_mfma_f32_16x16x32_bf16 v[94:97], v[134:137], v[182:185], v[94:97]
	v_mfma_f32_16x16x32_bf16 v[90:93], v[142:145], v[182:185], v[90:93]
	v_mfma_f32_16x16x32_bf16 v[78:81], v[134:137], v[190:193], v[78:81]
	v_mfma_f32_16x16x32_bf16 v[74:77], v[142:145], v[190:193], v[74:77]
	v_mfma_f32_16x16x32_bf16 v[118:121], v[146:149], v[162:165], v[118:121]
	v_mfma_f32_16x16x32_bf16 v[114:117], v[154:157], v[162:165], v[114:117]
	v_mfma_f32_16x16x32_bf16 v[102:105], v[146:149], v[170:173], v[102:105]
	v_mfma_f32_16x16x32_bf16 v[98:101], v[154:157], v[170:173], v[98:101]
	v_mfma_f32_16x16x32_bf16 v[86:89], v[146:149], v[178:181], v[86:89]
	v_mfma_f32_16x16x32_bf16 v[82:85], v[154:157], v[178:181], v[82:85]
	v_mfma_f32_16x16x32_bf16 v[70:73], v[146:149], v[186:189], v[70:73]
	v_mfma_f32_16x16x32_bf16 v[66:69], v[154:157], v[186:189], v[66:69]
	v_mfma_f32_16x16x32_bf16 v[118:121], v[150:153], v[166:169], v[118:121]
	v_mfma_f32_16x16x32_bf16 v[114:117], v[158:161], v[166:169], v[114:117]
	v_mfma_f32_16x16x32_bf16 v[102:105], v[150:153], v[174:177], v[102:105]
	v_mfma_f32_16x16x32_bf16 v[98:101], v[158:161], v[174:177], v[98:101]
	v_mfma_f32_16x16x32_bf16 v[86:89], v[150:153], v[182:185], v[86:89]
	v_mfma_f32_16x16x32_bf16 v[82:85], v[158:161], v[182:185], v[82:85]
	v_mfma_f32_16x16x32_bf16 v[70:73], v[150:153], v[190:193], v[70:73]
	v_mfma_f32_16x16x32_bf16 v[66:69], v[158:161], v[190:193], v[66:69]
	s_barrier
	s_add_i32 s48, s48, s52
	v_lshl_add_u64 v[194:195], s[8:9], 0, v[198:199]
	s_mov_b32 m0, s48
	ds_read_b128 v[162:165], v243 offset:16384
	ds_read_b128 v[166:169], v243 offset:17408
	ds_read_b128 v[170:173], v243 offset:18432
	ds_read_b128 v[174:177], v243 offset:19456
	ds_read_b128 v[178:181], v243 offset:20480
	ds_read_b128 v[182:185], v243 offset:21504
	ds_read_b128 v[186:189], v243 offset:22528
	ds_read_b128 v[190:193], v243 offset:23552
	global_load_lds_dwordx4 v[194:195], off
	s_add_i32 m0, s48, 0x2000
	s_add_u32 s48, s8, 0x80000
	v_lshl_add_u64 v[208:209], s[8:9], 0, v[202:203]
	s_addc_u32 s49, s9, 0
	s_add_i32 s50, s50, s52
	global_load_lds_dwordx4 v[208:209], off
	v_lshl_add_u64 v[210:211], s[48:49], 0, v[198:199]
	s_mov_b32 m0, s50
	v_lshl_add_u64 v[212:213], s[38:39], 0, v[200:201]
	global_load_lds_dwordx4 v[210:211], off
	v_lshl_add_u64 v[210:211], s[48:49], 0, v[202:203]
	s_add_i32 m0, s50, 0x2000
	s_nop 0
	global_load_lds_dwordx4 v[210:211], off
	v_lshl_add_u64 v[210:211], s[38:39], 0, v[196:197]
	s_mov_b32 m0, s53
	s_nop 0
	global_load_lds_dwordx4 v[210:211], off
	s_mov_b32 m0, s60
	s_nop 0
	global_load_lds_dwordx4 v[212:213], off
	s_waitcnt vmcnt(8)
	s_waitcnt lgkmcnt(0)
	s_barrier
; #define PG8_STAGE(bufoff, gbase, rows) do { _Pragma("unroll") for (int _i = 0; _i < 2; ++_i) \
;         __builtin_amdgcn_global_load_lds((const unsigned*)((const char*)(gbase) + (rows)[_i]), (LAS unsigned*)(lds + (bufoff) + ldsw + _i * 8192), 16, 0, 0); } while (0)
; #define PG8_LDA(dst, b, h) do { _Pragma("unroll") for (int m = 0; m < 4; ++m) _Pragma("unroll") for (int k = 0; k < 2; ++k) dst[m][k] = *(const LAS bf16x8*)(lds + PG8_SA(b, h) + aoff + m * 2048 + k * 1024); } while (0)
; #define PG8_LDB(dst, b, h) do { _Pragma("unroll") for (int n = 0; n < 2; ++n) _Pragma("unroll") for (int k = 0; k < 2; ++k) dst[n][k] = *(const LAS bf16x8*)(lds + PG8_SB(b, h) + boff + n * 2048 + k * 1024); } while (0)
; #define PG8_MMA(ai, bj, At, Bt) do { __builtin_amdgcn_s_setprio(1); _Pragma("unroll") for (int m = 0; m < 4; ++m) _Pragma("unroll") for (int n = 0; n < 2; ++n) _Pragma("unroll") for (int k = 0; k < 2; ++k) \
;         acc[ai][bj][m][n] = __builtin_amdgcn_mfma_f32_16x16x32_bf16(Bt[n][k], At[m][k], acc[ai][bj][m][n], 0, 0, 0); __builtin_amdgcn_s_setprio(0); } while (0)
; #define PG8_WAIT_V(n) asm volatile("s_waitcnt vmcnt(" #n ")" ::: "memory")
; #define PG8_WAIT_L(n) asm volatile("s_waitcnt lgkmcnt(" #n ")" ::: "memory")
; #define PG8_BAR __builtin_amdgcn_s_barrier()
; #define PG8_SCHED __builtin_amdgcn_sched_barrier(0)
; template <class Epi, class Sched>
; __device__ __forceinline__ void gemm_phase(LAS unsigned char* lds, const Sched& S, const Epi& E, const int tid) {
;     ...
;             PG8_WAIT_V(8); PG8_WAIT_L(0); PG8_BAR; PG8_MMA(1, 0, At, B0); PG8_MMA(1, 1, At, B1); PG8_BAR; PG8_SCHED;
;             PG8_LDB(B0, 1, 0); PG8_LDB(B1, 1, 1); PG8_SCHED; PG8_LDA(At, 1, 0); PG8_STAGE(PG8_SA(0, 1), a2 + hA, vA);
;             PG8_WAIT_V(8); PG8_WAIT_L(0); PG8_BAR; PG8_MMA(0, 0, At, B0); PG8_MMA(0, 1, At, B1); PG8_BAR; PG8_SCHED;
	s_waitcnt lgkmcnt(0)
	v_mfma_f32_16x16x32_bf16 v[62:65], v[130:133], v[162:165], v[62:65]
	v_mfma_f32_16x16x32_bf16 v[58:61], v[138:141], v[162:165], v[58:61]
	v_mfma_f32_16x16x32_bf16 v[46:49], v[130:133], v[170:173], v[46:49]
	v_mfma_f32_16x16x32_bf16 v[42:45], v[138:141], v[170:173], v[42:45]
	v_mfma_f32_16x16x32_bf16 v[26:29], v[130:133], v[178:181], v[26:29]
	v_mfma_f32_16x16x32_bf16 v[18:21], v[138:141], v[178:181], v[18:21]
	v_mfma_f32_16x16x32_bf16 v[6:9], v[130:133], v[186:189], v[6:9]
	v_mfma_f32_16x16x32_bf16 v[2:5], v[138:141], v[186:189], v[2:5]
	v_mfma_f32_16x16x32_bf16 v[62:65], v[134:137], v[166:169], v[62:65]
	v_mfma_f32_16x16x32_bf16 v[58:61], v[142:145], v[166:169], v[58:61]
	v_mfma_f32_16x16x32_bf16 v[46:49], v[134:137], v[174:177], v[46:49]
	v_mfma_f32_16x16x32_bf16 v[42:45], v[142:145], v[174:177], v[42:45]
	v_mfma_f32_16x16x32_bf16 v[26:29], v[134:137], v[182:185], v[26:29]
	v_mfma_f32_16x16x32_bf16 v[18:21], v[142:145], v[182:185], v[18:21]
	v_mfma_f32_16x16x32_bf16 v[6:9], v[134:137], v[190:193], v[6:9]
	v_mfma_f32_16x16x32_bf16 v[2:5], v[142:145], v[190:193], v[2:5]
	v_mfma_f32_16x16x32_bf16 v[54:57], v[146:149], v[162:165], v[54:57]
	v_mfma_f32_16x16x32_bf16 v[50:53], v[154:157], v[162:165], v[50:53]
	v_mfma_f32_16x16x32_bf16 v[34:37], v[146:149], v[170:173], v[34:37]
	v_mfma_f32_16x16x32_bf16 v[22:25], v[154:157], v[170:173], v[22:25]
	v_mfma_f32_16x16x32_bf16 v[38:41], v[146:149], v[178:181], v[38:41]
	v_mfma_f32_16x16x32_bf16 v[30:33], v[154:157], v[178:181], v[30:33]
	v_mfma_f32_16x16x32_bf16 v[14:17], v[146:149], v[186:189], v[14:17]
	v_mfma_f32_16x16x32_bf16 v[10:13], v[154:157], v[186:189], v[10:13]
	v_mfma_f32_16x16x32_bf16 v[54:57], v[150:153], v[166:169], v[54:57]
	v_mfma_f32_16x16x32_bf16 v[50:53], v[158:161], v[166:169], v[50:53]
	v_mfma_f32_16x16x32_bf16 v[34:37], v[150:153], v[174:177], v[34:37]
	v_mfma_f32_16x16x32_bf16 v[22:25], v[158:161], v[174:177], v[22:25]
	v_mfma_f32_16x16x32_bf16 v[38:41], v[150:153], v[182:185], v[38:41]
	v_mfma_f32_16x16x32_bf16 v[30:33], v[158:161], v[182:185], v[30:33]
	v_mfma_f32_16x16x32_bf16 v[14:17], v[150:153], v[190:193], v[14:17]
	v_mfma_f32_16x16x32_bf16 v[10:13], v[158:161], v[190:193], v[10:13]
	s_barrier
	s_add_i32 s48, 0, 0x18000
	v_add_u32_e32 v0, s48, v242
	s_add_i32 s49, 0, 0x1c000
	ds_read_b128 v[130:133], v0
	ds_read_b128 v[134:137], v0 offset:1024
	ds_read_b128 v[138:141], v0 offset:2048
	ds_read_b128 v[142:145], v0 offset:3072
	v_add_u32_e32 v0, s49, v242
	ds_read_b128 v[146:149], v0
	ds_read_b128 v[150:153], v0 offset:1024
	ds_read_b128 v[154:157], v0 offset:2048
	ds_read_b128 v[158:161], v0 offset:3072
	s_add_u32 s38, s38, 0x80000
	s_addc_u32 s39, s39, 0
	s_mov_b32 m0, s61
	v_lshl_add_u64 v[214:215], s[38:39], 0, v[196:197]
	ds_read_b128 v[162:165], v243 offset:32768
	ds_read_b128 v[166:169], v243 offset:33792
	ds_read_b128 v[170:173], v243 offset:34816
	ds_read_b128 v[174:177], v243 offset:35840
	ds_read_b128 v[178:181], v243 offset:36864
	ds_read_b128 v[182:185], v243 offset:37888
	ds_read_b128 v[186:189], v243 offset:38912
	ds_read_b128 v[190:193], v243 offset:39936
	global_load_lds_dwordx4 v[214:215], off
	v_lshl_add_u64 v[214:215], s[38:39], 0, v[200:201]
	s_mov_b32 m0, s76
	s_nop 0
	global_load_lds_dwordx4 v[214:215], off
	s_waitcnt vmcnt(8)
	s_waitcnt lgkmcnt(0)
	s_barrier
	s_waitcnt lgkmcnt(0)
	v_mfma_f32_16x16x32_bf16 v[126:129], v[130:133], v[162:165], v[126:129]
	v_mfma_f32_16x16x32_bf16 v[122:125], v[138:141], v[162:165], v[122:125]
	v_mfma_f32_16x16x32_bf16 v[110:113], v[130:133], v[170:173], v[110:113]
	v_mfma_f32_16x16x32_bf16 v[106:109], v[138:141], v[170:173], v[106:109]
	v_mfma_f32_16x16x32_bf16 v[94:97], v[130:133], v[178:181], v[94:97]
	v_mfma_f32_16x16x32_bf16 v[90:93], v[138:141], v[178:181], v[90:93]
	v_mfma_f32_16x16x32_bf16 v[78:81], v[130:133], v[186:189], v[78:81]
	v_mfma_f32_16x16x32_bf16 v[74:77], v[138:141], v[186:189], v[74:77]
	v_mfma_f32_16x16x32_bf16 v[126:129], v[134:137], v[166:169], v[126:129]
	v_mfma_f32_16x16x32_bf16 v[122:125], v[142:145], v[166:169], v[122:125]
	v_mfma_f32_16x16x32_bf16 v[110:113], v[134:137], v[174:177], v[110:113]
	v_mfma_f32_16x16x32_bf16 v[106:109], v[142:145], v[174:177], v[106:109]
	v_mfma_f32_16x16x32_bf16 v[94:97], v[134:137], v[182:185], v[94:97]
	v_mfma_f32_16x16x32_bf16 v[90:93], v[142:145], v[182:185], v[90:93]
	v_mfma_f32_16x16x32_bf16 v[78:81], v[134:137], v[190:193], v[78:81]
	v_mfma_f32_16x16x32_bf16 v[74:77], v[142:145], v[190:193], v[74:77]
	v_mfma_f32_16x16x32_bf16 v[118:121], v[146:149], v[162:165], v[118:121]
	v_mfma_f32_16x16x32_bf16 v[114:117], v[154:157], v[162:165], v[114:117]
	v_mfma_f32_16x16x32_bf16 v[102:105], v[146:149], v[170:173], v[102:105]
	v_mfma_f32_16x16x32_bf16 v[98:101], v[154:157], v[170:173], v[98:101]
	v_mfma_f32_16x16x32_bf16 v[86:89], v[146:149], v[178:181], v[86:89]
	v_mfma_f32_16x16x32_bf16 v[82:85], v[154:157], v[178:181], v[82:85]
	v_mfma_f32_16x16x32_bf16 v[70:73], v[146:149], v[186:189], v[70:73]
	v_mfma_f32_16x16x32_bf16 v[66:69], v[154:157], v[186:189], v[66:69]
	v_mfma_f32_16x16x32_bf16 v[118:121], v[150:153], v[166:169], v[118:121]
	v_mfma_f32_16x16x32_bf16 v[114:117], v[158:161], v[166:169], v[114:117]
	v_mfma_f32_16x16x32_bf16 v[102:105], v[150:153], v[174:177], v[102:105]
	v_mfma_f32_16x16x32_bf16 v[98:101], v[158:161], v[174:177], v[98:101]
	v_mfma_f32_16x16x32_bf16 v[86:89], v[150:153], v[182:185], v[86:89]
	v_mfma_f32_16x16x32_bf16 v[82:85], v[158:161], v[182:185], v[82:85]
	v_mfma_f32_16x16x32_bf16 v[70:73], v[150:153], v[190:193], v[70:73]
	v_mfma_f32_16x16x32_bf16 v[66:69], v[158:161], v[190:193], v[66:69]
	s_barrier
; #define PG8_STAGE(bufoff, gbase, rows) do { _Pragma("unroll") for (int _i = 0; _i < 2; ++_i) \
;         __builtin_amdgcn_global_load_lds((const unsigned*)((const char*)(gbase) + (rows)[_i]), (LAS unsigned*)(lds + (bufoff) + ldsw + _i * 8192), 16, 0, 0); } while (0)
; #define PG8_LDA(dst, b, h) do { _Pragma("unroll") for (int m = 0; m < 4; ++m) _Pragma("unroll") for (int k = 0; k < 2; ++k) dst[m][k] = *(const LAS bf16x8*)(lds + PG8_SA(b, h) + aoff + m * 2048 + k * 1024); } while (0)
; #define PG8_MMA(ai, bj, At, Bt) do { __builtin_amdgcn_s_setprio(1); _Pragma("unroll") for (int m = 0; m < 4; ++m) _Pragma("unroll") for (int n = 0; n < 2; ++n) _Pragma("unroll") for (int k = 0; k < 2; ++k) \
;         acc[ai][bj][m][n] = __builtin_amdgcn_mfma_f32_16x16x32_bf16(Bt[n][k], At[m][k], acc[ai][bj][m][n], 0, 0, 0); __builtin_amdgcn_s_setprio(0); } while (0)
; #define PG8_WAIT_V(n) asm volatile("s_waitcnt vmcnt(" #n ")" ::: "memory")
; #define PG8_WAIT_L(n) asm volatile("s_waitcnt lgkmcnt(" #n ")" ::: "memory")
; #define PG8_BAR __builtin_amdgcn_s_barrier()
; #define PG8_SCHED __builtin_amdgcn_sched_barrier(0)
; template <class Epi, class Sched>
; __device__ __forceinline__ void gemm_phase(LAS unsigned char* lds, const Sched& S, const Epi& E, const int tid) {
;     ...
;             PG8_LDA(At, 1, 1); PG8_STAGE(PG8_SB(1, 0), b3, vB); PG8_STAGE(PG8_SB(1, 1), b3 + hB, vB); PG8_STAGE(PG8_SA(1, 0), a3, vA);
;             PG8_WAIT_V(8); PG8_WAIT_L(0); PG8_BAR; PG8_MMA(1, 0, At, B0); PG8_MMA(1, 1, At, B1); PG8_BAR; PG8_SCHED;
;         }
;         if (wr == 0) PG8_BAR;
	s_add_i32 s38, s48, s52
	v_lshl_add_u64 v[194:195], v[194:195], 0, s[82:83]
	s_mov_b32 m0, s38
	ds_read_b128 v[162:165], v243 offset:49152
	ds_read_b128 v[166:169], v243 offset:50176
	ds_read_b128 v[170:173], v243 offset:51200
	ds_read_b128 v[174:177], v243 offset:52224
	ds_read_b128 v[178:181], v243 offset:53248
	ds_read_b128 v[182:185], v243 offset:54272
	ds_read_b128 v[186:189], v243 offset:55296
	ds_read_b128 v[190:193], v243 offset:56320
	global_load_lds_dwordx4 v[194:195], off
	s_add_i32 m0, s38, 0x2000
	s_add_u32 s8, s8, 0x80080
	v_lshl_add_u64 v[194:195], v[208:209], 0, s[82:83]
	s_addc_u32 s9, s9, 0
	s_add_i32 s38, s49, s52
	global_load_lds_dwordx4 v[194:195], off
	v_lshl_add_u64 v[194:195], s[8:9], 0, v[198:199]
	s_mov_b32 m0, s38
	s_nop 0
	global_load_lds_dwordx4 v[194:195], off
	v_lshl_add_u64 v[194:195], s[8:9], 0, v[202:203]
	s_add_i32 m0, s38, 0x2000
	s_nop 0
	global_load_lds_dwordx4 v[194:195], off
	v_lshl_add_u64 v[194:195], v[210:211], 0, s[82:83]
	s_mov_b32 m0, s85
	s_nop 0
	global_load_lds_dwordx4 v[194:195], off
	v_lshl_add_u64 v[194:195], v[212:213], 0, s[82:83]
	s_mov_b32 m0, s86
	s_nop 0
	global_load_lds_dwordx4 v[194:195], off
	s_waitcnt vmcnt(8)
	s_waitcnt lgkmcnt(0)
	s_barrier
	s_waitcnt lgkmcnt(0)
	v_mfma_f32_16x16x32_bf16 v[62:65], v[130:133], v[162:165], v[62:65]
	v_mfma_f32_16x16x32_bf16 v[58:61], v[138:141], v[162:165], v[58:61]
	v_mfma_f32_16x16x32_bf16 v[46:49], v[130:133], v[170:173], v[46:49]
	v_mfma_f32_16x16x32_bf16 v[42:45], v[138:141], v[170:173], v[42:45]
	v_mfma_f32_16x16x32_bf16 v[26:29], v[130:133], v[178:181], v[26:29]
	v_mfma_f32_16x16x32_bf16 v[18:21], v[138:141], v[178:181], v[18:21]
	v_mfma_f32_16x16x32_bf16 v[6:9], v[130:133], v[186:189], v[6:9]
	v_mfma_f32_16x16x32_bf16 v[2:5], v[138:141], v[186:189], v[2:5]
	v_mfma_f32_16x16x32_bf16 v[62:65], v[134:137], v[166:169], v[62:65]
	v_mfma_f32_16x16x32_bf16 v[58:61], v[142:145], v[166:169], v[58:61]
	v_mfma_f32_16x16x32_bf16 v[46:49], v[134:137], v[174:177], v[46:49]
	v_mfma_f32_16x16x32_bf16 v[42:45], v[142:145], v[174:177], v[42:45]
	v_mfma_f32_16x16x32_bf16 v[26:29], v[134:137], v[182:185], v[26:29]
	v_mfma_f32_16x16x32_bf16 v[18:21], v[142:145], v[182:185], v[18:21]
	v_mfma_f32_16x16x32_bf16 v[6:9], v[134:137], v[190:193], v[6:9]
	v_mfma_f32_16x16x32_bf16 v[2:5], v[142:145], v[190:193], v[2:5]
	v_mfma_f32_16x16x32_bf16 v[54:57], v[146:149], v[162:165], v[54:57]
	v_mfma_f32_16x16x32_bf16 v[50:53], v[154:157], v[162:165], v[50:53]
	v_mfma_f32_16x16x32_bf16 v[34:37], v[146:149], v[170:173], v[34:37]
	v_mfma_f32_16x16x32_bf16 v[22:25], v[154:157], v[170:173], v[22:25]
	v_mfma_f32_16x16x32_bf16 v[38:41], v[146:149], v[178:181], v[38:41]
	v_mfma_f32_16x16x32_bf16 v[30:33], v[154:157], v[178:181], v[30:33]
	v_mfma_f32_16x16x32_bf16 v[14:17], v[146:149], v[186:189], v[14:17]
	v_mfma_f32_16x16x32_bf16 v[10:13], v[154:157], v[186:189], v[10:13]
	v_mfma_f32_16x16x32_bf16 v[54:57], v[150:153], v[166:169], v[54:57]
	v_mfma_f32_16x16x32_bf16 v[50:53], v[158:161], v[166:169], v[50:53]
	v_mfma_f32_16x16x32_bf16 v[34:37], v[150:153], v[174:177], v[34:37]
	v_mfma_f32_16x16x32_bf16 v[22:25], v[158:161], v[174:177], v[22:25]
	v_mfma_f32_16x16x32_bf16 v[38:41], v[150:153], v[182:185], v[38:41]
	v_mfma_f32_16x16x32_bf16 v[30:33], v[158:161], v[182:185], v[30:33]
	v_mfma_f32_16x16x32_bf16 v[14:17], v[150:153], v[190:193], v[14:17]
	v_mfma_f32_16x16x32_bf16 v[10:13], v[158:161], v[190:193], v[10:13]
	s_barrier
	s_add_i32 s25, s25, 2
	s_add_u32 s4, s4, 0x100
	s_addc_u32 s5, s5, 0
	s_add_u32 s15, s15, 0x100
	s_addc_u32 s23, s23, 0
	s_cmp_gt_u32 s25, 13
	s_cbranch_scc0 .LBB0_679
	s_and_b64 vcc, exec, s[12:13]
	s_cbranch_vccz .LBB0_682
	s_barrier

; __device__ __forceinline__ void xcd_barrier(const XcdBarrier& b) {
;     asm volatile("s_waitcnt vmcnt(0)" ::: "memory");
;     __syncthreads();
;     if (threadIdx.x == 0) {
;         unsigned* bar = b.bar;
;         __builtin_amdgcn_s_waitcnt(0);
;         unsigned nloc = b.st[0], nx = b.st[1];
;         if (nloc == 0u) { xcd_barrier_complete(bar, b.x, nloc, nx); b.st[0] = nloc; b.st[1] = nx; }
.LBB0_718:
	s_mov_b64 s[4:5], s[66:67]
	s_waitcnt vmcnt(0) lgkmcnt(0)
	s_setprio 0
	s_getreg_b32 s8, hwreg(HW_REG_XCC_ID, 0, 4)
	s_waitcnt vmcnt(0)
	s_waitcnt lgkmcnt(0)
	s_barrier
	s_and_saveexec_b64 s[0:1], s[26:27]
	s_cbranch_execz .LBB0_595
	v_mov_b32_e32 v0, s96
	s_load_dwordx2 s[4:5], s[4:5], 0xc0
	s_waitcnt vmcnt(0) expcnt(0) lgkmcnt(0)
	ds_read_b32 v3, v0
	v_mov_b32_e32 v0, s97
	ds_read_b32 v2, v0
	s_and_b32 s35, s8, 15
	s_waitcnt lgkmcnt(1)
	v_cmp_ne_u32_e32 vcc, 0, v3
	s_cbranch_vccnz .LBB0_734
	s_add_u32 s8, s4, 0x1200
	s_addc_u32 s9, s5, 0
	s_add_u32 s10, s4, 0x1400
	s_addc_u32 s11, s5, 0
	s_add_u32 s12, s4, 0x1500
	s_addc_u32 s13, s5, 0
	s_add_u32 s14, s4, 0x1600
	s_addc_u32 s15, s5, 0
	s_add_u32 s16, s4, 0x1700
	s_addc_u32 s17, s5, 0
	s_add_u32 s18, s4, 0x1800
	s_addc_u32 s19, s5, 0
	s_add_u32 s20, s4, 0x1900
	s_addc_u32 s21, s5, 0
	s_add_u32 s22, s4, 0x1a00
	s_addc_u32 s23, s5, 0
	s_add_u32 s24, s4, 0x1b00
	s_addc_u32 s25, s5, 0
	s_add_u32 s38, s4, 0x1c00
	s_addc_u32 s39, s5, 0
	s_add_u32 s48, s4, 0x1d00
	s_addc_u32 s49, s5, 0
	s_add_u32 s52, s4, 0x1e00
	s_addc_u32 s53, s5, 0
	s_add_u32 s76, s4, 0x1f00
	s_addc_u32 s77, s5, 0
	s_add_u32 s78, s4, 0x2000
	s_addc_u32 s79, s5, 0
	s_add_u32 s80, s4, 0x2100
	s_addc_u32 s81, s5, 0
	s_add_u32 s84, s4, 0x2200
	s_addc_u32 s85, s5, 0
	s_add_u32 s86, s4, 0x2300
	s_addc_u32 s87, s5, 0
	s_mov_b32 s37, 1
	s_branch .LBB0_722

; __device__ __forceinline__ ParamsCP get_params() { ParamsCP q = (ParamsCP)__builtin_amdgcn_kernarg_segment_ptr(); asm volatile("" : "+s"(q)); return q; }
; #define PG8_BAR __builtin_amdgcn_s_barrier()
; template <class Epi, class Sched>
; __device__ __forceinline__ void gemm_phase(LAS unsigned char* lds, const Sched& S, const Epi& E, const int tid) {
;     const int wid = __builtin_amdgcn_readfirstlane(tid >> 6), lane = tid & 63, wr = wid >> 2, wc = wid & 3, fr = lane & 15, fq = lane >> 4;
;     int sR[2], sC[2], sRbi[2];
; #pragma unroll
;     for (int i = 0; i < 2; ++i) { stage_rc(tid * 16 + i * 8192, sR[i], sC[i]); sRbi[i] = (sR[i] & ~31) + perm32(sR[i] & 31); }
;     const unsigned ldsw = (unsigned)wid * 1024u;
;     const int aoff = lds_byte(wr * 64 + fr, fq * 8), boff = lds_byte(wc * 32 + fr, fq * 8);
;     ...
;     GUnit cur, nxt; int ui = 0;
;     if (!S.next(0, cur)) return;
;     f32x4 acc[2][2][4][2];
; #pragma unroll
;     for (int a = 0; a < 2; ++a)
; #pragma unroll
;         for (int b = 0; b < 2; ++b)
; #pragma unroll
;             for (int m = 0; m < 4; ++m)
; #pragma unroll
;                 for (int n = 0; n < 2; ++n) acc[a][b][m][n] = (f32x4){0.f, 0.f, 0.f, 0.f};
;     bf16x8 At[4][2], B0[2][2], B1[2][2];
;     const char* cA = cur.A; const char* cB = cur.B;
;     constexpr unsigned kstep = (unsigned)(BK * 2);
;     const unsigned lda = cur.lda, ldb = cur.ldb, hA = HALF * lda, hB = HALF * ldb;
;     unsigned vA[2], vB[2];
; #pragma unroll
;     for (int i = 0; i < 2; ++i) { vA[i] = (unsigned)sR[i] * lda + (unsigned)sC[i] * 2u; vB[i] = (unsigned)sRbi[i] * ldb + (unsigned)sC[i] * 2u; }
;     PG8_STAGE(PG8_SB(0, 0), cB, vB); PG8_STAGE(PG8_SB(0, 1), cB + hB, vB); PG8_STAGE(PG8_SA(0, 0), cA, vA); PG8_STAGE(PG8_SA(0, 1), cA + hA, vA);
;     if (wr == 1) PG8_BAR;
; __global__ void __launch_bounds__(512) fwd_kernel(Params p_unused) {
;     ...
;         { FRESH_IDS(); ParamsCP pp = get_params(); unsigned char* ws = pp->ws; float* hmeta = (float*)(ws + WS_HMETA);
;           SchedPlain S{(const char*)(ws + WS_BIG + BIG_MERGED), (const char*)(ws + WS_WT + WT_OUT), 4096u, 4096u, 32, 128, 8, 1, G, blk};
;           EpiResid E{layer == 0 ? pp->in[0] : (const float*)pp->out, hmeta, pp->out, hmeta}; pg8::gemm_phase(lds, S, E, tid); }
.LBB0_769:
	v_mov_b32_e32 v15, v222
	s_mov_b64 s[0:1], s[66:67]
	s_and_b64 vcc, exec, s[6:7]
	v_readfirstlane_b32 s14, v15
	s_cbranch_vccnz .LBB0_793
	v_lshlrev_b32_e32 v2, 4, v15
	v_add_u32_e32 v3, 0x2000, v2
	v_ashrrev_i32_e32 v0, 31, v3
	v_lshrrev_b32_e32 v0, 22, v0
	v_add_u32_e32 v0, v3, v0
	v_ashrrev_i32_e32 v0, 10, v0
	v_mul_i32_i24_e32 v4, 0x400, v0
	v_sub_u32_e32 v3, v3, v4
	v_lshrrev_b32_e32 v4, 4, v3
	v_bitop3_b32 v3, v4, v3, 32 bitop3:0x6c
	v_ashrrev_i32_e32 v4, 31, v3
	v_lshrrev_b32_e32 v4, 26, v4
	v_add_u32_e32 v4, v3, v4
	s_load_dwordx4 s[8:11], s[0:1], 0xb8
	v_ashrrev_i32_e32 v10, 6, v4
	v_and_b32_e32 v4, 0xc0, v4
	v_lshlrev_b32_e32 v5, 3, v0
	v_sub_u32_e32 v3, v3, v4
	v_bfe_i32 v4, v15, 27, 1
	v_and_b32_e32 v5, -16, v5
	v_lshrrev_b32_e32 v4, 22, v4
	v_add_u32_e32 v5, v10, v5
	v_add_u32_e32 v4, v2, v4
	v_and_b32_e32 v6, 3, v10
	v_lshrrev_b32_e32 v7, 2, v5
	v_lshlrev_b32_e32 v8, 1, v5
	v_and_b32_e32 v4, 0xfffffc00, v4
	s_waitcnt lgkmcnt(0)
	s_add_u32 s30, s10, 0x2a880000
	v_and_or_b32 v6, v5, s55, v6
	v_and_b32_e32 v7, 4, v7
	v_and_b32_e32 v8, 24, v8
	v_sub_u32_e32 v2, v2, v4
	s_addc_u32 s35, s11, 0
	v_or3_b32 v6, v6, v7, v8
	v_lshrrev_b32_e32 v4, 4, v2
	v_ashrrev_i32_e32 v7, 31, v15
	s_add_u32 s37, s10, 0x5c00000
	v_readlane_b32 s4, v254, 60
	v_bitop3_b32 v2, v4, v2, 32 bitop3:0x6c
	v_lshrrev_b32_e32 v7, 26, v7
	s_addc_u32 s40, s11, 0
	v_readlane_b32 s5, v254, 61
	v_ashrrev_i32_e32 v4, 31, v2
	v_add_u32_e32 v7, v15, v7
	s_and_b64 s[4:5], s[4:5], exec
	v_lshrrev_b32_e32 v4, 26, v4
	v_ashrrev_i32_e32 v13, 6, v7
	s_cselect_b32 s4, 0, 0xb8
	v_add_u32_e32 v4, v2, v4
	v_lshlrev_b32_e32 v7, 3, v13
	s_add_u32 s0, s0, s4
	v_ashrrev_i32_e32 v12, 6, v4
	v_and_b32_e32 v7, -16, v7
	s_addc_u32 s1, s1, 0
	s_ashr_i32 s15, s14, 6
	v_add_u32_e32 v7, v12, v7
	v_and_b32_e32 v4, 0xc0, v4
	s_ashr_i32 s16, s14, 8
	s_lshl_b32 s41, s15, 10
	v_and_b32_e32 v8, 3, v12
	v_lshrrev_b32_e32 v9, 2, v7
	v_lshlrev_b32_e32 v14, 1, v7
	v_sub_u32_e32 v2, v2, v4
	v_and_or_b32 v8, v7, s55, v8
	v_and_b32_e32 v9, 4, v9
	v_and_b32_e32 v14, 24, v14
	v_ashrrev_i16_sdwa v2, v231, sext(v2) dst_sel:DWORD dst_unused:UNUSED_PAD src0_sel:DWORD src1_sel:BYTE_0
	s_add_u32 s4, s30, s56
	v_or3_b32 v8, v8, v9, v14
	v_bfe_i32 v14, v2, 0, 16
	v_lshlrev_b32_e32 v2, 5, v13
	s_addc_u32 s5, s35, s57
	v_ashrrev_i16_sdwa v3, v231, sext(v3) dst_sel:DWORD dst_unused:UNUSED_PAD src0_sel:DWORD src1_sel:BYTE_0
	v_and_b32_e32 v2, 32, v2
	s_add_u32 s24, s37, s58
	v_bfe_i32 v11, v3, 0, 16
	v_lshlrev_b32_e32 v3, 5, v0
	s_addc_u32 s25, s40, s59
	v_add_lshl_u32 v2, v2, v14, 1
	s_add_i32 s48, s41, 0
	v_and_b32_e32 v3, 32, v3
	v_lshl_add_u32 v168, v8, 12, v2
	s_add_i32 m0, s48, 0x10000
	v_lshl_add_u32 v166, v7, 12, v2
	v_add_lshl_u32 v2, v3, v11, 1
	global_load_lds_dwordx4 v168, s[24:25]
	s_add_i32 m0, s48, 0x12000
	v_lshl_add_u32 v172, v6, 12, v2
	s_add_u32 s12, s24, 0x80000
	global_load_lds_dwordx4 v172, s[24:25]
	s_addc_u32 s13, s25, 0
	s_add_i32 m0, s48, 0x14000
	s_add_i32 s49, s48, 0x2000
	global_load_lds_dwordx4 v168, s[12:13]
	s_add_i32 m0, s48, 0x16000
	v_lshl_add_u32 v170, v5, 12, v2
	global_load_lds_dwordx4 v172, s[12:13]
	s_mov_b32 m0, s48
	s_add_u32 s12, s4, 0x80000
	global_load_lds_dwordx4 v166, s[4:5]
	s_mov_b32 m0, s49
	s_addc_u32 s13, s5, 0
	s_add_i32 s52, s48, 0x4000
	global_load_lds_dwordx4 v170, s[4:5]
	s_mov_b32 m0, s52
	s_add_i32 s53, s48, 0x6000
	global_load_lds_dwordx4 v166, s[12:13]
	s_mov_b32 m0, s53
	s_load_dwordx2 s[0:1], s[0:1], 0x0
	global_load_lds_dwordx4 v170, s[12:13]
	v_mov_b32_e32 v169, v1
	v_mov_b32_e32 v173, v1
	v_mov_b32_e32 v167, v1
	v_mov_b32_e32 v171, v1
	s_cmp_eq_u32 s16, 1
	v_lshl_add_u64 v[8:9], s[24:25], 0, v[168:169]
	v_lshl_add_u64 v[6:7], s[24:25], 0, v[172:173]
	v_lshl_add_u64 v[2:3], s[4:5], 0, v[166:167]
	s_cselect_b64 s[12:13], -1, 0
	s_cmp_lg_u32 s16, 1
	v_lshl_add_u64 v[4:5], s[4:5], 0, v[170:171]
	s_cbranch_scc1 .LBB0_772
	s_setprio 1
	s_barrier

; #define PG8_STAGE(bufoff, gbase, rows) do { _Pragma("unroll") for (int _i = 0; _i < 2; ++_i) \
;         __builtin_amdgcn_global_load_lds((const unsigned*)((const char*)(gbase) + (rows)[_i]), (LAS unsigned*)(lds + (bufoff) + ldsw + _i * 8192), 16, 0, 0); } while (0)
; #define PG8_LDA(dst, b, h) do { _Pragma("unroll") for (int m = 0; m < 4; ++m) _Pragma("unroll") for (int k = 0; k < 2; ++k) dst[m][k] = *(const LAS bf16x8*)(lds + PG8_SA(b, h) + aoff + m * 2048 + k * 1024); } while (0)
; #define PG8_LDB(dst, b, h) do { _Pragma("unroll") for (int n = 0; n < 2; ++n) _Pragma("unroll") for (int k = 0; k < 2; ++k) dst[n][k] = *(const LAS bf16x8*)(lds + PG8_SB(b, h) + boff + n * 2048 + k * 1024); } while (0)
; #define PG8_MMA(ai, bj, At, Bt) do { __builtin_amdgcn_s_setprio(1); _Pragma("unroll") for (int m = 0; m < 4; ++m) _Pragma("unroll") for (int n = 0; n < 2; ++n) _Pragma("unroll") for (int k = 0; k < 2; ++k) \
;         acc[ai][bj][m][n] = __builtin_amdgcn_mfma_f32_16x16x32_bf16(Bt[n][k], At[m][k], acc[ai][bj][m][n], 0, 0, 0); __builtin_amdgcn_s_setprio(0); } while (0)
; #define PG8_WAIT_V(n) asm volatile("s_waitcnt vmcnt(" #n ")" ::: "memory")
; #define PG8_WAIT_L(n) asm volatile("s_waitcnt lgkmcnt(" #n ")" ::: "memory")
; #define PG8_BAR __builtin_amdgcn_s_barrier()
; #define PG8_SCHED __builtin_amdgcn_sched_barrier(0)
; template <class Epi, class Sched>
; __device__ __forceinline__ void gemm_phase(LAS unsigned char* lds, const Sched& S, const Epi& E, const int tid) {
;     ...
;         for (int t = 0; t < nt; t += 2) {
;             const bool last = (t == nt - 2);
;             const char* a1 = cA + (size_t)(t + 1) * kstep;
;             const char* a2 = last ? nA : cA + (size_t)(t + 2) * kstep; const char* b2 = last ? nB : cB + (size_t)(t + 2) * kstep;
;             const char* a3 = a2 + kstep; const char* b3 = b2 + kstep;
;             PG8_LDB(B0, 0, 0); PG8_LDB(B1, 0, 1); PG8_SCHED; PG8_LDA(At, 0, 0); PG8_STAGE(PG8_SA(1, 1), a1 + hA, vA);
;             PG8_WAIT_V(8); PG8_WAIT_L(0); PG8_BAR; PG8_MMA(0, 0, At, B0); PG8_MMA(0, 1, At, B1); PG8_BAR; PG8_SCHED;
;             PG8_LDA(At, 0, 1); PG8_STAGE(PG8_SB(0, 0), b2, vB); PG8_STAGE(PG8_SB(0, 1), b2 + hB, vB); PG8_STAGE(PG8_SA(0, 0), a2, vA);
;             PG8_WAIT_V(8); PG8_WAIT_L(0); PG8_BAR; PG8_MMA(1, 0, At, B0); PG8_MMA(1, 1, At, B1); PG8_BAR; PG8_SCHED;
.LBB0_782:
	s_add_u32 s24, s4, 0xfff80080
	s_addc_u32 s25, s5, -1
	s_add_i32 s50, 0, 0x10000
	s_cmp_eq_u32 s80, 28
	s_cselect_b32 s39, s19, s25
	s_cselect_b32 s38, s18, s24
	v_add_u32_e32 v0, s50, v196
	s_cselect_b32 s25, s21, s23
	s_cselect_b32 s24, s20, s17
	s_add_i32 s51, 0, 0x14000
	ds_read_b128 v[130:133], v0
	ds_read_b128 v[134:137], v0 offset:1024
	ds_read_b128 v[138:141], v0 offset:2048
	ds_read_b128 v[142:145], v0 offset:3072
	v_add_u32_e32 v0, s51, v196
	ds_read_b128 v[146:149], v0
	ds_read_b128 v[150:153], v0 offset:1024
	ds_read_b128 v[154:157], v0 offset:2048
	ds_read_b128 v[158:161], v0 offset:3072
	v_lshl_add_u64 v[194:195], s[4:5], 0, v[174:175]
	s_add_i32 m0, s48, 0xc000
	ds_read_b128 v[162:165], v197
	ds_read_b128 v[178:181], v197 offset:1024
	ds_read_b128 v[182:185], v197 offset:2048
	ds_read_b128 v[186:189], v197 offset:3072
	ds_read_b128 v[190:193], v197 offset:4096
	ds_read_b128 v[198:201], v197 offset:5120
	ds_read_b128 v[202:205], v197 offset:6144
	ds_read_b128 v[206:209], v197 offset:7168
	global_load_lds_dwordx4 v[194:195], off
	v_lshl_add_u64 v[194:195], s[4:5], 0, v[176:177]
	s_add_i32 m0, s48, 0xe000
	s_nop 0
	global_load_lds_dwordx4 v[194:195], off
	s_waitcnt vmcnt(8)
	s_waitcnt lgkmcnt(0)
	s_barrier
	s_waitcnt lgkmcnt(0)
	v_mfma_f32_16x16x32_bf16 v[126:129], v[130:133], v[162:165], v[126:129]
	v_mfma_f32_16x16x32_bf16 v[122:125], v[138:141], v[162:165], v[122:125]
	v_mfma_f32_16x16x32_bf16 v[118:121], v[130:133], v[182:185], v[118:121]
	v_mfma_f32_16x16x32_bf16 v[106:109], v[138:141], v[182:185], v[106:109]
	v_mfma_f32_16x16x32_bf16 v[98:101], v[130:133], v[190:193], v[98:101]
	v_mfma_f32_16x16x32_bf16 v[90:93], v[138:141], v[190:193], v[90:93]
	v_mfma_f32_16x16x32_bf16 v[86:89], v[130:133], v[202:205], v[86:89]
	v_mfma_f32_16x16x32_bf16 v[78:81], v[138:141], v[202:205], v[78:81]
	v_mfma_f32_16x16x32_bf16 v[126:129], v[134:137], v[178:181], v[126:129]
	v_mfma_f32_16x16x32_bf16 v[122:125], v[142:145], v[178:181], v[122:125]
	v_mfma_f32_16x16x32_bf16 v[118:121], v[134:137], v[186:189], v[118:121]
	v_mfma_f32_16x16x32_bf16 v[106:109], v[142:145], v[186:189], v[106:109]
	v_mfma_f32_16x16x32_bf16 v[98:101], v[134:137], v[198:201], v[98:101]
	v_mfma_f32_16x16x32_bf16 v[90:93], v[142:145], v[198:201], v[90:93]
	v_mfma_f32_16x16x32_bf16 v[86:89], v[134:137], v[206:209], v[86:89]
	v_mfma_f32_16x16x32_bf16 v[78:81], v[142:145], v[206:209], v[78:81]
	v_mfma_f32_16x16x32_bf16 v[114:117], v[146:149], v[162:165], v[114:117]
	v_mfma_f32_16x16x32_bf16 v[110:113], v[154:157], v[162:165], v[110:113]
	v_mfma_f32_16x16x32_bf16 v[102:105], v[146:149], v[182:185], v[102:105]
	v_mfma_f32_16x16x32_bf16 v[94:97], v[154:157], v[182:185], v[94:97]
	v_mfma_f32_16x16x32_bf16 v[82:85], v[146:149], v[190:193], v[82:85]
	v_mfma_f32_16x16x32_bf16 v[74:77], v[154:157], v[190:193], v[74:77]
	v_mfma_f32_16x16x32_bf16 v[70:73], v[146:149], v[202:205], v[70:73]
	v_mfma_f32_16x16x32_bf16 v[66:69], v[154:157], v[202:205], v[66:69]
	v_mfma_f32_16x16x32_bf16 v[114:117], v[150:153], v[178:181], v[114:117]
	v_mfma_f32_16x16x32_bf16 v[110:113], v[158:161], v[178:181], v[110:113]
	v_mfma_f32_16x16x32_bf16 v[102:105], v[150:153], v[186:189], v[102:105]
	v_mfma_f32_16x16x32_bf16 v[94:97], v[158:161], v[186:189], v[94:97]
	v_mfma_f32_16x16x32_bf16 v[82:85], v[150:153], v[198:201], v[82:85]
	v_mfma_f32_16x16x32_bf16 v[74:77], v[158:161], v[198:201], v[74:77]
	v_mfma_f32_16x16x32_bf16 v[70:73], v[150:153], v[206:209], v[70:73]
	v_mfma_f32_16x16x32_bf16 v[66:69], v[158:161], v[206:209], v[66:69]
	s_barrier
	s_add_i32 s50, s50, s41
	v_lshl_add_u64 v[194:195], s[24:25], 0, v[168:169]
	s_mov_b32 m0, s50
	ds_read_b128 v[162:165], v197 offset:16384
	ds_read_b128 v[178:181], v197 offset:17408
	ds_read_b128 v[182:185], v197 offset:18432
	ds_read_b128 v[186:189], v197 offset:19456
	ds_read_b128 v[190:193], v197 offset:20480
	ds_read_b128 v[198:201], v197 offset:21504
	ds_read_b128 v[202:205], v197 offset:22528
	ds_read_b128 v[206:209], v197 offset:23552
	global_load_lds_dwordx4 v[194:195], off
	s_add_i32 m0, s50, 0x2000
	s_add_u32 s84, s24, 0x80000
	v_lshl_add_u64 v[210:211], s[24:25], 0, v[172:173]
	s_addc_u32 s85, s25, 0
	s_add_i32 s50, s51, s41
	global_load_lds_dwordx4 v[210:211], off
	v_lshl_add_u64 v[212:213], s[84:85], 0, v[168:169]
	s_mov_b32 m0, s50
	v_lshl_add_u64 v[214:215], s[38:39], 0, v[170:171]
	global_load_lds_dwordx4 v[212:213], off
	v_lshl_add_u64 v[212:213], s[84:85], 0, v[172:173]
	s_add_i32 m0, s50, 0x2000
	s_nop 0
	global_load_lds_dwordx4 v[212:213], off
	v_lshl_add_u64 v[212:213], s[38:39], 0, v[166:167]
	s_mov_b32 m0, s48
	s_nop 0
	global_load_lds_dwordx4 v[212:213], off
	s_mov_b32 m0, s49
	s_nop 0
	global_load_lds_dwordx4 v[214:215], off
	s_waitcnt vmcnt(8)
	s_waitcnt lgkmcnt(0)
	s_barrier
; #define PG8_STAGE(bufoff, gbase, rows) do { _Pragma("unroll") for (int _i = 0; _i < 2; ++_i) \
;         __builtin_amdgcn_global_load_lds((const unsigned*)((const char*)(gbase) + (rows)[_i]), (LAS unsigned*)(lds + (bufoff) + ldsw + _i * 8192), 16, 0, 0); } while (0)
; #define PG8_LDA(dst, b, h) do { _Pragma("unroll") for (int m = 0; m < 4; ++m) _Pragma("unroll") for (int k = 0; k < 2; ++k) dst[m][k] = *(const LAS bf16x8*)(lds + PG8_SA(b, h) + aoff + m * 2048 + k * 1024); } while (0)
; #define PG8_LDB(dst, b, h) do { _Pragma("unroll") for (int n = 0; n < 2; ++n) _Pragma("unroll") for (int k = 0; k < 2; ++k) dst[n][k] = *(const LAS bf16x8*)(lds + PG8_SB(b, h) + boff + n * 2048 + k * 1024); } while (0)
; #define PG8_MMA(ai, bj, At, Bt) do { __builtin_amdgcn_s_setprio(1); _Pragma("unroll") for (int m = 0; m < 4; ++m) _Pragma("unroll") for (int n = 0; n < 2; ++n) _Pragma("unroll") for (int k = 0; k < 2; ++k) \
;         acc[ai][bj][m][n] = __builtin_amdgcn_mfma_f32_16x16x32_bf16(Bt[n][k], At[m][k], acc[ai][bj][m][n], 0, 0, 0); __builtin_amdgcn_s_setprio(0); } while (0)
; #define PG8_WAIT_V(n) asm volatile("s_waitcnt vmcnt(" #n ")" ::: "memory")
; #define PG8_WAIT_L(n) asm volatile("s_waitcnt lgkmcnt(" #n ")" ::: "memory")
; #define PG8_BAR __builtin_amdgcn_s_barrier()
; #define PG8_SCHED __builtin_amdgcn_sched_barrier(0)
; template <class Epi, class Sched>
; __device__ __forceinline__ void gemm_phase(LAS unsigned char* lds, const Sched& S, const Epi& E, const int tid) {
;     ...
;             PG8_WAIT_V(8); PG8_WAIT_L(0); PG8_BAR; PG8_MMA(1, 0, At, B0); PG8_MMA(1, 1, At, B1); PG8_BAR; PG8_SCHED;
;             PG8_LDB(B0, 1, 0); PG8_LDB(B1, 1, 1); PG8_SCHED; PG8_LDA(At, 1, 0); PG8_STAGE(PG8_SA(0, 1), a2 + hA, vA);
;             PG8_WAIT_V(8); PG8_WAIT_L(0); PG8_BAR; PG8_MMA(0, 0, At, B0); PG8_MMA(0, 1, At, B1); PG8_BAR; PG8_SCHED;
	s_waitcnt lgkmcnt(0)
	v_mfma_f32_16x16x32_bf16 v[62:65], v[130:133], v[162:165], v[62:65]
	v_mfma_f32_16x16x32_bf16 v[58:61], v[138:141], v[162:165], v[58:61]
	v_mfma_f32_16x16x32_bf16 v[46:49], v[130:133], v[182:185], v[46:49]
	v_mfma_f32_16x16x32_bf16 v[38:41], v[138:141], v[182:185], v[38:41]
	v_mfma_f32_16x16x32_bf16 v[22:25], v[130:133], v[190:193], v[22:25]
	v_mfma_f32_16x16x32_bf16 v[14:17], v[138:141], v[190:193], v[14:17]
	v_mfma_f32_16x16x32_bf16 v[6:9], v[130:133], v[202:205], v[6:9]
	v_mfma_f32_16x16x32_bf16 v[2:5], v[138:141], v[202:205], v[2:5]
	v_mfma_f32_16x16x32_bf16 v[62:65], v[134:137], v[178:181], v[62:65]
	v_mfma_f32_16x16x32_bf16 v[58:61], v[142:145], v[178:181], v[58:61]
	v_mfma_f32_16x16x32_bf16 v[46:49], v[134:137], v[186:189], v[46:49]
	v_mfma_f32_16x16x32_bf16 v[38:41], v[142:145], v[186:189], v[38:41]
	v_mfma_f32_16x16x32_bf16 v[22:25], v[134:137], v[198:201], v[22:25]
	v_mfma_f32_16x16x32_bf16 v[14:17], v[142:145], v[198:201], v[14:17]
	v_mfma_f32_16x16x32_bf16 v[6:9], v[134:137], v[206:209], v[6:9]
	v_mfma_f32_16x16x32_bf16 v[2:5], v[142:145], v[206:209], v[2:5]
	v_mfma_f32_16x16x32_bf16 v[50:53], v[146:149], v[162:165], v[50:53]
	v_mfma_f32_16x16x32_bf16 v[34:37], v[154:157], v[162:165], v[34:37]
	v_mfma_f32_16x16x32_bf16 v[18:21], v[146:149], v[182:185], v[18:21]
	v_mfma_f32_16x16x32_bf16 v[10:13], v[154:157], v[182:185], v[10:13]
	v_mfma_f32_16x16x32_bf16 v[54:57], v[146:149], v[190:193], v[54:57]
	v_mfma_f32_16x16x32_bf16 v[42:45], v[154:157], v[190:193], v[42:45]
	v_mfma_f32_16x16x32_bf16 v[30:33], v[146:149], v[202:205], v[30:33]
	v_mfma_f32_16x16x32_bf16 v[26:29], v[154:157], v[202:205], v[26:29]
	v_mfma_f32_16x16x32_bf16 v[50:53], v[150:153], v[178:181], v[50:53]
	v_mfma_f32_16x16x32_bf16 v[34:37], v[158:161], v[178:181], v[34:37]
	v_mfma_f32_16x16x32_bf16 v[18:21], v[150:153], v[186:189], v[18:21]
	v_mfma_f32_16x16x32_bf16 v[10:13], v[158:161], v[186:189], v[10:13]
	v_mfma_f32_16x16x32_bf16 v[54:57], v[150:153], v[198:201], v[54:57]
	v_mfma_f32_16x16x32_bf16 v[42:45], v[158:161], v[198:201], v[42:45]
	v_mfma_f32_16x16x32_bf16 v[30:33], v[150:153], v[206:209], v[30:33]
	v_mfma_f32_16x16x32_bf16 v[26:29], v[158:161], v[206:209], v[26:29]
	s_barrier
	s_add_i32 s50, 0, 0x18000
	v_add_u32_e32 v0, s50, v196
	s_add_i32 s51, 0, 0x1c000
	ds_read_b128 v[130:133], v0
	ds_read_b128 v[134:137], v0 offset:1024
	ds_read_b128 v[138:141], v0 offset:2048
	ds_read_b128 v[142:145], v0 offset:3072
	v_add_u32_e32 v0, s51, v196
	ds_read_b128 v[146:149], v0
	ds_read_b128 v[150:153], v0 offset:1024
	ds_read_b128 v[154:157], v0 offset:2048
	ds_read_b128 v[158:161], v0 offset:3072
	s_add_u32 s38, s38, 0x80000
	s_addc_u32 s39, s39, 0
	s_mov_b32 m0, s52
	v_lshl_add_u64 v[216:217], s[38:39], 0, v[166:167]
	ds_read_b128 v[162:165], v197 offset:32768
	ds_read_b128 v[178:181], v197 offset:33792
	ds_read_b128 v[182:185], v197 offset:34816
	ds_read_b128 v[186:189], v197 offset:35840
	ds_read_b128 v[190:193], v197 offset:36864
	ds_read_b128 v[198:201], v197 offset:37888
	ds_read_b128 v[202:205], v197 offset:38912
	ds_read_b128 v[206:209], v197 offset:39936
	global_load_lds_dwordx4 v[216:217], off
	v_lshl_add_u64 v[216:217], s[38:39], 0, v[170:171]
	s_mov_b32 m0, s53
	s_nop 0
	global_load_lds_dwordx4 v[216:217], off
	s_waitcnt vmcnt(8)
	s_waitcnt lgkmcnt(0)
	s_barrier
	s_waitcnt lgkmcnt(0)
	v_mfma_f32_16x16x32_bf16 v[126:129], v[130:133], v[162:165], v[126:129]
	v_mfma_f32_16x16x32_bf16 v[122:125], v[138:141], v[162:165], v[122:125]
	v_mfma_f32_16x16x32_bf16 v[118:121], v[130:133], v[182:185], v[118:121]
	v_mfma_f32_16x16x32_bf16 v[106:109], v[138:141], v[182:185], v[106:109]
	v_mfma_f32_16x16x32_bf16 v[98:101], v[130:133], v[190:193], v[98:101]
	v_mfma_f32_16x16x32_bf16 v[90:93], v[138:141], v[190:193], v[90:93]
	v_mfma_f32_16x16x32_bf16 v[86:89], v[130:133], v[202:205], v[86:89]
	v_mfma_f32_16x16x32_bf16 v[78:81], v[138:141], v[202:205], v[78:81]
	v_mfma_f32_16x16x32_bf16 v[126:129], v[134:137], v[178:181], v[126:129]
	v_mfma_f32_16x16x32_bf16 v[122:125], v[142:145], v[178:181], v[122:125]
	v_mfma_f32_16x16x32_bf16 v[118:121], v[134:137], v[186:189], v[118:121]
	v_mfma_f32_16x16x32_bf16 v[106:109], v[142:145], v[186:189], v[106:109]
	v_mfma_f32_16x16x32_bf16 v[98:101], v[134:137], v[198:201], v[98:101]
	v_mfma_f32_16x16x32_bf16 v[90:93], v[142:145], v[198:201], v[90:93]
	v_mfma_f32_16x16x32_bf16 v[86:89], v[134:137], v[206:209], v[86:89]
	v_mfma_f32_16x16x32_bf16 v[78:81], v[142:145], v[206:209], v[78:81]
	v_mfma_f32_16x16x32_bf16 v[114:117], v[146:149], v[162:165], v[114:117]
	v_mfma_f32_16x16x32_bf16 v[110:113], v[154:157], v[162:165], v[110:113]
	v_mfma_f32_16x16x32_bf16 v[102:105], v[146:149], v[182:185], v[102:105]
	v_mfma_f32_16x16x32_bf16 v[94:97], v[154:157], v[182:185], v[94:97]
	v_mfma_f32_16x16x32_bf16 v[82:85], v[146:149], v[190:193], v[82:85]
	v_mfma_f32_16x16x32_bf16 v[74:77], v[154:157], v[190:193], v[74:77]
	v_mfma_f32_16x16x32_bf16 v[70:73], v[146:149], v[202:205], v[70:73]
	v_mfma_f32_16x16x32_bf16 v[66:69], v[154:157], v[202:205], v[66:69]
	v_mfma_f32_16x16x32_bf16 v[114:117], v[150:153], v[178:181], v[114:117]
	v_mfma_f32_16x16x32_bf16 v[110:113], v[158:161], v[178:181], v[110:113]
	v_mfma_f32_16x16x32_bf16 v[102:105], v[150:153], v[186:189], v[102:105]
	v_mfma_f32_16x16x32_bf16 v[94:97], v[158:161], v[186:189], v[94:97]
	v_mfma_f32_16x16x32_bf16 v[82:85], v[150:153], v[198:201], v[82:85]
	v_mfma_f32_16x16x32_bf16 v[74:77], v[158:161], v[198:201], v[74:77]
	v_mfma_f32_16x16x32_bf16 v[70:73], v[150:153], v[206:209], v[70:73]
	v_mfma_f32_16x16x32_bf16 v[66:69], v[158:161], v[206:209], v[66:69]
	s_barrier
; #define PG8_STAGE(bufoff, gbase, rows) do { _Pragma("unroll") for (int _i = 0; _i < 2; ++_i) \
;         __builtin_amdgcn_global_load_lds((const unsigned*)((const char*)(gbase) + (rows)[_i]), (LAS unsigned*)(lds + (bufoff) + ldsw + _i * 8192), 16, 0, 0); } while (0)
; #define PG8_LDA(dst, b, h) do { _Pragma("unroll") for (int m = 0; m < 4; ++m) _Pragma("unroll") for (int k = 0; k < 2; ++k) dst[m][k] = *(const LAS bf16x8*)(lds + PG8_SA(b, h) + aoff + m * 2048 + k * 1024); } while (0)
; #define PG8_MMA(ai, bj, At, Bt) do { __builtin_amdgcn_s_setprio(1); _Pragma("unroll") for (int m = 0; m < 4; ++m) _Pragma("unroll") for (int n = 0; n < 2; ++n) _Pragma("unroll") for (int k = 0; k < 2; ++k) \
;         acc[ai][bj][m][n] = __builtin_amdgcn_mfma_f32_16x16x32_bf16(Bt[n][k], At[m][k], acc[ai][bj][m][n], 0, 0, 0); __builtin_amdgcn_s_setprio(0); } while (0)
; #define PG8_WAIT_V(n) asm volatile("s_waitcnt vmcnt(" #n ")" ::: "memory")
; #define PG8_WAIT_L(n) asm volatile("s_waitcnt lgkmcnt(" #n ")" ::: "memory")
; #define PG8_BAR __builtin_amdgcn_s_barrier()
; #define PG8_SCHED __builtin_amdgcn_sched_barrier(0)
; template <class Epi, class Sched>
; __device__ __forceinline__ void gemm_phase(LAS unsigned char* lds, const Sched& S, const Epi& E, const int tid) {
;     ...
;             PG8_LDA(At, 1, 1); PG8_STAGE(PG8_SB(1, 0), b3, vB); PG8_STAGE(PG8_SB(1, 1), b3 + hB, vB); PG8_STAGE(PG8_SA(1, 0), a3, vA);
;             PG8_WAIT_V(8); PG8_WAIT_L(0); PG8_BAR; PG8_MMA(1, 0, At, B0); PG8_MMA(1, 1, At, B1); PG8_BAR; PG8_SCHED;
;         }
;         if (wr == 0) PG8_BAR;
	s_add_i32 s38, s50, s41
	v_lshl_add_u64 v[194:195], v[194:195], 0, s[82:83]
	s_mov_b32 m0, s38
	ds_read_b128 v[162:165], v197 offset:49152
	ds_read_b128 v[178:181], v197 offset:50176
	ds_read_b128 v[182:185], v197 offset:51200
	ds_read_b128 v[186:189], v197 offset:52224
	ds_read_b128 v[190:193], v197 offset:53248
	ds_read_b128 v[198:201], v197 offset:54272
	ds_read_b128 v[202:205], v197 offset:55296
	ds_read_b128 v[206:209], v197 offset:56320
	global_load_lds_dwordx4 v[194:195], off
	s_add_i32 m0, s38, 0x2000
	s_add_u32 s24, s24, 0x80080
	v_lshl_add_u64 v[194:195], v[210:211], 0, s[82:83]
	s_addc_u32 s25, s25, 0
	s_add_i32 s38, s51, s41
	global_load_lds_dwordx4 v[194:195], off
	v_lshl_add_u64 v[194:195], s[24:25], 0, v[168:169]
	s_mov_b32 m0, s38
	s_nop 0
	global_load_lds_dwordx4 v[194:195], off
	v_lshl_add_u64 v[194:195], s[24:25], 0, v[172:173]
	s_add_i32 m0, s38, 0x2000
	s_nop 0
	global_load_lds_dwordx4 v[194:195], off
	v_lshl_add_u64 v[194:195], v[212:213], 0, s[82:83]
	s_mov_b32 m0, s64
	s_nop 0
	global_load_lds_dwordx4 v[194:195], off
	v_lshl_add_u64 v[194:195], v[214:215], 0, s[82:83]
	s_mov_b32 m0, s76
	s_nop 0
	global_load_lds_dwordx4 v[194:195], off
	s_waitcnt vmcnt(8)
	s_waitcnt lgkmcnt(0)
	s_barrier
	s_waitcnt lgkmcnt(0)
	v_mfma_f32_16x16x32_bf16 v[62:65], v[130:133], v[162:165], v[62:65]
	v_mfma_f32_16x16x32_bf16 v[58:61], v[138:141], v[162:165], v[58:61]
	v_mfma_f32_16x16x32_bf16 v[46:49], v[130:133], v[182:185], v[46:49]
	v_mfma_f32_16x16x32_bf16 v[38:41], v[138:141], v[182:185], v[38:41]
	v_mfma_f32_16x16x32_bf16 v[22:25], v[130:133], v[190:193], v[22:25]
	v_mfma_f32_16x16x32_bf16 v[14:17], v[138:141], v[190:193], v[14:17]
	v_mfma_f32_16x16x32_bf16 v[6:9], v[130:133], v[202:205], v[6:9]
	v_mfma_f32_16x16x32_bf16 v[2:5], v[138:141], v[202:205], v[2:5]
	v_mfma_f32_16x16x32_bf16 v[62:65], v[134:137], v[178:181], v[62:65]
	v_mfma_f32_16x16x32_bf16 v[58:61], v[142:145], v[178:181], v[58:61]
	v_mfma_f32_16x16x32_bf16 v[46:49], v[134:137], v[186:189], v[46:49]
	v_mfma_f32_16x16x32_bf16 v[38:41], v[142:145], v[186:189], v[38:41]
	v_mfma_f32_16x16x32_bf16 v[22:25], v[134:137], v[198:201], v[22:25]
	v_mfma_f32_16x16x32_bf16 v[14:17], v[142:145], v[198:201], v[14:17]
	v_mfma_f32_16x16x32_bf16 v[6:9], v[134:137], v[206:209], v[6:9]
	v_mfma_f32_16x16x32_bf16 v[2:5], v[142:145], v[206:209], v[2:5]
	v_mfma_f32_16x16x32_bf16 v[50:53], v[146:149], v[162:165], v[50:53]
	v_mfma_f32_16x16x32_bf16 v[34:37], v[154:157], v[162:165], v[34:37]
	v_mfma_f32_16x16x32_bf16 v[18:21], v[146:149], v[182:185], v[18:21]
	v_mfma_f32_16x16x32_bf16 v[10:13], v[154:157], v[182:185], v[10:13]
	v_mfma_f32_16x16x32_bf16 v[54:57], v[146:149], v[190:193], v[54:57]
	v_mfma_f32_16x16x32_bf16 v[42:45], v[154:157], v[190:193], v[42:45]
	v_mfma_f32_16x16x32_bf16 v[30:33], v[146:149], v[202:205], v[30:33]
	v_mfma_f32_16x16x32_bf16 v[26:29], v[154:157], v[202:205], v[26:29]
	v_mfma_f32_16x16x32_bf16 v[50:53], v[150:153], v[178:181], v[50:53]
	v_mfma_f32_16x16x32_bf16 v[34:37], v[158:161], v[178:181], v[34:37]
	v_mfma_f32_16x16x32_bf16 v[18:21], v[150:153], v[186:189], v[18:21]
	v_mfma_f32_16x16x32_bf16 v[10:13], v[158:161], v[186:189], v[10:13]
	v_mfma_f32_16x16x32_bf16 v[54:57], v[150:153], v[198:201], v[54:57]
	v_mfma_f32_16x16x32_bf16 v[42:45], v[158:161], v[198:201], v[42:45]
	v_mfma_f32_16x16x32_bf16 v[30:33], v[150:153], v[206:209], v[30:33]
	v_mfma_f32_16x16x32_bf16 v[26:29], v[158:161], v[206:209], v[26:29]
	s_barrier
	s_add_i32 s80, s80, 2
	s_add_u32 s4, s4, 0x100
	s_addc_u32 s5, s5, 0
	s_add_u32 s17, s17, 0x100
	s_addc_u32 s23, s23, 0
	s_cmp_gt_u32 s80, 29
	s_cbranch_scc0 .LBB0_782
	s_and_b64 vcc, exec, s[10:11]
	s_cbranch_vccz .LBB0_785
	s_barrier

; __device__ __forceinline__ void xcd_barrier(const XcdBarrier& b) {
;     asm volatile("s_waitcnt vmcnt(0)" ::: "memory");
;     __syncthreads();
;     if (threadIdx.x == 0) {
;         unsigned* bar = b.bar;
;         __builtin_amdgcn_s_waitcnt(0);
;         unsigned nloc = b.st[0], nx = b.st[1];
;         if (nloc == 0u) { xcd_barrier_complete(bar, b.x, nloc, nx); b.st[0] = nloc; b.st[1] = nx; }
.LBB0_793:
	s_mov_b64 s[4:5], s[66:67]
	s_waitcnt vmcnt(0) lgkmcnt(0)
	s_setprio 0
	s_getreg_b32 s8, hwreg(HW_REG_XCC_ID, 0, 4)
	s_waitcnt vmcnt(0)
	s_waitcnt lgkmcnt(0)
	s_barrier
	s_and_saveexec_b64 s[0:1], s[26:27]
	s_cbranch_execz .LBB0_845
	v_mov_b32_e32 v0, s96
	s_load_dwordx2 s[4:5], s[4:5], 0xc0
	s_waitcnt vmcnt(0) expcnt(0) lgkmcnt(0)
	ds_read_b32 v3, v0
	v_mov_b32_e32 v0, s97
	ds_read_b32 v2, v0
	s_and_b32 s30, s8, 15
	s_waitcnt lgkmcnt(1)
	v_cmp_ne_u32_e32 vcc, 0, v3
	s_cbranch_vccnz .LBB0_809
	s_add_u32 s8, s4, 0x1200
	s_addc_u32 s9, s5, 0
	s_add_u32 s10, s4, 0x1400
	s_addc_u32 s11, s5, 0
	s_add_u32 s12, s4, 0x1500
	s_addc_u32 s13, s5, 0
	s_add_u32 s14, s4, 0x1600
	s_addc_u32 s15, s5, 0
	s_add_u32 s16, s4, 0x1700
	s_addc_u32 s17, s5, 0
	s_add_u32 s18, s4, 0x1800
	s_addc_u32 s19, s5, 0
	s_add_u32 s20, s4, 0x1900
	s_addc_u32 s21, s5, 0
	s_add_u32 s22, s4, 0x1a00
	s_addc_u32 s23, s5, 0
	s_add_u32 s24, s4, 0x1b00
	s_addc_u32 s25, s5, 0
	s_add_u32 s38, s4, 0x1c00
	s_addc_u32 s39, s5, 0
	s_add_u32 s48, s4, 0x1d00
	s_addc_u32 s49, s5, 0
	s_add_u32 s52, s4, 0x1e00
	s_addc_u32 s53, s5, 0
	s_add_u32 s76, s4, 0x1f00
	s_addc_u32 s77, s5, 0
	s_add_u32 s78, s4, 0x2000
	s_addc_u32 s79, s5, 0
	s_add_u32 s80, s4, 0x2100
	s_addc_u32 s81, s5, 0
	s_add_u32 s84, s4, 0x2200
	s_addc_u32 s85, s5, 0
	s_add_u32 s86, s4, 0x2300
	s_addc_u32 s87, s5, 0
	s_mov_b32 s35, 1
	s_branch .LBB0_797

; __device__ __forceinline__ ParamsCP get_params() { ParamsCP q = (ParamsCP)__builtin_amdgcn_kernarg_segment_ptr(); asm volatile("" : "+s"(q)); return q; }
; #define PG8_BAR __builtin_amdgcn_s_barrier()
; template <class Epi, class Sched>
; __device__ __forceinline__ void gemm_phase(LAS unsigned char* lds, const Sched& S, const Epi& E, const int tid) {
;     const int wid = __builtin_amdgcn_readfirstlane(tid >> 6), lane = tid & 63, wr = wid >> 2, wc = wid & 3, fr = lane & 15, fq = lane >> 4;
;     int sR[2], sC[2], sRbi[2];
; #pragma unroll
;     for (int i = 0; i < 2; ++i) { stage_rc(tid * 16 + i * 8192, sR[i], sC[i]); sRbi[i] = (sR[i] & ~31) + perm32(sR[i] & 31); }
;     const unsigned ldsw = (unsigned)wid * 1024u;
;     const int aoff = lds_byte(wr * 64 + fr, fq * 8), boff = lds_byte(wc * 32 + fr, fq * 8);
;     ...
;     GUnit cur, nxt; int ui = 0;
;     if (!S.next(0, cur)) return;
;     f32x4 acc[2][2][4][2];
; #pragma unroll
;     for (int a = 0; a < 2; ++a)
; #pragma unroll
;         for (int b = 0; b < 2; ++b)
; #pragma unroll
;             for (int m = 0; m < 4; ++m)
; #pragma unroll
;                 for (int n = 0; n < 2; ++n) acc[a][b][m][n] = (f32x4){0.f, 0.f, 0.f, 0.f};
;     bf16x8 At[4][2], B0[2][2], B1[2][2];
;     const char* cA = cur.A; const char* cB = cur.B;
;     constexpr unsigned kstep = (unsigned)(BK * 2);
;     const unsigned lda = cur.lda, ldb = cur.ldb, hA = HALF * lda, hB = HALF * ldb;
;     unsigned vA[2], vB[2];
; #pragma unroll
;     for (int i = 0; i < 2; ++i) { vA[i] = (unsigned)sR[i] * lda + (unsigned)sC[i] * 2u; vB[i] = (unsigned)sRbi[i] * ldb + (unsigned)sC[i] * 2u; }
;     PG8_STAGE(PG8_SB(0, 0), cB, vB); PG8_STAGE(PG8_SB(0, 1), cB + hB, vB); PG8_STAGE(PG8_SA(0, 0), cA, vA); PG8_STAGE(PG8_SA(0, 1), cA + hA, vA);
;     if (wr == 1) PG8_BAR;
; __global__ void __launch_bounds__(512) fwd_kernel(Params p_unused) {
;     ...
;         { FRESH_IDS(); ParamsCP pp = get_params(); unsigned char* ws = pp->ws; float* hmeta = (float*)(ws + WS_HMETA);
;           if (blk < 8) { SchedPlain S{(const char*)(ws + WS_BIG + BIG_MERGED), (const char*)(ws + WS_WT + WT_OUT), 4096u, 4096u, 32, 1, 8, 0, 8, blk};
;                          EpiResid E{layer == 0 ? pp->in[0] : (const float*)pp->out, hmeta, pp->out, hmeta}; pg8::gemm_phase(lds, S, E, tid); }
.LBB0_852:
	s_andn2_b64 vcc, exec, s[4:5]
	s_cbranch_vccnz .LBB0_872
	v_bfe_i32 v2, v79, 27, 1
	v_lshlrev_b32_e32 v4, 4, v79
	v_lshrrev_b32_e32 v2, 22, v2
	v_ashrrev_i32_e32 v0, 31, v79
	v_add_u32_e32 v2, v4, v2
	v_lshrrev_b32_e32 v0, 26, v0
	v_and_b32_e32 v2, 0xfffffc00, v2
	v_add_u32_e32 v0, v79, v0
	v_sub_u32_e32 v2, v4, v2
	v_ashrrev_i32_e32 v0, 6, v0
	v_lshrrev_b32_e32 v3, 4, v2
	v_bitop3_b32 v3, v3, v2, 32 bitop3:0x6c
	v_lshlrev_b32_e32 v2, 3, v0
	v_and_b32_e32 v5, -16, v2
	v_ashrrev_i32_e32 v2, 31, v3
	v_lshrrev_b32_e32 v2, 26, v2
	v_add_u32_e32 v6, v3, v2
	v_ashrrev_i32_e32 v2, 6, v6
	v_add_u32_e32 v7, v2, v5
	v_lshlrev_b32_e32 v5, 5, v0
	v_and_b32_e32 v8, 32, v5
	v_and_b32_e32 v5, 0xc0, v6
	v_sub_u32_e32 v3, v3, v5
	v_lshlrev_b32_e32 v5, 1, v7
	v_lshrrev_b32_e32 v6, 2, v7
	v_and_b32_e32 v9, 3, v2
	v_and_b32_e32 v5, 24, v5
	v_and_b32_e32 v6, 4, v6
	v_and_or_b32 v9, v7, s55, v9
	v_or3_b32 v9, v9, v6, v5
	v_add_u32_e32 v5, 0x2000, v4
	s_add_u32 s30, s0, 0x2a880000
	v_ashrrev_i32_e32 v4, 31, v5
	s_addc_u32 s40, s1, 0
	v_lshrrev_b32_e32 v4, 22, v4
	s_add_u32 s41, s0, 0x5c00000
	v_add_u32_e32 v4, v5, v4
	s_addc_u32 s48, s1, 0
	v_readlane_b32 s0, v254, 60
	v_ashrrev_i32_e32 v4, 10, v4
	v_readlane_b32 s1, v254, 61
	v_mul_i32_i24_e32 v6, 0x400, v4
	s_and_b64 s[0:1], s[0:1], exec
	v_sub_u32_e32 v5, v5, v6
	s_cselect_b32 s0, 0, 0xb8
	v_lshrrev_b32_e32 v6, 4, v5
	s_add_u32 s0, s8, s0
	v_readfirstlane_b32 s12, v79
	v_bitop3_b32 v6, v6, v5, 32 bitop3:0x6c
	v_lshlrev_b32_e32 v5, 3, v4
	s_addc_u32 s1, s9, 0
	v_and_b32_e32 v10, -16, v5
	v_ashrrev_i32_e32 v5, 31, v6
	s_ashr_i32 s14, s12, 6
	s_ashr_i32 s13, s12, 8
	v_lshrrev_b32_e32 v5, 26, v5
	s_lshl_b32 s49, s14, 10
	v_readlane_b32 s4, v254, 34
	v_add_u32_e32 v11, v6, v5
	v_readlane_b32 s5, v254, 35
	s_add_u32 s4, s30, s4
	v_ashrrev_i16_sdwa v3, v231, sext(v3) dst_sel:DWORD dst_unused:UNUSED_PAD src0_sel:DWORD src1_sel:BYTE_0
	v_ashrrev_i32_e32 v5, 6, v11
	v_and_b32_e32 v11, 0xc0, v11
	s_addc_u32 s5, s40, s5
	v_readlane_b32 s10, v254, 36
	v_bfe_i32 v3, v3, 0, 16
	v_add_u32_e32 v10, v5, v10
	v_sub_u32_e32 v6, v6, v11
	v_readlane_b32 s11, v254, 37
	s_add_u32 s24, s41, s10
	v_lshlrev_b32_e32 v12, 5, v4
	v_ashrrev_i16_sdwa v6, v231, sext(v6) dst_sel:DWORD dst_unused:UNUSED_PAD src0_sel:DWORD src1_sel:BYTE_0
	v_lshlrev_b32_e32 v11, 1, v10
	v_lshrrev_b32_e32 v13, 2, v10
	v_and_b32_e32 v14, 3, v5
	s_addc_u32 s25, s48, s11
	v_add_lshl_u32 v8, v8, v3, 1
	s_add_i32 s52, s49, 0
	v_and_b32_e32 v12, 32, v12
	v_bfe_i32 v6, v6, 0, 16
	v_and_b32_e32 v11, 24, v11
	v_and_b32_e32 v13, 4, v13
	v_and_or_b32 v14, v10, s55, v14
	v_lshl_add_u32 v168, v9, 12, v8
	s_add_i32 m0, s52, 0x10000
	v_or3_b32 v11, v14, v13, v11
	v_lshl_add_u32 v166, v7, 12, v8
	v_add_lshl_u32 v7, v12, v6, 1
	global_load_lds_dwordx4 v168, s[24:25]
	s_add_i32 m0, s52, 0x12000
	v_lshl_add_u32 v172, v11, 12, v7
	s_add_u32 s10, s24, 0x80000
	global_load_lds_dwordx4 v172, s[24:25]
	s_addc_u32 s11, s25, 0
	s_add_i32 m0, s52, 0x14000
	s_add_i32 s53, s52, 0x2000
	global_load_lds_dwordx4 v168, s[10:11]
	s_add_i32 m0, s52, 0x16000
	v_lshl_add_u32 v170, v10, 12, v7
	global_load_lds_dwordx4 v172, s[10:11]
	s_mov_b32 m0, s52
	s_add_u32 s10, s4, 0x80000
	global_load_lds_dwordx4 v166, s[4:5]
	s_mov_b32 m0, s53
	s_addc_u32 s11, s5, 0
	s_add_i32 s60, s52, 0x4000
	global_load_lds_dwordx4 v170, s[4:5]
	s_mov_b32 m0, s60
	s_add_i32 s61, s52, 0x6000
	global_load_lds_dwordx4 v166, s[10:11]
	s_mov_b32 m0, s61
	s_cmp_eq_u32 s13, 1
	global_load_lds_dwordx4 v170, s[10:11]
	s_load_dwordx2 s[0:1], s[0:1], 0x0
	s_nop 0
	s_load_dwordx2 s[8:9], s[8:9], 0xb8
	s_cselect_b64 s[10:11], -1, 0
	s_cmp_lg_u32 s13, 1
	s_cbranch_scc1 .LBB0_855
	s_setprio 1
	s_barrier

; #define PG8_STAGE(bufoff, gbase, rows) do { _Pragma("unroll") for (int _i = 0; _i < 2; ++_i) \
;         __builtin_amdgcn_global_load_lds((const unsigned*)((const char*)(gbase) + (rows)[_i]), (LAS unsigned*)(lds + (bufoff) + ldsw + _i * 8192), 16, 0, 0); } while (0)
; #define PG8_LDA(dst, b, h) do { _Pragma("unroll") for (int m = 0; m < 4; ++m) _Pragma("unroll") for (int k = 0; k < 2; ++k) dst[m][k] = *(const LAS bf16x8*)(lds + PG8_SA(b, h) + aoff + m * 2048 + k * 1024); } while (0)
; #define PG8_LDB(dst, b, h) do { _Pragma("unroll") for (int n = 0; n < 2; ++n) _Pragma("unroll") for (int k = 0; k < 2; ++k) dst[n][k] = *(const LAS bf16x8*)(lds + PG8_SB(b, h) + boff + n * 2048 + k * 1024); } while (0)
; #define PG8_MMA(ai, bj, At, Bt) do { __builtin_amdgcn_s_setprio(1); _Pragma("unroll") for (int m = 0; m < 4; ++m) _Pragma("unroll") for (int n = 0; n < 2; ++n) _Pragma("unroll") for (int k = 0; k < 2; ++k) \
;         acc[ai][bj][m][n] = __builtin_amdgcn_mfma_f32_16x16x32_bf16(Bt[n][k], At[m][k], acc[ai][bj][m][n], 0, 0, 0); __builtin_amdgcn_s_setprio(0); } while (0)
; #define PG8_WAIT_V(n) asm volatile("s_waitcnt vmcnt(" #n ")" ::: "memory")
; #define PG8_WAIT_L(n) asm volatile("s_waitcnt lgkmcnt(" #n ")" ::: "memory")
; #define PG8_BAR __builtin_amdgcn_s_barrier()
; #define PG8_SCHED __builtin_amdgcn_sched_barrier(0)
; template <class Epi, class Sched>
; __device__ __forceinline__ void gemm_phase(LAS unsigned char* lds, const Sched& S, const Epi& E, const int tid) {
;     ...
;         for (int t = 0; t < nt; t += 2) {
;             const bool last = (t == nt - 2);
;             const char* a1 = cA + (size_t)(t + 1) * kstep;
;             const char* a2 = last ? nA : cA + (size_t)(t + 2) * kstep; const char* b2 = last ? nB : cB + (size_t)(t + 2) * kstep;
;             const char* a3 = a2 + kstep; const char* b3 = b2 + kstep;
;             PG8_LDB(B0, 0, 0); PG8_LDB(B1, 0, 1); PG8_SCHED; PG8_LDA(At, 0, 0); PG8_STAGE(PG8_SA(1, 1), a1 + hA, vA);
;             PG8_WAIT_V(8); PG8_WAIT_L(0); PG8_BAR; PG8_MMA(0, 0, At, B0); PG8_MMA(0, 1, At, B1); PG8_BAR; PG8_SCHED;
;             PG8_LDA(At, 0, 1); PG8_STAGE(PG8_SB(0, 0), b2, vB); PG8_STAGE(PG8_SB(0, 1), b2 + hB, vB); PG8_STAGE(PG8_SA(0, 0), a2, vA);
;             PG8_WAIT_V(8); PG8_WAIT_L(0); PG8_BAR; PG8_MMA(1, 0, At, B0); PG8_MMA(1, 1, At, B1); PG8_BAR; PG8_SCHED;
.LBB0_861:
	s_add_u32 s24, s4, 0xfff80080
	s_addc_u32 s25, s5, -1
	s_add_i32 s50, 0, 0x10000
	s_cmp_eq_u32 s80, 28
	s_cselect_b32 s39, s17, s25
	s_cselect_b32 s38, s16, s24
	v_add_u32_e32 v0, s50, v196
	s_cselect_b32 s25, s19, s23
	s_cselect_b32 s24, s18, s15
	s_add_i32 s51, 0, 0x14000
	ds_read_b128 v[130:133], v0
	ds_read_b128 v[134:137], v0 offset:1024
	ds_read_b128 v[138:141], v0 offset:2048
	ds_read_b128 v[142:145], v0 offset:3072
	v_add_u32_e32 v0, s51, v196
	ds_read_b128 v[146:149], v0
	ds_read_b128 v[150:153], v0 offset:1024
	ds_read_b128 v[154:157], v0 offset:2048
	ds_read_b128 v[158:161], v0 offset:3072
	v_lshl_add_u64 v[194:195], s[4:5], 0, v[174:175]
	s_add_i32 m0, s52, 0xc000
	ds_read_b128 v[162:165], v197
	ds_read_b128 v[178:181], v197 offset:1024
	ds_read_b128 v[182:185], v197 offset:2048
	ds_read_b128 v[186:189], v197 offset:3072
	ds_read_b128 v[190:193], v197 offset:4096
	ds_read_b128 v[198:201], v197 offset:5120
	ds_read_b128 v[202:205], v197 offset:6144
	ds_read_b128 v[206:209], v197 offset:7168
	global_load_lds_dwordx4 v[194:195], off
	v_lshl_add_u64 v[194:195], s[4:5], 0, v[176:177]
	s_add_i32 m0, s52, 0xe000
	s_nop 0
	global_load_lds_dwordx4 v[194:195], off
	s_waitcnt vmcnt(8)
	s_waitcnt lgkmcnt(0)
	s_barrier
	s_waitcnt lgkmcnt(0)
	v_mfma_f32_16x16x32_bf16 v[126:129], v[130:133], v[162:165], v[126:129]
	v_mfma_f32_16x16x32_bf16 v[122:125], v[138:141], v[162:165], v[122:125]
	v_mfma_f32_16x16x32_bf16 v[118:121], v[130:133], v[182:185], v[118:121]
	v_mfma_f32_16x16x32_bf16 v[106:109], v[138:141], v[182:185], v[106:109]
	v_mfma_f32_16x16x32_bf16 v[98:101], v[130:133], v[190:193], v[98:101]
	v_mfma_f32_16x16x32_bf16 v[90:93], v[138:141], v[190:193], v[90:93]
	v_mfma_f32_16x16x32_bf16 v[86:89], v[130:133], v[202:205], v[86:89]
	v_mfma_f32_16x16x32_bf16 v[78:81], v[138:141], v[202:205], v[78:81]
	v_mfma_f32_16x16x32_bf16 v[126:129], v[134:137], v[178:181], v[126:129]
	v_mfma_f32_16x16x32_bf16 v[122:125], v[142:145], v[178:181], v[122:125]
	v_mfma_f32_16x16x32_bf16 v[118:121], v[134:137], v[186:189], v[118:121]
	v_mfma_f32_16x16x32_bf16 v[106:109], v[142:145], v[186:189], v[106:109]
	v_mfma_f32_16x16x32_bf16 v[98:101], v[134:137], v[198:201], v[98:101]
	v_mfma_f32_16x16x32_bf16 v[90:93], v[142:145], v[198:201], v[90:93]
	v_mfma_f32_16x16x32_bf16 v[86:89], v[134:137], v[206:209], v[86:89]
	v_mfma_f32_16x16x32_bf16 v[78:81], v[142:145], v[206:209], v[78:81]
	v_mfma_f32_16x16x32_bf16 v[114:117], v[146:149], v[162:165], v[114:117]
	v_mfma_f32_16x16x32_bf16 v[110:113], v[154:157], v[162:165], v[110:113]
	v_mfma_f32_16x16x32_bf16 v[102:105], v[146:149], v[182:185], v[102:105]
	v_mfma_f32_16x16x32_bf16 v[94:97], v[154:157], v[182:185], v[94:97]
	v_mfma_f32_16x16x32_bf16 v[82:85], v[146:149], v[190:193], v[82:85]
	v_mfma_f32_16x16x32_bf16 v[74:77], v[154:157], v[190:193], v[74:77]
	v_mfma_f32_16x16x32_bf16 v[70:73], v[146:149], v[202:205], v[70:73]
	v_mfma_f32_16x16x32_bf16 v[66:69], v[154:157], v[202:205], v[66:69]
	v_mfma_f32_16x16x32_bf16 v[114:117], v[150:153], v[178:181], v[114:117]
	v_mfma_f32_16x16x32_bf16 v[110:113], v[158:161], v[178:181], v[110:113]
	v_mfma_f32_16x16x32_bf16 v[102:105], v[150:153], v[186:189], v[102:105]
	v_mfma_f32_16x16x32_bf16 v[94:97], v[158:161], v[186:189], v[94:97]
	v_mfma_f32_16x16x32_bf16 v[82:85], v[150:153], v[198:201], v[82:85]
	v_mfma_f32_16x16x32_bf16 v[74:77], v[158:161], v[198:201], v[74:77]
	v_mfma_f32_16x16x32_bf16 v[70:73], v[150:153], v[206:209], v[70:73]
	v_mfma_f32_16x16x32_bf16 v[66:69], v[158:161], v[206:209], v[66:69]
	s_barrier
	s_add_i32 s50, s50, s49
	v_lshl_add_u64 v[194:195], s[24:25], 0, v[168:169]
	s_mov_b32 m0, s50
	ds_read_b128 v[162:165], v197 offset:16384
	ds_read_b128 v[178:181], v197 offset:17408
	ds_read_b128 v[182:185], v197 offset:18432
	ds_read_b128 v[186:189], v197 offset:19456
	ds_read_b128 v[190:193], v197 offset:20480
	ds_read_b128 v[198:201], v197 offset:21504
	ds_read_b128 v[202:205], v197 offset:22528
	ds_read_b128 v[206:209], v197 offset:23552
	global_load_lds_dwordx4 v[194:195], off
	s_add_i32 m0, s50, 0x2000
	s_add_u32 s84, s24, 0x80000
	v_lshl_add_u64 v[210:211], s[24:25], 0, v[172:173]
	s_addc_u32 s85, s25, 0
	s_add_i32 s50, s51, s49
	global_load_lds_dwordx4 v[210:211], off
	v_lshl_add_u64 v[212:213], s[84:85], 0, v[168:169]
	s_mov_b32 m0, s50
	v_lshl_add_u64 v[214:215], s[38:39], 0, v[170:171]
	global_load_lds_dwordx4 v[212:213], off
	v_lshl_add_u64 v[212:213], s[84:85], 0, v[172:173]
	s_add_i32 m0, s50, 0x2000
	s_nop 0
	global_load_lds_dwordx4 v[212:213], off
	v_lshl_add_u64 v[212:213], s[38:39], 0, v[166:167]
	s_mov_b32 m0, s52
	s_nop 0
	global_load_lds_dwordx4 v[212:213], off
	s_mov_b32 m0, s53
	s_nop 0
	global_load_lds_dwordx4 v[214:215], off
	s_waitcnt vmcnt(8)
	s_waitcnt lgkmcnt(0)
	s_barrier
; #define PG8_STAGE(bufoff, gbase, rows) do { _Pragma("unroll") for (int _i = 0; _i < 2; ++_i) \
;         __builtin_amdgcn_global_load_lds((const unsigned*)((const char*)(gbase) + (rows)[_i]), (LAS unsigned*)(lds + (bufoff) + ldsw + _i * 8192), 16, 0, 0); } while (0)
; #define PG8_LDA(dst, b, h) do { _Pragma("unroll") for (int m = 0; m < 4; ++m) _Pragma("unroll") for (int k = 0; k < 2; ++k) dst[m][k] = *(const LAS bf16x8*)(lds + PG8_SA(b, h) + aoff + m * 2048 + k * 1024); } while (0)
; #define PG8_LDB(dst, b, h) do { _Pragma("unroll") for (int n = 0; n < 2; ++n) _Pragma("unroll") for (int k = 0; k < 2; ++k) dst[n][k] = *(const LAS bf16x8*)(lds + PG8_SB(b, h) + boff + n * 2048 + k * 1024); } while (0)
; #define PG8_MMA(ai, bj, At, Bt) do { __builtin_amdgcn_s_setprio(1); _Pragma("unroll") for (int m = 0; m < 4; ++m) _Pragma("unroll") for (int n = 0; n < 2; ++n) _Pragma("unroll") for (int k = 0; k < 2; ++k) \
;         acc[ai][bj][m][n] = __builtin_amdgcn_mfma_f32_16x16x32_bf16(Bt[n][k], At[m][k], acc[ai][bj][m][n], 0, 0, 0); __builtin_amdgcn_s_setprio(0); } while (0)
; #define PG8_WAIT_V(n) asm volatile("s_waitcnt vmcnt(" #n ")" ::: "memory")
; #define PG8_WAIT_L(n) asm volatile("s_waitcnt lgkmcnt(" #n ")" ::: "memory")
; #define PG8_BAR __builtin_amdgcn_s_barrier()
; #define PG8_SCHED __builtin_amdgcn_sched_barrier(0)
; template <class Epi, class Sched>
; __device__ __forceinline__ void gemm_phase(LAS unsigned char* lds, const Sched& S, const Epi& E, const int tid) {
;     ...
;             PG8_WAIT_V(8); PG8_WAIT_L(0); PG8_BAR; PG8_MMA(1, 0, At, B0); PG8_MMA(1, 1, At, B1); PG8_BAR; PG8_SCHED;
;             PG8_LDB(B0, 1, 0); PG8_LDB(B1, 1, 1); PG8_SCHED; PG8_LDA(At, 1, 0); PG8_STAGE(PG8_SA(0, 1), a2 + hA, vA);
;             PG8_WAIT_V(8); PG8_WAIT_L(0); PG8_BAR; PG8_MMA(0, 0, At, B0); PG8_MMA(0, 1, At, B1); PG8_BAR; PG8_SCHED;
	s_waitcnt lgkmcnt(0)
	v_mfma_f32_16x16x32_bf16 v[62:65], v[130:133], v[162:165], v[62:65]
	v_mfma_f32_16x16x32_bf16 v[58:61], v[138:141], v[162:165], v[58:61]
	v_mfma_f32_16x16x32_bf16 v[46:49], v[130:133], v[182:185], v[46:49]
	v_mfma_f32_16x16x32_bf16 v[38:41], v[138:141], v[182:185], v[38:41]
	v_mfma_f32_16x16x32_bf16 v[22:25], v[130:133], v[190:193], v[22:25]
	v_mfma_f32_16x16x32_bf16 v[14:17], v[138:141], v[190:193], v[14:17]
	v_mfma_f32_16x16x32_bf16 v[6:9], v[130:133], v[202:205], v[6:9]
	v_mfma_f32_16x16x32_bf16 v[2:5], v[138:141], v[202:205], v[2:5]
	v_mfma_f32_16x16x32_bf16 v[62:65], v[134:137], v[178:181], v[62:65]
	v_mfma_f32_16x16x32_bf16 v[58:61], v[142:145], v[178:181], v[58:61]
	v_mfma_f32_16x16x32_bf16 v[46:49], v[134:137], v[186:189], v[46:49]
	v_mfma_f32_16x16x32_bf16 v[38:41], v[142:145], v[186:189], v[38:41]
	v_mfma_f32_16x16x32_bf16 v[22:25], v[134:137], v[198:201], v[22:25]
	v_mfma_f32_16x16x32_bf16 v[14:17], v[142:145], v[198:201], v[14:17]
	v_mfma_f32_16x16x32_bf16 v[6:9], v[134:137], v[206:209], v[6:9]
	v_mfma_f32_16x16x32_bf16 v[2:5], v[142:145], v[206:209], v[2:5]
	v_mfma_f32_16x16x32_bf16 v[50:53], v[146:149], v[162:165], v[50:53]
	v_mfma_f32_16x16x32_bf16 v[34:37], v[154:157], v[162:165], v[34:37]
	v_mfma_f32_16x16x32_bf16 v[18:21], v[146:149], v[182:185], v[18:21]
	v_mfma_f32_16x16x32_bf16 v[10:13], v[154:157], v[182:185], v[10:13]
	v_mfma_f32_16x16x32_bf16 v[54:57], v[146:149], v[190:193], v[54:57]
	v_mfma_f32_16x16x32_bf16 v[42:45], v[154:157], v[190:193], v[42:45]
	v_mfma_f32_16x16x32_bf16 v[30:33], v[146:149], v[202:205], v[30:33]
	v_mfma_f32_16x16x32_bf16 v[26:29], v[154:157], v[202:205], v[26:29]
	v_mfma_f32_16x16x32_bf16 v[50:53], v[150:153], v[178:181], v[50:53]
	v_mfma_f32_16x16x32_bf16 v[34:37], v[158:161], v[178:181], v[34:37]
	v_mfma_f32_16x16x32_bf16 v[18:21], v[150:153], v[186:189], v[18:21]
	v_mfma_f32_16x16x32_bf16 v[10:13], v[158:161], v[186:189], v[10:13]
	v_mfma_f32_16x16x32_bf16 v[54:57], v[150:153], v[198:201], v[54:57]
	v_mfma_f32_16x16x32_bf16 v[42:45], v[158:161], v[198:201], v[42:45]
	v_mfma_f32_16x16x32_bf16 v[30:33], v[150:153], v[206:209], v[30:33]
	v_mfma_f32_16x16x32_bf16 v[26:29], v[158:161], v[206:209], v[26:29]
	s_barrier
	s_add_i32 s50, 0, 0x18000
	v_add_u32_e32 v0, s50, v196
	s_add_i32 s51, 0, 0x1c000
	ds_read_b128 v[130:133], v0
	ds_read_b128 v[134:137], v0 offset:1024
	ds_read_b128 v[138:141], v0 offset:2048
	ds_read_b128 v[142:145], v0 offset:3072
	v_add_u32_e32 v0, s51, v196
	ds_read_b128 v[146:149], v0
	ds_read_b128 v[150:153], v0 offset:1024
	ds_read_b128 v[154:157], v0 offset:2048
	ds_read_b128 v[158:161], v0 offset:3072
	s_add_u32 s38, s38, 0x80000
	s_addc_u32 s39, s39, 0
	s_mov_b32 m0, s60
	v_lshl_add_u64 v[216:217], s[38:39], 0, v[166:167]
	ds_read_b128 v[162:165], v197 offset:32768
	ds_read_b128 v[178:181], v197 offset:33792
	ds_read_b128 v[182:185], v197 offset:34816
	ds_read_b128 v[186:189], v197 offset:35840
	ds_read_b128 v[190:193], v197 offset:36864
	ds_read_b128 v[198:201], v197 offset:37888
	ds_read_b128 v[202:205], v197 offset:38912
	ds_read_b128 v[206:209], v197 offset:39936
	global_load_lds_dwordx4 v[216:217], off
	v_lshl_add_u64 v[216:217], s[38:39], 0, v[170:171]
	s_mov_b32 m0, s61
	s_nop 0
	global_load_lds_dwordx4 v[216:217], off
	s_waitcnt vmcnt(8)
	s_waitcnt lgkmcnt(0)
	s_barrier
	s_waitcnt lgkmcnt(0)
	v_mfma_f32_16x16x32_bf16 v[126:129], v[130:133], v[162:165], v[126:129]
	v_mfma_f32_16x16x32_bf16 v[122:125], v[138:141], v[162:165], v[122:125]
	v_mfma_f32_16x16x32_bf16 v[118:121], v[130:133], v[182:185], v[118:121]
	v_mfma_f32_16x16x32_bf16 v[106:109], v[138:141], v[182:185], v[106:109]
	v_mfma_f32_16x16x32_bf16 v[98:101], v[130:133], v[190:193], v[98:101]
	v_mfma_f32_16x16x32_bf16 v[90:93], v[138:141], v[190:193], v[90:93]
	v_mfma_f32_16x16x32_bf16 v[86:89], v[130:133], v[202:205], v[86:89]
	v_mfma_f32_16x16x32_bf16 v[78:81], v[138:141], v[202:205], v[78:81]
	v_mfma_f32_16x16x32_bf16 v[126:129], v[134:137], v[178:181], v[126:129]
	v_mfma_f32_16x16x32_bf16 v[122:125], v[142:145], v[178:181], v[122:125]
	v_mfma_f32_16x16x32_bf16 v[118:121], v[134:137], v[186:189], v[118:121]
	v_mfma_f32_16x16x32_bf16 v[106:109], v[142:145], v[186:189], v[106:109]
	v_mfma_f32_16x16x32_bf16 v[98:101], v[134:137], v[198:201], v[98:101]
	v_mfma_f32_16x16x32_bf16 v[90:93], v[142:145], v[198:201], v[90:93]
	v_mfma_f32_16x16x32_bf16 v[86:89], v[134:137], v[206:209], v[86:89]
	v_mfma_f32_16x16x32_bf16 v[78:81], v[142:145], v[206:209], v[78:81]
	v_mfma_f32_16x16x32_bf16 v[114:117], v[146:149], v[162:165], v[114:117]
	v_mfma_f32_16x16x32_bf16 v[110:113], v[154:157], v[162:165], v[110:113]
	v_mfma_f32_16x16x32_bf16 v[102:105], v[146:149], v[182:185], v[102:105]
	v_mfma_f32_16x16x32_bf16 v[94:97], v[154:157], v[182:185], v[94:97]
	v_mfma_f32_16x16x32_bf16 v[82:85], v[146:149], v[190:193], v[82:85]
	v_mfma_f32_16x16x32_bf16 v[74:77], v[154:157], v[190:193], v[74:77]
	v_mfma_f32_16x16x32_bf16 v[70:73], v[146:149], v[202:205], v[70:73]
	v_mfma_f32_16x16x32_bf16 v[66:69], v[154:157], v[202:205], v[66:69]
	v_mfma_f32_16x16x32_bf16 v[114:117], v[150:153], v[178:181], v[114:117]
	v_mfma_f32_16x16x32_bf16 v[110:113], v[158:161], v[178:181], v[110:113]
	v_mfma_f32_16x16x32_bf16 v[102:105], v[150:153], v[186:189], v[102:105]
	v_mfma_f32_16x16x32_bf16 v[94:97], v[158:161], v[186:189], v[94:97]
	v_mfma_f32_16x16x32_bf16 v[82:85], v[150:153], v[198:201], v[82:85]
	v_mfma_f32_16x16x32_bf16 v[74:77], v[158:161], v[198:201], v[74:77]
	v_mfma_f32_16x16x32_bf16 v[70:73], v[150:153], v[206:209], v[70:73]
	v_mfma_f32_16x16x32_bf16 v[66:69], v[158:161], v[206:209], v[66:69]
	s_barrier
; #define PG8_STAGE(bufoff, gbase, rows) do { _Pragma("unroll") for (int _i = 0; _i < 2; ++_i) \
;         __builtin_amdgcn_global_load_lds((const unsigned*)((const char*)(gbase) + (rows)[_i]), (LAS unsigned*)(lds + (bufoff) + ldsw + _i * 8192), 16, 0, 0); } while (0)
; #define PG8_LDA(dst, b, h) do { _Pragma("unroll") for (int m = 0; m < 4; ++m) _Pragma("unroll") for (int k = 0; k < 2; ++k) dst[m][k] = *(const LAS bf16x8*)(lds + PG8_SA(b, h) + aoff + m * 2048 + k * 1024); } while (0)
; #define PG8_MMA(ai, bj, At, Bt) do { __builtin_amdgcn_s_setprio(1); _Pragma("unroll") for (int m = 0; m < 4; ++m) _Pragma("unroll") for (int n = 0; n < 2; ++n) _Pragma("unroll") for (int k = 0; k < 2; ++k) \
;         acc[ai][bj][m][n] = __builtin_amdgcn_mfma_f32_16x16x32_bf16(Bt[n][k], At[m][k], acc[ai][bj][m][n], 0, 0, 0); __builtin_amdgcn_s_setprio(0); } while (0)
; #define PG8_WAIT_V(n) asm volatile("s_waitcnt vmcnt(" #n ")" ::: "memory")
; #define PG8_WAIT_L(n) asm volatile("s_waitcnt lgkmcnt(" #n ")" ::: "memory")
; #define PG8_BAR __builtin_amdgcn_s_barrier()
; #define PG8_SCHED __builtin_amdgcn_sched_barrier(0)
; template <class Epi, class Sched>
; __device__ __forceinline__ void gemm_phase(LAS unsigned char* lds, const Sched& S, const Epi& E, const int tid) {
;     ...
;             PG8_LDA(At, 1, 1); PG8_STAGE(PG8_SB(1, 0), b3, vB); PG8_STAGE(PG8_SB(1, 1), b3 + hB, vB); PG8_STAGE(PG8_SA(1, 0), a3, vA);
;             PG8_WAIT_V(8); PG8_WAIT_L(0); PG8_BAR; PG8_MMA(1, 0, At, B0); PG8_MMA(1, 1, At, B1); PG8_BAR; PG8_SCHED;
;         }
;         if (wr == 0) PG8_BAR;
	s_add_i32 s38, s50, s49
	v_lshl_add_u64 v[194:195], v[194:195], 0, s[82:83]
	s_mov_b32 m0, s38
	ds_read_b128 v[162:165], v197 offset:49152
	ds_read_b128 v[178:181], v197 offset:50176
	ds_read_b128 v[182:185], v197 offset:51200
	ds_read_b128 v[186:189], v197 offset:52224
	ds_read_b128 v[190:193], v197 offset:53248
	ds_read_b128 v[198:201], v197 offset:54272
	ds_read_b128 v[202:205], v197 offset:55296
	ds_read_b128 v[206:209], v197 offset:56320
	global_load_lds_dwordx4 v[194:195], off
	s_add_i32 m0, s38, 0x2000
	s_add_u32 s24, s24, 0x80080
	v_lshl_add_u64 v[194:195], v[210:211], 0, s[82:83]
	s_addc_u32 s25, s25, 0
	s_add_i32 s38, s51, s49
	global_load_lds_dwordx4 v[194:195], off
	v_lshl_add_u64 v[194:195], s[24:25], 0, v[168:169]
	s_mov_b32 m0, s38
	s_nop 0
	global_load_lds_dwordx4 v[194:195], off
	v_lshl_add_u64 v[194:195], s[24:25], 0, v[172:173]
	s_add_i32 m0, s38, 0x2000
	s_nop 0
	global_load_lds_dwordx4 v[194:195], off
	v_lshl_add_u64 v[194:195], v[212:213], 0, s[82:83]
	s_mov_b32 m0, s64
	s_nop 0
	global_load_lds_dwordx4 v[194:195], off
	v_lshl_add_u64 v[194:195], v[214:215], 0, s[82:83]
	s_mov_b32 m0, s76
	s_nop 0
	global_load_lds_dwordx4 v[194:195], off
	s_waitcnt vmcnt(8)
	s_waitcnt lgkmcnt(0)
	s_barrier
	s_waitcnt lgkmcnt(0)
	v_mfma_f32_16x16x32_bf16 v[62:65], v[130:133], v[162:165], v[62:65]
	v_mfma_f32_16x16x32_bf16 v[58:61], v[138:141], v[162:165], v[58:61]
	v_mfma_f32_16x16x32_bf16 v[46:49], v[130:133], v[182:185], v[46:49]
	v_mfma_f32_16x16x32_bf16 v[38:41], v[138:141], v[182:185], v[38:41]
	v_mfma_f32_16x16x32_bf16 v[22:25], v[130:133], v[190:193], v[22:25]
	v_mfma_f32_16x16x32_bf16 v[14:17], v[138:141], v[190:193], v[14:17]
	v_mfma_f32_16x16x32_bf16 v[6:9], v[130:133], v[202:205], v[6:9]
	v_mfma_f32_16x16x32_bf16 v[2:5], v[138:141], v[202:205], v[2:5]
	v_mfma_f32_16x16x32_bf16 v[62:65], v[134:137], v[178:181], v[62:65]
	v_mfma_f32_16x16x32_bf16 v[58:61], v[142:145], v[178:181], v[58:61]
	v_mfma_f32_16x16x32_bf16 v[46:49], v[134:137], v[186:189], v[46:49]
	v_mfma_f32_16x16x32_bf16 v[38:41], v[142:145], v[186:189], v[38:41]
	v_mfma_f32_16x16x32_bf16 v[22:25], v[134:137], v[198:201], v[22:25]
	v_mfma_f32_16x16x32_bf16 v[14:17], v[142:145], v[198:201], v[14:17]
	v_mfma_f32_16x16x32_bf16 v[6:9], v[134:137], v[206:209], v[6:9]
	v_mfma_f32_16x16x32_bf16 v[2:5], v[142:145], v[206:209], v[2:5]
	v_mfma_f32_16x16x32_bf16 v[50:53], v[146:149], v[162:165], v[50:53]
	v_mfma_f32_16x16x32_bf16 v[34:37], v[154:157], v[162:165], v[34:37]
	v_mfma_f32_16x16x32_bf16 v[18:21], v[146:149], v[182:185], v[18:21]
	v_mfma_f32_16x16x32_bf16 v[10:13], v[154:157], v[182:185], v[10:13]
	v_mfma_f32_16x16x32_bf16 v[54:57], v[146:149], v[190:193], v[54:57]
	v_mfma_f32_16x16x32_bf16 v[42:45], v[154:157], v[190:193], v[42:45]
	v_mfma_f32_16x16x32_bf16 v[30:33], v[146:149], v[202:205], v[30:33]
	v_mfma_f32_16x16x32_bf16 v[26:29], v[154:157], v[202:205], v[26:29]
	v_mfma_f32_16x16x32_bf16 v[50:53], v[150:153], v[178:181], v[50:53]
	v_mfma_f32_16x16x32_bf16 v[34:37], v[158:161], v[178:181], v[34:37]
	v_mfma_f32_16x16x32_bf16 v[18:21], v[150:153], v[186:189], v[18:21]
	v_mfma_f32_16x16x32_bf16 v[10:13], v[158:161], v[186:189], v[10:13]
	v_mfma_f32_16x16x32_bf16 v[54:57], v[150:153], v[198:201], v[54:57]
	v_mfma_f32_16x16x32_bf16 v[42:45], v[158:161], v[198:201], v[42:45]
	v_mfma_f32_16x16x32_bf16 v[30:33], v[150:153], v[206:209], v[30:33]
	v_mfma_f32_16x16x32_bf16 v[26:29], v[158:161], v[206:209], v[26:29]
	s_barrier
	s_add_i32 s80, s80, 2
	s_add_u32 s4, s4, 0x100
	s_addc_u32 s5, s5, 0
	s_add_u32 s15, s15, 0x100
	s_addc_u32 s23, s23, 0
	s_cmp_gt_u32 s80, 29
	s_cbranch_scc0 .LBB0_861
	s_and_b64 vcc, exec, s[12:13]
	s_cbranch_vccz .LBB0_864
	s_barrier

; __device__ __forceinline__ void xcd_barrier(const XcdBarrier& b) {
;     asm volatile("s_waitcnt vmcnt(0)" ::: "memory");
;     __syncthreads();
;     if (threadIdx.x == 0) {
;         unsigned* bar = b.bar;
;         __builtin_amdgcn_s_waitcnt(0);
;         unsigned nloc = b.st[0], nx = b.st[1];
;         if (nloc == 0u) { xcd_barrier_complete(bar, b.x, nloc, nx); b.st[0] = nloc; b.st[1] = nx; }
.LBB0_872:
	s_mov_b64 s[4:5], s[66:67]
	s_waitcnt vmcnt(0) lgkmcnt(0)
	s_setprio 0
	s_getreg_b32 s8, hwreg(HW_REG_XCC_ID, 0, 4)
	s_waitcnt vmcnt(0)
	s_waitcnt lgkmcnt(0)
	s_barrier
	s_and_saveexec_b64 s[0:1], s[26:27]
	s_cbranch_execz .LBB0_924
	v_mov_b32_e32 v0, s96
	s_load_dwordx2 s[4:5], s[4:5], 0xc0
	s_waitcnt vmcnt(0) expcnt(0) lgkmcnt(0)
	ds_read_b32 v3, v0
	v_mov_b32_e32 v0, s97
	ds_read_b32 v2, v0
	s_and_b32 s30, s8, 15
	s_waitcnt lgkmcnt(1)
	v_cmp_ne_u32_e32 vcc, 0, v3
	s_cbranch_vccnz .LBB0_888
	s_add_u32 s8, s4, 0x1200
	s_addc_u32 s9, s5, 0
	s_add_u32 s10, s4, 0x1400
	s_addc_u32 s11, s5, 0
	s_add_u32 s12, s4, 0x1500
	s_addc_u32 s13, s5, 0
	s_add_u32 s14, s4, 0x1600
	s_addc_u32 s15, s5, 0
	s_add_u32 s16, s4, 0x1700
	s_addc_u32 s17, s5, 0
	s_add_u32 s18, s4, 0x1800
	s_addc_u32 s19, s5, 0
	s_add_u32 s20, s4, 0x1900
	s_addc_u32 s21, s5, 0
	s_add_u32 s22, s4, 0x1a00
	s_addc_u32 s23, s5, 0
	s_add_u32 s24, s4, 0x1b00
	s_addc_u32 s25, s5, 0
	s_add_u32 s38, s4, 0x1c00
	s_addc_u32 s39, s5, 0
	s_add_u32 s48, s4, 0x1d00
	s_addc_u32 s49, s5, 0
	s_add_u32 s52, s4, 0x1e00
	s_addc_u32 s53, s5, 0
	s_add_u32 s60, s4, 0x1f00
	s_addc_u32 s61, s5, 0
	s_add_u32 s76, s4, 0x2000
	s_addc_u32 s77, s5, 0
	s_add_u32 s78, s4, 0x2100
	s_addc_u32 s79, s5, 0
	s_add_u32 s80, s4, 0x2200
	s_addc_u32 s81, s5, 0
	s_add_u32 s84, s4, 0x2300
	s_addc_u32 s85, s5, 0
	s_mov_b32 s35, 1
	s_branch .LBB0_876

; __device__ __forceinline__ void xcd_barrier(const XcdBarrier& b) {
;     asm volatile("s_waitcnt vmcnt(0)" ::: "memory");
;     __syncthreads();
;     if (threadIdx.x == 0) {
;         unsigned* bar = b.bar;
;         __builtin_amdgcn_s_waitcnt(0);
;         unsigned nloc = b.st[0], nx = b.st[1];
;         if (nloc == 0u) { xcd_barrier_complete(bar, b.x, nloc, nx); b.st[0] = nloc; b.st[1] = nx; }
.LBB0_927:
	s_mov_b64 s[4:5], s[66:67]
	s_waitcnt vmcnt(0) lgkmcnt(0)
	s_setprio 0
	s_getreg_b32 s8, hwreg(HW_REG_XCC_ID, 0, 4)
	s_waitcnt vmcnt(0)
	s_barrier
	s_and_saveexec_b64 s[0:1], s[26:27]
	s_cbranch_execz .LBB0_979
	v_mov_b32_e32 v0, s96
	s_load_dwordx2 s[4:5], s[4:5], 0xc0
	s_waitcnt vmcnt(0) expcnt(0) lgkmcnt(0)
	ds_read_b32 v3, v0
	v_mov_b32_e32 v0, s97
	ds_read_b32 v2, v0
	s_and_b32 s30, s8, 15
	s_waitcnt lgkmcnt(1)
	v_cmp_ne_u32_e32 vcc, 0, v3
	s_cbranch_vccnz .LBB0_943
	s_add_u32 s8, s4, 0x1200
	s_addc_u32 s9, s5, 0
	s_add_u32 s10, s4, 0x1400
	s_addc_u32 s11, s5, 0
	s_add_u32 s12, s4, 0x1500
	s_addc_u32 s13, s5, 0
	s_add_u32 s14, s4, 0x1600
	s_addc_u32 s15, s5, 0
	s_add_u32 s16, s4, 0x1700
	s_addc_u32 s17, s5, 0
	s_add_u32 s18, s4, 0x1800
	s_addc_u32 s19, s5, 0
	s_add_u32 s20, s4, 0x1900
	s_addc_u32 s21, s5, 0
	s_add_u32 s22, s4, 0x1a00
	s_addc_u32 s23, s5, 0
	s_add_u32 s24, s4, 0x1b00
	s_addc_u32 s25, s5, 0
	s_add_u32 s38, s4, 0x1c00
	s_addc_u32 s39, s5, 0
	s_add_u32 s48, s4, 0x1d00
	s_addc_u32 s49, s5, 0
	s_add_u32 s52, s4, 0x1e00
	s_addc_u32 s53, s5, 0
	s_add_u32 s60, s4, 0x1f00
	s_addc_u32 s61, s5, 0
	s_add_u32 s76, s4, 0x2000
	s_addc_u32 s77, s5, 0
	s_add_u32 s78, s4, 0x2100
	s_addc_u32 s79, s5, 0
	s_add_u32 s80, s4, 0x2200
	s_addc_u32 s81, s5, 0
	s_add_u32 s84, s4, 0x2300
	s_addc_u32 s85, s5, 0
	s_mov_b32 s35, 1
	s_branch .LBB0_931

; __device__ __forceinline__ ParamsCP get_params() { ParamsCP q = (ParamsCP)__builtin_amdgcn_kernarg_segment_ptr(); asm volatile("" : "+s"(q)); return q; }
; #define PG8_BAR __builtin_amdgcn_s_barrier()
; template <class Epi, class Sched>
; __device__ __forceinline__ void gemm_phase(LAS unsigned char* lds, const Sched& S, const Epi& E, const int tid) {
;     const int wid = __builtin_amdgcn_readfirstlane(tid >> 6), lane = tid & 63, wr = wid >> 2, wc = wid & 3, fr = lane & 15, fq = lane >> 4;
;     int sR[2], sC[2], sRbi[2];
; #pragma unroll
;     for (int i = 0; i < 2; ++i) { stage_rc(tid * 16 + i * 8192, sR[i], sC[i]); sRbi[i] = (sR[i] & ~31) + perm32(sR[i] & 31); }
;     const unsigned ldsw = (unsigned)wid * 1024u;
;     const int aoff = lds_byte(wr * 64 + fr, fq * 8), boff = lds_byte(wc * 32 + fr, fq * 8);
;     ...
;     GUnit cur, nxt; int ui = 0;
;     if (!S.next(0, cur)) return;
;     f32x4 acc[2][2][4][2];
; #pragma unroll
;     for (int a = 0; a < 2; ++a)
; #pragma unroll
;         for (int b = 0; b < 2; ++b)
; #pragma unroll
;             for (int m = 0; m < 4; ++m)
; #pragma unroll
;                 for (int n = 0; n < 2; ++n) acc[a][b][m][n] = (f32x4){0.f, 0.f, 0.f, 0.f};
;     bf16x8 At[4][2], B0[2][2], B1[2][2];
;     const char* cA = cur.A; const char* cB = cur.B;
;     constexpr unsigned kstep = (unsigned)(BK * 2);
;     const unsigned lda = cur.lda, ldb = cur.ldb, hA = HALF * lda, hB = HALF * ldb;
;     unsigned vA[2], vB[2];
; #pragma unroll
;     for (int i = 0; i < 2; ++i) { vA[i] = (unsigned)sR[i] * lda + (unsigned)sC[i] * 2u; vB[i] = (unsigned)sRbi[i] * ldb + (unsigned)sC[i] * 2u; }
;     PG8_STAGE(PG8_SB(0, 0), cB, vB); PG8_STAGE(PG8_SB(0, 1), cB + hB, vB); PG8_STAGE(PG8_SA(0, 0), cA, vA); PG8_STAGE(PG8_SA(0, 1), cA + hA, vA);
;     if (wr == 1) PG8_BAR;
; __global__ void __launch_bounds__(512) fwd_kernel(Params p_unused) {
;     ...
;         { FRESH_IDS(); ParamsCP pp = get_params(); unsigned char* ws = pp->ws;
;           SchedPlain S{(const char*)(ws + WS_U), (const char*)(ws + WS_WT + WT_UP), 4096u, 4096u, 32, 129, 43, 0, G, blk};
;           EpiUp E{(bf16_t*)(ws + WS_BIG + BIG_G), (bf16_t*)(ws + WS_BIG + BIG_V)}; pg8::gemm_phase(lds, S, E, tid); }
.LBB0_979:
	s_or_b64 exec, exec, s[0:1]
	s_waitcnt lgkmcnt(0)
	s_barrier
	v_readlane_b32 s4, v254, 13
	v_mov_b32_e32 v15, v222
	v_readlane_b32 s5, v254, 14
	s_mov_b64 s[0:1], s[66:67]
	s_andn2_b64 vcc, exec, s[4:5]
	v_readfirstlane_b32 s10, v15
	s_cbranch_vccnz .LBB0_999
	v_lshlrev_b32_e32 v2, 4, v15
	v_add_u32_e32 v3, 0x2000, v2
	v_ashrrev_i32_e32 v0, 31, v3
	v_lshrrev_b32_e32 v0, 22, v0
	v_add_u32_e32 v0, v3, v0
	v_ashrrev_i32_e32 v0, 10, v0
	v_mul_i32_i24_e32 v4, 0x400, v0
	v_sub_u32_e32 v3, v3, v4
	v_lshrrev_b32_e32 v4, 4, v3
	v_bitop3_b32 v3, v4, v3, 32 bitop3:0x6c
	v_ashrrev_i32_e32 v4, 31, v3
	v_lshrrev_b32_e32 v4, 26, v4
	v_add_u32_e32 v4, v3, v4
	v_ashrrev_i32_e32 v10, 6, v4
	v_and_b32_e32 v4, 0xc0, v4
	v_lshlrev_b32_e32 v5, 3, v0
	v_sub_u32_e32 v3, v3, v4
	v_bfe_i32 v4, v15, 27, 1
	v_and_b32_e32 v5, -16, v5
	v_lshrrev_b32_e32 v4, 22, v4
	v_add_u32_e32 v5, v10, v5
	v_add_u32_e32 v4, v2, v4
	s_load_dwordx2 s[8:9], s[0:1], 0xc0
	v_and_b32_e32 v6, 3, v10
	v_lshrrev_b32_e32 v7, 2, v5
	v_lshlrev_b32_e32 v8, 1, v5
	v_and_b32_e32 v4, 0xfffffc00, v4
	v_and_or_b32 v6, v5, s55, v6
	v_and_b32_e32 v7, 4, v7
	v_and_b32_e32 v8, 24, v8
	v_sub_u32_e32 v2, v2, v4
	v_or3_b32 v6, v6, v7, v8
	v_lshrrev_b32_e32 v4, 4, v2
	v_ashrrev_i32_e32 v7, 31, v15
	v_bitop3_b32 v2, v4, v2, 32 bitop3:0x6c
	v_lshrrev_b32_e32 v7, 26, v7
	v_ashrrev_i32_e32 v4, 31, v2
	v_add_u32_e32 v7, v15, v7
	s_waitcnt lgkmcnt(0)
	s_add_u32 s24, s8, 0xa480000
	v_lshrrev_b32_e32 v4, 26, v4
	v_ashrrev_i32_e32 v13, 6, v7
	s_addc_u32 s25, s9, 0
	v_add_u32_e32 v4, v2, v4
	v_lshlrev_b32_e32 v7, 3, v13
	s_add_u32 s30, s8, 0x6400000
	v_ashrrev_i32_e32 v12, 6, v4
	v_and_b32_e32 v7, -16, v7
	s_addc_u32 s35, s9, 0
	s_ashr_i32 s11, s10, 6
	v_add_u32_e32 v7, v12, v7
	v_and_b32_e32 v4, 0xc0, v4
	s_ashr_i32 s12, s10, 8
	s_lshl_b32 s37, s11, 10
	v_and_b32_e32 v8, 3, v12
	v_lshrrev_b32_e32 v9, 2, v7
	v_lshlrev_b32_e32 v14, 1, v7
	v_sub_u32_e32 v2, v2, v4
	v_readlane_b32 s0, v254, 52
	v_and_or_b32 v8, v7, s55, v8
	v_and_b32_e32 v9, 4, v9
	v_and_b32_e32 v14, 24, v14
	v_ashrrev_i16_sdwa v2, v231, sext(v2) dst_sel:DWORD dst_unused:UNUSED_PAD src0_sel:DWORD src1_sel:BYTE_0
	v_readlane_b32 s1, v254, 53
	s_add_u32 s4, s24, s0
	v_or3_b32 v8, v8, v9, v14
	v_bfe_i32 v14, v2, 0, 16
	v_lshlrev_b32_e32 v2, 5, v13
	s_addc_u32 s5, s25, s1
	v_readlane_b32 s0, v254, 43
	v_ashrrev_i16_sdwa v3, v231, sext(v3) dst_sel:DWORD dst_unused:UNUSED_PAD src0_sel:DWORD src1_sel:BYTE_0
	v_and_b32_e32 v2, 32, v2
	v_readlane_b32 s1, v254, 44
	s_add_u32 s20, s30, s0
	v_bfe_i32 v11, v3, 0, 16
	v_lshlrev_b32_e32 v3, 5, v0
	s_addc_u32 s21, s35, s1
	v_add_lshl_u32 v2, v2, v14, 1
	s_add_i32 s38, s37, 0
	v_and_b32_e32 v3, 32, v3
	v_lshl_add_u32 v132, v8, 12, v2
	s_add_i32 m0, s38, 0x10000
	v_lshl_add_u32 v130, v7, 12, v2
	v_add_lshl_u32 v2, v3, v11, 1
	global_load_lds_dwordx4 v132, s[20:21]
	s_add_i32 m0, s38, 0x12000
	v_lshl_add_u32 v136, v6, 12, v2
	s_add_u32 s0, s20, 0x80000
	global_load_lds_dwordx4 v136, s[20:21]
	s_addc_u32 s1, s21, 0
	s_add_i32 m0, s38, 0x14000
	s_add_i32 s39, s38, 0x2000
	global_load_lds_dwordx4 v132, s[0:1]
	s_add_i32 m0, s38, 0x16000
	v_lshl_add_u32 v134, v5, 12, v2
	global_load_lds_dwordx4 v136, s[0:1]
	s_mov_b32 m0, s38
	s_add_u32 s0, s4, 0x80000
	global_load_lds_dwordx4 v130, s[4:5]
	s_mov_b32 m0, s39
	s_addc_u32 s1, s5, 0
	s_add_i32 s40, s38, 0x4000
	global_load_lds_dwordx4 v134, s[4:5]
	s_mov_b32 m0, s40
	s_add_i32 s41, s38, 0x6000
	global_load_lds_dwordx4 v130, s[0:1]
	s_mov_b32 m0, s41
	v_mov_b32_e32 v133, v1
	global_load_lds_dwordx4 v134, s[0:1]
	v_mov_b32_e32 v137, v1
	v_mov_b32_e32 v131, v1
	v_mov_b32_e32 v135, v1
	s_cmp_eq_u32 s12, 1
	v_lshl_add_u64 v[8:9], s[20:21], 0, v[132:133]
	v_lshl_add_u64 v[6:7], s[20:21], 0, v[136:137]
	v_lshl_add_u64 v[2:3], s[4:5], 0, v[130:131]
	s_cselect_b64 s[0:1], -1, 0
	s_cmp_lg_u32 s12, 1
	v_lshl_add_u64 v[4:5], s[4:5], 0, v[134:135]
	s_cbranch_scc1 .LBB0_982
	s_setprio 1
	s_barrier

; #define PG8_STAGE(bufoff, gbase, rows) do { _Pragma("unroll") for (int _i = 0; _i < 2; ++_i) \
;         __builtin_amdgcn_global_load_lds((const unsigned*)((const char*)(gbase) + (rows)[_i]), (LAS unsigned*)(lds + (bufoff) + ldsw + _i * 8192), 16, 0, 0); } while (0)
; #define PG8_LDA(dst, b, h) do { _Pragma("unroll") for (int m = 0; m < 4; ++m) _Pragma("unroll") for (int k = 0; k < 2; ++k) dst[m][k] = *(const LAS bf16x8*)(lds + PG8_SA(b, h) + aoff + m * 2048 + k * 1024); } while (0)
; #define PG8_LDB(dst, b, h) do { _Pragma("unroll") for (int n = 0; n < 2; ++n) _Pragma("unroll") for (int k = 0; k < 2; ++k) dst[n][k] = *(const LAS bf16x8*)(lds + PG8_SB(b, h) + boff + n * 2048 + k * 1024); } while (0)
; #define PG8_MMA(ai, bj, At, Bt) do { __builtin_amdgcn_s_setprio(1); _Pragma("unroll") for (int m = 0; m < 4; ++m) _Pragma("unroll") for (int n = 0; n < 2; ++n) _Pragma("unroll") for (int k = 0; k < 2; ++k) \
;         acc[ai][bj][m][n] = __builtin_amdgcn_mfma_f32_16x16x32_bf16(Bt[n][k], At[m][k], acc[ai][bj][m][n], 0, 0, 0); __builtin_amdgcn_s_setprio(0); } while (0)
; #define PG8_WAIT_V(n) asm volatile("s_waitcnt vmcnt(" #n ")" ::: "memory")
; #define PG8_WAIT_L(n) asm volatile("s_waitcnt lgkmcnt(" #n ")" ::: "memory")
; #define PG8_BAR __builtin_amdgcn_s_barrier()
; #define PG8_SCHED __builtin_amdgcn_sched_barrier(0)
; template <class Epi, class Sched>
; __device__ __forceinline__ void gemm_phase(LAS unsigned char* lds, const Sched& S, const Epi& E, const int tid) {
;     ...
;         for (int t = 0; t < nt; t += 2) {
;             const bool last = (t == nt - 2);
;             const char* a1 = cA + (size_t)(t + 1) * kstep;
;             const char* a2 = last ? nA : cA + (size_t)(t + 2) * kstep; const char* b2 = last ? nB : cB + (size_t)(t + 2) * kstep;
;             const char* a3 = a2 + kstep; const char* b3 = b2 + kstep;
;             PG8_LDB(B0, 0, 0); PG8_LDB(B1, 0, 1); PG8_SCHED; PG8_LDA(At, 0, 0); PG8_STAGE(PG8_SA(1, 1), a1 + hA, vA);
;             PG8_WAIT_V(8); PG8_WAIT_L(0); PG8_BAR; PG8_MMA(0, 0, At, B0); PG8_MMA(0, 1, At, B1); PG8_BAR; PG8_SCHED;
;             PG8_LDA(At, 0, 1); PG8_STAGE(PG8_SB(0, 0), b2, vB); PG8_STAGE(PG8_SB(0, 1), b2 + hB, vB); PG8_STAGE(PG8_SA(0, 0), a2, vA);
;             PG8_WAIT_V(8); PG8_WAIT_L(0); PG8_BAR; PG8_MMA(1, 0, At, B0); PG8_MMA(1, 1, At, B1); PG8_BAR; PG8_SCHED;
.LBB0_992:
	s_add_u32 s20, s4, 0xfff80080
	s_addc_u32 s21, s5, -1
	s_add_i32 s50, 0, 0x10000
	s_cmp_eq_u32 s78, 28
	s_cselect_b32 s23, s15, s21
	s_cselect_b32 s22, s14, s20
	v_add_u32_e32 v0, s50, v142
	s_cselect_b32 s21, s17, s77
	s_cselect_b32 s20, s16, s13
	s_add_i32 s51, 0, 0x14000
	ds_read_b128 v[144:147], v0
	ds_read_b128 v[148:151], v0 offset:1024
	ds_read_b128 v[152:155], v0 offset:2048
	ds_read_b128 v[156:159], v0 offset:3072
	v_add_u32_e32 v0, s51, v142
	ds_read_b128 v[160:163], v0
	ds_read_b128 v[164:167], v0 offset:1024
	ds_read_b128 v[168:171], v0 offset:2048
	ds_read_b128 v[172:175], v0 offset:3072
	v_lshl_add_u64 v[208:209], s[4:5], 0, v[138:139]
	s_add_i32 m0, s38, 0xc000
	ds_read_b128 v[176:179], v143
	ds_read_b128 v[180:183], v143 offset:1024
	ds_read_b128 v[184:187], v143 offset:2048
	ds_read_b128 v[188:191], v143 offset:3072
	ds_read_b128 v[192:195], v143 offset:4096
	ds_read_b128 v[196:199], v143 offset:5120
	ds_read_b128 v[200:203], v143 offset:6144
	ds_read_b128 v[204:207], v143 offset:7168
	global_load_lds_dwordx4 v[208:209], off
	v_lshl_add_u64 v[208:209], s[4:5], 0, v[140:141]
	s_add_i32 m0, s38, 0xe000
	s_nop 0
	global_load_lds_dwordx4 v[208:209], off
	s_waitcnt vmcnt(8)
	s_waitcnt lgkmcnt(0)
	s_barrier
	s_waitcnt lgkmcnt(0)
	v_mfma_f32_16x16x32_bf16 v[126:129], v[144:147], v[176:179], v[126:129]
	v_mfma_f32_16x16x32_bf16 v[122:125], v[152:155], v[176:179], v[122:125]
	v_mfma_f32_16x16x32_bf16 v[118:121], v[144:147], v[184:187], v[118:121]
	v_mfma_f32_16x16x32_bf16 v[114:117], v[152:155], v[184:187], v[114:117]
	v_mfma_f32_16x16x32_bf16 v[102:105], v[144:147], v[192:195], v[102:105]
	v_mfma_f32_16x16x32_bf16 v[98:101], v[152:155], v[192:195], v[98:101]
	v_mfma_f32_16x16x32_bf16 v[86:89], v[144:147], v[200:203], v[86:89]
	v_mfma_f32_16x16x32_bf16 v[82:85], v[152:155], v[200:203], v[82:85]
	v_mfma_f32_16x16x32_bf16 v[126:129], v[148:151], v[180:183], v[126:129]
	v_mfma_f32_16x16x32_bf16 v[122:125], v[156:159], v[180:183], v[122:125]
	v_mfma_f32_16x16x32_bf16 v[118:121], v[148:151], v[188:191], v[118:121]
	v_mfma_f32_16x16x32_bf16 v[114:117], v[156:159], v[188:191], v[114:117]
	v_mfma_f32_16x16x32_bf16 v[102:105], v[148:151], v[196:199], v[102:105]
	v_mfma_f32_16x16x32_bf16 v[98:101], v[156:159], v[196:199], v[98:101]
	v_mfma_f32_16x16x32_bf16 v[86:89], v[148:151], v[204:207], v[86:89]
	v_mfma_f32_16x16x32_bf16 v[82:85], v[156:159], v[204:207], v[82:85]
	v_mfma_f32_16x16x32_bf16 v[110:113], v[160:163], v[176:179], v[110:113]
	v_mfma_f32_16x16x32_bf16 v[106:109], v[168:171], v[176:179], v[106:109]
	v_mfma_f32_16x16x32_bf16 v[94:97], v[160:163], v[184:187], v[94:97]
	v_mfma_f32_16x16x32_bf16 v[90:93], v[168:171], v[184:187], v[90:93]
	v_mfma_f32_16x16x32_bf16 v[78:81], v[160:163], v[192:195], v[78:81]
	v_mfma_f32_16x16x32_bf16 v[74:77], v[168:171], v[192:195], v[74:77]
	v_mfma_f32_16x16x32_bf16 v[70:73], v[160:163], v[200:203], v[70:73]
	v_mfma_f32_16x16x32_bf16 v[66:69], v[168:171], v[200:203], v[66:69]
	v_mfma_f32_16x16x32_bf16 v[110:113], v[164:167], v[180:183], v[110:113]
	v_mfma_f32_16x16x32_bf16 v[106:109], v[172:175], v[180:183], v[106:109]
	v_mfma_f32_16x16x32_bf16 v[94:97], v[164:167], v[188:191], v[94:97]
	v_mfma_f32_16x16x32_bf16 v[90:93], v[172:175], v[188:191], v[90:93]
	v_mfma_f32_16x16x32_bf16 v[78:81], v[164:167], v[196:199], v[78:81]
	v_mfma_f32_16x16x32_bf16 v[74:77], v[172:175], v[196:199], v[74:77]
	v_mfma_f32_16x16x32_bf16 v[70:73], v[164:167], v[204:207], v[70:73]
	v_mfma_f32_16x16x32_bf16 v[66:69], v[172:175], v[204:207], v[66:69]
	s_barrier
	s_add_i32 s50, s50, s37
	v_lshl_add_u64 v[208:209], s[20:21], 0, v[132:133]
	s_mov_b32 m0, s50
	ds_read_b128 v[176:179], v143 offset:16384
	ds_read_b128 v[180:183], v143 offset:17408
	ds_read_b128 v[184:187], v143 offset:18432
	ds_read_b128 v[188:191], v143 offset:19456
	ds_read_b128 v[192:195], v143 offset:20480
	ds_read_b128 v[196:199], v143 offset:21504
	ds_read_b128 v[200:203], v143 offset:22528
	ds_read_b128 v[204:207], v143 offset:23552
	global_load_lds_dwordx4 v[208:209], off
	s_add_i32 m0, s50, 0x2000
	s_add_u32 s80, s20, 0x80000
	v_lshl_add_u64 v[210:211], s[20:21], 0, v[136:137]
	s_addc_u32 s81, s21, 0
	s_add_i32 s50, s51, s37
	global_load_lds_dwordx4 v[210:211], off
	v_lshl_add_u64 v[212:213], s[80:81], 0, v[132:133]
	s_mov_b32 m0, s50
	v_lshl_add_u64 v[214:215], s[22:23], 0, v[134:135]
	global_load_lds_dwordx4 v[212:213], off
	v_lshl_add_u64 v[212:213], s[80:81], 0, v[136:137]
	s_add_i32 m0, s50, 0x2000
	s_nop 0
	global_load_lds_dwordx4 v[212:213], off
	v_lshl_add_u64 v[212:213], s[22:23], 0, v[130:131]
	s_mov_b32 m0, s38
	s_nop 0
	global_load_lds_dwordx4 v[212:213], off
	s_mov_b32 m0, s39
	s_nop 0
	global_load_lds_dwordx4 v[214:215], off
	s_waitcnt vmcnt(8)
	s_waitcnt lgkmcnt(0)
	s_barrier
; #define PG8_STAGE(bufoff, gbase, rows) do { _Pragma("unroll") for (int _i = 0; _i < 2; ++_i) \
;         __builtin_amdgcn_global_load_lds((const unsigned*)((const char*)(gbase) + (rows)[_i]), (LAS unsigned*)(lds + (bufoff) + ldsw + _i * 8192), 16, 0, 0); } while (0)
; #define PG8_LDA(dst, b, h) do { _Pragma("unroll") for (int m = 0; m < 4; ++m) _Pragma("unroll") for (int k = 0; k < 2; ++k) dst[m][k] = *(const LAS bf16x8*)(lds + PG8_SA(b, h) + aoff + m * 2048 + k * 1024); } while (0)
; #define PG8_LDB(dst, b, h) do { _Pragma("unroll") for (int n = 0; n < 2; ++n) _Pragma("unroll") for (int k = 0; k < 2; ++k) dst[n][k] = *(const LAS bf16x8*)(lds + PG8_SB(b, h) + boff + n * 2048 + k * 1024); } while (0)
; #define PG8_MMA(ai, bj, At, Bt) do { __builtin_amdgcn_s_setprio(1); _Pragma("unroll") for (int m = 0; m < 4; ++m) _Pragma("unroll") for (int n = 0; n < 2; ++n) _Pragma("unroll") for (int k = 0; k < 2; ++k) \
;         acc[ai][bj][m][n] = __builtin_amdgcn_mfma_f32_16x16x32_bf16(Bt[n][k], At[m][k], acc[ai][bj][m][n], 0, 0, 0); __builtin_amdgcn_s_setprio(0); } while (0)
; #define PG8_WAIT_V(n) asm volatile("s_waitcnt vmcnt(" #n ")" ::: "memory")
; #define PG8_WAIT_L(n) asm volatile("s_waitcnt lgkmcnt(" #n ")" ::: "memory")
; #define PG8_BAR __builtin_amdgcn_s_barrier()
; #define PG8_SCHED __builtin_amdgcn_sched_barrier(0)
; template <class Epi, class Sched>
; __device__ __forceinline__ void gemm_phase(LAS unsigned char* lds, const Sched& S, const Epi& E, const int tid) {
;     ...
;             PG8_WAIT_V(8); PG8_WAIT_L(0); PG8_BAR; PG8_MMA(1, 0, At, B0); PG8_MMA(1, 1, At, B1); PG8_BAR; PG8_SCHED;
;             PG8_LDB(B0, 1, 0); PG8_LDB(B1, 1, 1); PG8_SCHED; PG8_LDA(At, 1, 0); PG8_STAGE(PG8_SA(0, 1), a2 + hA, vA);
;             PG8_WAIT_V(8); PG8_WAIT_L(0); PG8_BAR; PG8_MMA(0, 0, At, B0); PG8_MMA(0, 1, At, B1); PG8_BAR; PG8_SCHED;
	s_waitcnt lgkmcnt(0)
	v_mfma_f32_16x16x32_bf16 v[54:57], v[144:147], v[176:179], v[54:57]
	v_mfma_f32_16x16x32_bf16 v[42:45], v[152:155], v[176:179], v[42:45]
	v_mfma_f32_16x16x32_bf16 v[38:41], v[144:147], v[184:187], v[38:41]
	v_mfma_f32_16x16x32_bf16 v[34:37], v[152:155], v[184:187], v[34:37]
	v_mfma_f32_16x16x32_bf16 v[22:25], v[144:147], v[192:195], v[22:25]
	v_mfma_f32_16x16x32_bf16 v[18:21], v[152:155], v[192:195], v[18:21]
	v_mfma_f32_16x16x32_bf16 v[6:9], v[144:147], v[200:203], v[6:9]
	v_mfma_f32_16x16x32_bf16 v[2:5], v[152:155], v[200:203], v[2:5]
	v_mfma_f32_16x16x32_bf16 v[54:57], v[148:151], v[180:183], v[54:57]
	v_mfma_f32_16x16x32_bf16 v[42:45], v[156:159], v[180:183], v[42:45]
	v_mfma_f32_16x16x32_bf16 v[38:41], v[148:151], v[188:191], v[38:41]
	v_mfma_f32_16x16x32_bf16 v[34:37], v[156:159], v[188:191], v[34:37]
	v_mfma_f32_16x16x32_bf16 v[22:25], v[148:151], v[196:199], v[22:25]
	v_mfma_f32_16x16x32_bf16 v[18:21], v[156:159], v[196:199], v[18:21]
	v_mfma_f32_16x16x32_bf16 v[6:9], v[148:151], v[204:207], v[6:9]
	v_mfma_f32_16x16x32_bf16 v[2:5], v[156:159], v[204:207], v[2:5]
	v_mfma_f32_16x16x32_bf16 v[30:33], v[160:163], v[176:179], v[30:33]
	v_mfma_f32_16x16x32_bf16 v[26:29], v[168:171], v[176:179], v[26:29]
	v_mfma_f32_16x16x32_bf16 v[14:17], v[160:163], v[184:187], v[14:17]
	v_mfma_f32_16x16x32_bf16 v[10:13], v[168:171], v[184:187], v[10:13]
	v_mfma_f32_16x16x32_bf16 v[58:61], v[160:163], v[192:195], v[58:61]
	v_mfma_f32_16x16x32_bf16 v[62:65], v[168:171], v[192:195], v[62:65]
	v_mfma_f32_16x16x32_bf16 v[46:49], v[160:163], v[200:203], v[46:49]
	v_mfma_f32_16x16x32_bf16 v[50:53], v[168:171], v[200:203], v[50:53]
	v_mfma_f32_16x16x32_bf16 v[30:33], v[164:167], v[180:183], v[30:33]
	v_mfma_f32_16x16x32_bf16 v[26:29], v[172:175], v[180:183], v[26:29]
	v_mfma_f32_16x16x32_bf16 v[14:17], v[164:167], v[188:191], v[14:17]
	v_mfma_f32_16x16x32_bf16 v[10:13], v[172:175], v[188:191], v[10:13]
	v_mfma_f32_16x16x32_bf16 v[58:61], v[164:167], v[196:199], v[58:61]
	v_mfma_f32_16x16x32_bf16 v[62:65], v[172:175], v[196:199], v[62:65]
	v_mfma_f32_16x16x32_bf16 v[46:49], v[164:167], v[204:207], v[46:49]
	v_mfma_f32_16x16x32_bf16 v[50:53], v[172:175], v[204:207], v[50:53]
	s_barrier
	s_add_i32 s50, 0, 0x18000
	v_add_u32_e32 v0, s50, v142
	s_add_i32 s51, 0, 0x1c000
	ds_read_b128 v[144:147], v0
	ds_read_b128 v[148:151], v0 offset:1024
	ds_read_b128 v[152:155], v0 offset:2048
	ds_read_b128 v[156:159], v0 offset:3072
	v_add_u32_e32 v0, s51, v142
	ds_read_b128 v[160:163], v0
	ds_read_b128 v[164:167], v0 offset:1024
	ds_read_b128 v[168:171], v0 offset:2048
	ds_read_b128 v[172:175], v0 offset:3072
	s_add_u32 s22, s22, 0x80000
	s_addc_u32 s23, s23, 0
	s_mov_b32 m0, s40
	v_lshl_add_u64 v[216:217], s[22:23], 0, v[130:131]
	ds_read_b128 v[176:179], v143 offset:32768
	ds_read_b128 v[180:183], v143 offset:33792
	ds_read_b128 v[184:187], v143 offset:34816
	ds_read_b128 v[188:191], v143 offset:35840
	ds_read_b128 v[192:195], v143 offset:36864
	ds_read_b128 v[196:199], v143 offset:37888
	ds_read_b128 v[200:203], v143 offset:38912
	ds_read_b128 v[204:207], v143 offset:39936
	global_load_lds_dwordx4 v[216:217], off
	v_lshl_add_u64 v[216:217], s[22:23], 0, v[134:135]
	s_mov_b32 m0, s41
	s_nop 0
	global_load_lds_dwordx4 v[216:217], off
	s_waitcnt vmcnt(8)
	s_waitcnt lgkmcnt(0)
	s_barrier
	s_waitcnt lgkmcnt(0)
	v_mfma_f32_16x16x32_bf16 v[126:129], v[144:147], v[176:179], v[126:129]
	v_mfma_f32_16x16x32_bf16 v[122:125], v[152:155], v[176:179], v[122:125]
	v_mfma_f32_16x16x32_bf16 v[118:121], v[144:147], v[184:187], v[118:121]
	v_mfma_f32_16x16x32_bf16 v[114:117], v[152:155], v[184:187], v[114:117]
	v_mfma_f32_16x16x32_bf16 v[102:105], v[144:147], v[192:195], v[102:105]
	v_mfma_f32_16x16x32_bf16 v[98:101], v[152:155], v[192:195], v[98:101]
	v_mfma_f32_16x16x32_bf16 v[86:89], v[144:147], v[200:203], v[86:89]
	v_mfma_f32_16x16x32_bf16 v[82:85], v[152:155], v[200:203], v[82:85]
	v_mfma_f32_16x16x32_bf16 v[126:129], v[148:151], v[180:183], v[126:129]
	v_mfma_f32_16x16x32_bf16 v[122:125], v[156:159], v[180:183], v[122:125]
	v_mfma_f32_16x16x32_bf16 v[118:121], v[148:151], v[188:191], v[118:121]
	v_mfma_f32_16x16x32_bf16 v[114:117], v[156:159], v[188:191], v[114:117]
	v_mfma_f32_16x16x32_bf16 v[102:105], v[148:151], v[196:199], v[102:105]
	v_mfma_f32_16x16x32_bf16 v[98:101], v[156:159], v[196:199], v[98:101]
	v_mfma_f32_16x16x32_bf16 v[86:89], v[148:151], v[204:207], v[86:89]
	v_mfma_f32_16x16x32_bf16 v[82:85], v[156:159], v[204:207], v[82:85]
	v_mfma_f32_16x16x32_bf16 v[110:113], v[160:163], v[176:179], v[110:113]
	v_mfma_f32_16x16x32_bf16 v[106:109], v[168:171], v[176:179], v[106:109]
	v_mfma_f32_16x16x32_bf16 v[94:97], v[160:163], v[184:187], v[94:97]
	v_mfma_f32_16x16x32_bf16 v[90:93], v[168:171], v[184:187], v[90:93]
	v_mfma_f32_16x16x32_bf16 v[78:81], v[160:163], v[192:195], v[78:81]
	v_mfma_f32_16x16x32_bf16 v[74:77], v[168:171], v[192:195], v[74:77]
	v_mfma_f32_16x16x32_bf16 v[70:73], v[160:163], v[200:203], v[70:73]
	v_mfma_f32_16x16x32_bf16 v[66:69], v[168:171], v[200:203], v[66:69]
	v_mfma_f32_16x16x32_bf16 v[110:113], v[164:167], v[180:183], v[110:113]
	v_mfma_f32_16x16x32_bf16 v[106:109], v[172:175], v[180:183], v[106:109]
	v_mfma_f32_16x16x32_bf16 v[94:97], v[164:167], v[188:191], v[94:97]
	v_mfma_f32_16x16x32_bf16 v[90:93], v[172:175], v[188:191], v[90:93]
	v_mfma_f32_16x16x32_bf16 v[78:81], v[164:167], v[196:199], v[78:81]
	v_mfma_f32_16x16x32_bf16 v[74:77], v[172:175], v[196:199], v[74:77]
	v_mfma_f32_16x16x32_bf16 v[70:73], v[164:167], v[204:207], v[70:73]
	v_mfma_f32_16x16x32_bf16 v[66:69], v[172:175], v[204:207], v[66:69]
	s_barrier
; #define PG8_STAGE(bufoff, gbase, rows) do { _Pragma("unroll") for (int _i = 0; _i < 2; ++_i) \
;         __builtin_amdgcn_global_load_lds((const unsigned*)((const char*)(gbase) + (rows)[_i]), (LAS unsigned*)(lds + (bufoff) + ldsw + _i * 8192), 16, 0, 0); } while (0)
; #define PG8_LDA(dst, b, h) do { _Pragma("unroll") for (int m = 0; m < 4; ++m) _Pragma("unroll") for (int k = 0; k < 2; ++k) dst[m][k] = *(const LAS bf16x8*)(lds + PG8_SA(b, h) + aoff + m * 2048 + k * 1024); } while (0)
; #define PG8_MMA(ai, bj, At, Bt) do { __builtin_amdgcn_s_setprio(1); _Pragma("unroll") for (int m = 0; m < 4; ++m) _Pragma("unroll") for (int n = 0; n < 2; ++n) _Pragma("unroll") for (int k = 0; k < 2; ++k) \
;         acc[ai][bj][m][n] = __builtin_amdgcn_mfma_f32_16x16x32_bf16(Bt[n][k], At[m][k], acc[ai][bj][m][n], 0, 0, 0); __builtin_amdgcn_s_setprio(0); } while (0)
; #define PG8_WAIT_V(n) asm volatile("s_waitcnt vmcnt(" #n ")" ::: "memory")
; #define PG8_WAIT_L(n) asm volatile("s_waitcnt lgkmcnt(" #n ")" ::: "memory")
; #define PG8_BAR __builtin_amdgcn_s_barrier()
; #define PG8_SCHED __builtin_amdgcn_sched_barrier(0)
; template <class Epi, class Sched>
; __device__ __forceinline__ void gemm_phase(LAS unsigned char* lds, const Sched& S, const Epi& E, const int tid) {
;     ...
;             PG8_LDA(At, 1, 1); PG8_STAGE(PG8_SB(1, 0), b3, vB); PG8_STAGE(PG8_SB(1, 1), b3 + hB, vB); PG8_STAGE(PG8_SA(1, 0), a3, vA);
;             PG8_WAIT_V(8); PG8_WAIT_L(0); PG8_BAR; PG8_MMA(1, 0, At, B0); PG8_MMA(1, 1, At, B1); PG8_BAR; PG8_SCHED;
;         }
;         if (wr == 0) PG8_BAR;
	s_add_i32 s22, s50, s37
	v_lshl_add_u64 v[208:209], v[208:209], 0, s[82:83]
	s_mov_b32 m0, s22
	ds_read_b128 v[176:179], v143 offset:49152
	ds_read_b128 v[180:183], v143 offset:50176
	ds_read_b128 v[184:187], v143 offset:51200
	ds_read_b128 v[188:191], v143 offset:52224
	ds_read_b128 v[192:195], v143 offset:53248
	ds_read_b128 v[196:199], v143 offset:54272
	ds_read_b128 v[200:203], v143 offset:55296
	ds_read_b128 v[204:207], v143 offset:56320
	global_load_lds_dwordx4 v[208:209], off
	s_add_i32 m0, s22, 0x2000
	s_add_u32 s20, s20, 0x80080
	v_lshl_add_u64 v[208:209], v[210:211], 0, s[82:83]
	s_addc_u32 s21, s21, 0
	s_add_i32 s22, s51, s37
	global_load_lds_dwordx4 v[208:209], off
	v_lshl_add_u64 v[208:209], s[20:21], 0, v[132:133]
	s_mov_b32 m0, s22
	s_nop 0
	global_load_lds_dwordx4 v[208:209], off
	v_lshl_add_u64 v[208:209], s[20:21], 0, v[136:137]
	s_add_i32 m0, s22, 0x2000
	s_nop 0
	global_load_lds_dwordx4 v[208:209], off
	v_lshl_add_u64 v[208:209], v[212:213], 0, s[82:83]
	s_mov_b32 m0, s60
	s_nop 0
	global_load_lds_dwordx4 v[208:209], off
	v_lshl_add_u64 v[208:209], v[214:215], 0, s[82:83]
	s_mov_b32 m0, s61
	s_nop 0
	global_load_lds_dwordx4 v[208:209], off
	s_waitcnt vmcnt(8)
	s_waitcnt lgkmcnt(0)
	s_barrier
	s_waitcnt lgkmcnt(0)
	v_mfma_f32_16x16x32_bf16 v[54:57], v[144:147], v[176:179], v[54:57]
	v_mfma_f32_16x16x32_bf16 v[42:45], v[152:155], v[176:179], v[42:45]
	v_mfma_f32_16x16x32_bf16 v[38:41], v[144:147], v[184:187], v[38:41]
	v_mfma_f32_16x16x32_bf16 v[34:37], v[152:155], v[184:187], v[34:37]
	v_mfma_f32_16x16x32_bf16 v[22:25], v[144:147], v[192:195], v[22:25]
	v_mfma_f32_16x16x32_bf16 v[18:21], v[152:155], v[192:195], v[18:21]
	v_mfma_f32_16x16x32_bf16 v[6:9], v[144:147], v[200:203], v[6:9]
	v_mfma_f32_16x16x32_bf16 v[2:5], v[152:155], v[200:203], v[2:5]
	v_mfma_f32_16x16x32_bf16 v[54:57], v[148:151], v[180:183], v[54:57]
	v_mfma_f32_16x16x32_bf16 v[42:45], v[156:159], v[180:183], v[42:45]
	v_mfma_f32_16x16x32_bf16 v[38:41], v[148:151], v[188:191], v[38:41]
	v_mfma_f32_16x16x32_bf16 v[34:37], v[156:159], v[188:191], v[34:37]
	v_mfma_f32_16x16x32_bf16 v[22:25], v[148:151], v[196:199], v[22:25]
	v_mfma_f32_16x16x32_bf16 v[18:21], v[156:159], v[196:199], v[18:21]
	v_mfma_f32_16x16x32_bf16 v[6:9], v[148:151], v[204:207], v[6:9]
	v_mfma_f32_16x16x32_bf16 v[2:5], v[156:159], v[204:207], v[2:5]
	v_mfma_f32_16x16x32_bf16 v[30:33], v[160:163], v[176:179], v[30:33]
	v_mfma_f32_16x16x32_bf16 v[26:29], v[168:171], v[176:179], v[26:29]
	v_mfma_f32_16x16x32_bf16 v[14:17], v[160:163], v[184:187], v[14:17]
	v_mfma_f32_16x16x32_bf16 v[10:13], v[168:171], v[184:187], v[10:13]
	v_mfma_f32_16x16x32_bf16 v[58:61], v[160:163], v[192:195], v[58:61]
	v_mfma_f32_16x16x32_bf16 v[62:65], v[168:171], v[192:195], v[62:65]
	v_mfma_f32_16x16x32_bf16 v[46:49], v[160:163], v[200:203], v[46:49]
	v_mfma_f32_16x16x32_bf16 v[50:53], v[168:171], v[200:203], v[50:53]
	v_mfma_f32_16x16x32_bf16 v[30:33], v[164:167], v[180:183], v[30:33]
	v_mfma_f32_16x16x32_bf16 v[26:29], v[172:175], v[180:183], v[26:29]
	v_mfma_f32_16x16x32_bf16 v[14:17], v[164:167], v[188:191], v[14:17]
	v_mfma_f32_16x16x32_bf16 v[10:13], v[172:175], v[188:191], v[10:13]
	v_mfma_f32_16x16x32_bf16 v[58:61], v[164:167], v[196:199], v[58:61]
	v_mfma_f32_16x16x32_bf16 v[62:65], v[172:175], v[196:199], v[62:65]
	v_mfma_f32_16x16x32_bf16 v[46:49], v[164:167], v[204:207], v[46:49]
	v_mfma_f32_16x16x32_bf16 v[50:53], v[172:175], v[204:207], v[50:53]
	s_barrier
	s_add_i32 s78, s78, 2
	s_add_u32 s4, s4, 0x100
	s_addc_u32 s5, s5, 0
	s_add_u32 s13, s13, 0x100
	s_addc_u32 s77, s77, 0
	s_cmp_gt_u32 s78, 29
	s_cbranch_scc0 .LBB0_992
	s_and_b64 vcc, exec, s[8:9]
	s_cbranch_vccz .LBB0_995
	s_barrier

; __device__ __forceinline__ void xcd_barrier(const XcdBarrier& b) {
;     asm volatile("s_waitcnt vmcnt(0)" ::: "memory");
;     __syncthreads();
;     if (threadIdx.x == 0) {
;         unsigned* bar = b.bar;
;         __builtin_amdgcn_s_waitcnt(0);
;         unsigned nloc = b.st[0], nx = b.st[1];
;         if (nloc == 0u) { xcd_barrier_complete(bar, b.x, nloc, nx); b.st[0] = nloc; b.st[1] = nx; }
.LBB0_999:
	s_mov_b64 s[4:5], s[66:67]
	s_waitcnt vmcnt(0) lgkmcnt(0)
	s_setprio 0
	s_getreg_b32 s8, hwreg(HW_REG_XCC_ID, 0, 4)
	s_waitcnt vmcnt(0)
	s_waitcnt vmcnt(0) lgkmcnt(0)
	s_barrier
	s_and_saveexec_b64 s[0:1], s[26:27]
	s_cbranch_execz .LBB0_1051
	v_mov_b32_e32 v0, s96
	s_load_dwordx2 s[4:5], s[4:5], 0xc0
	s_waitcnt vmcnt(0) expcnt(0) lgkmcnt(0)
	ds_read_b32 v3, v0
	v_mov_b32_e32 v0, s97
	ds_read_b32 v2, v0
	s_and_b32 s30, s8, 15
	s_waitcnt lgkmcnt(1)
	v_cmp_ne_u32_e32 vcc, 0, v3
	s_cbranch_vccnz .LBB0_1015
	s_add_u32 s8, s4, 0x1200
	s_addc_u32 s9, s5, 0
	s_add_u32 s10, s4, 0x1400
	s_addc_u32 s11, s5, 0
	s_add_u32 s12, s4, 0x1500
	s_addc_u32 s13, s5, 0
	s_add_u32 s14, s4, 0x1600
	s_addc_u32 s15, s5, 0
	s_add_u32 s16, s4, 0x1700
	s_addc_u32 s17, s5, 0
	s_add_u32 s18, s4, 0x1800
	s_addc_u32 s19, s5, 0
	s_add_u32 s20, s4, 0x1900
	s_addc_u32 s21, s5, 0
	s_add_u32 s22, s4, 0x1a00
	s_addc_u32 s23, s5, 0
	s_add_u32 s24, s4, 0x1b00
	s_addc_u32 s25, s5, 0
	s_add_u32 s38, s4, 0x1c00
	s_addc_u32 s39, s5, 0
	s_add_u32 s48, s4, 0x1d00
	s_addc_u32 s49, s5, 0
	s_add_u32 s52, s4, 0x1e00
	s_addc_u32 s53, s5, 0
	s_add_u32 s60, s4, 0x1f00
	s_addc_u32 s61, s5, 0
	s_add_u32 s76, s4, 0x2000
	s_addc_u32 s77, s5, 0
	s_add_u32 s78, s4, 0x2100
	s_addc_u32 s79, s5, 0
	s_add_u32 s80, s4, 0x2200
	s_addc_u32 s81, s5, 0
	s_add_u32 s84, s4, 0x2300
	s_addc_u32 s85, s5, 0
	s_mov_b32 s35, 1
	s_branch .LBB0_1003

; __device__ __forceinline__ void xcd_barrier(const XcdBarrier& b) {
;     asm volatile("s_waitcnt vmcnt(0)" ::: "memory");
;     __syncthreads();
;     if (threadIdx.x == 0) {
;         unsigned* bar = b.bar;
;         __builtin_amdgcn_s_waitcnt(0);
;         unsigned nloc = b.st[0], nx = b.st[1];
;         if (nloc == 0u) { xcd_barrier_complete(bar, b.x, nloc, nx); b.st[0] = nloc; b.st[1] = nx; }
.LBB0_1068:
	s_or_b64 exec, exec, s[0:1]
	s_mov_b64 s[4:5], s[66:67]
	s_waitcnt vmcnt(0) lgkmcnt(0)
	s_setprio 0
	s_getreg_b32 s8, hwreg(HW_REG_XCC_ID, 0, 4)
	s_waitcnt vmcnt(0)
	s_barrier
	s_and_saveexec_b64 s[0:1], s[26:27]
	s_cbranch_execz .LBB0_1120
	v_mov_b32_e32 v0, s96
	s_load_dwordx2 s[4:5], s[4:5], 0xc0
	s_waitcnt vmcnt(0) expcnt(0) lgkmcnt(0)
	ds_read_b32 v3, v0
	v_mov_b32_e32 v0, s97
	ds_read_b32 v2, v0
	s_and_b32 s30, s8, 15
	s_waitcnt lgkmcnt(1)
	v_cmp_ne_u32_e32 vcc, 0, v3
	s_cbranch_vccnz .LBB0_1084
	s_add_u32 s8, s4, 0x1200
	s_addc_u32 s9, s5, 0
	s_add_u32 s10, s4, 0x1400
	s_addc_u32 s11, s5, 0
	s_add_u32 s12, s4, 0x1500
	s_addc_u32 s13, s5, 0
	s_add_u32 s14, s4, 0x1600
	s_addc_u32 s15, s5, 0
	s_add_u32 s16, s4, 0x1700
	s_addc_u32 s17, s5, 0
	s_add_u32 s18, s4, 0x1800
	s_addc_u32 s19, s5, 0
	s_add_u32 s20, s4, 0x1900
	s_addc_u32 s21, s5, 0
	s_add_u32 s22, s4, 0x1a00
	s_addc_u32 s23, s5, 0
	s_add_u32 s24, s4, 0x1b00
	s_addc_u32 s25, s5, 0
	s_add_u32 s38, s4, 0x1c00
	s_addc_u32 s39, s5, 0
	s_add_u32 s48, s4, 0x1d00
	s_addc_u32 s49, s5, 0
	s_add_u32 s52, s4, 0x1e00
	s_addc_u32 s53, s5, 0
	s_add_u32 s60, s4, 0x1f00
	s_addc_u32 s61, s5, 0
	s_add_u32 s76, s4, 0x2000
	s_addc_u32 s77, s5, 0
	s_add_u32 s78, s4, 0x2100
	s_addc_u32 s79, s5, 0
	s_add_u32 s80, s4, 0x2200
	s_addc_u32 s81, s5, 0
	s_add_u32 s84, s4, 0x2300
	s_addc_u32 s85, s5, 0
	s_mov_b32 s35, 1
	s_branch .LBB0_1072

; __device__ __forceinline__ ParamsCP get_params() { ParamsCP q = (ParamsCP)__builtin_amdgcn_kernarg_segment_ptr(); asm volatile("" : "+s"(q)); return q; }
; #define PG8_BAR __builtin_amdgcn_s_barrier()
; template <class Epi, class Sched>
; __device__ __forceinline__ void gemm_phase(LAS unsigned char* lds, const Sched& S, const Epi& E, const int tid) {
;     const int wid = __builtin_amdgcn_readfirstlane(tid >> 6), lane = tid & 63, wr = wid >> 2, wc = wid & 3, fr = lane & 15, fq = lane >> 4;
;     int sR[2], sC[2], sRbi[2];
; #pragma unroll
;     for (int i = 0; i < 2; ++i) { stage_rc(tid * 16 + i * 8192, sR[i], sC[i]); sRbi[i] = (sR[i] & ~31) + perm32(sR[i] & 31); }
;     const unsigned ldsw = (unsigned)wid * 1024u;
;     const int aoff = lds_byte(wr * 64 + fr, fq * 8), boff = lds_byte(wc * 32 + fr, fq * 8);
;     ...
;     GUnit cur, nxt; int ui = 0;
;     if (!S.next(0, cur)) return;
;     f32x4 acc[2][2][4][2];
; #pragma unroll
;     for (int a = 0; a < 2; ++a)
; #pragma unroll
;         for (int b = 0; b < 2; ++b)
; #pragma unroll
;             for (int m = 0; m < 4; ++m)
; #pragma unroll
;                 for (int n = 0; n < 2; ++n) acc[a][b][m][n] = (f32x4){0.f, 0.f, 0.f, 0.f};
;     bf16x8 At[4][2], B0[2][2], B1[2][2];
;     const char* cA = cur.A; const char* cB = cur.B;
;     constexpr unsigned kstep = (unsigned)(BK * 2);
;     const unsigned lda = cur.lda, ldb = cur.ldb, hA = HALF * lda, hB = HALF * ldb;
;     unsigned vA[2], vB[2];
; #pragma unroll
;     for (int i = 0; i < 2; ++i) { vA[i] = (unsigned)sR[i] * lda + (unsigned)sC[i] * 2u; vB[i] = (unsigned)sRbi[i] * ldb + (unsigned)sC[i] * 2u; }
;     PG8_STAGE(PG8_SB(0, 0), cB, vB); PG8_STAGE(PG8_SB(0, 1), cB + hB, vB); PG8_STAGE(PG8_SA(0, 0), cA, vA); PG8_STAGE(PG8_SA(0, 1), cA + hA, vA);
;     if (wr == 1) PG8_BAR;
; __global__ void __launch_bounds__(512) fwd_kernel(Params p_unused) {
;     ...
;         { FRESH_IDS(); ParamsCP pp = get_params(); unsigned char* ws = pp->ws; float* hmeta = (float*)(ws + WS_HMETA);
;           SchedPlain S{(const char*)(ws + WS_BIG + BIG_V), (const char*)(ws + WS_WT + WT_DOWN), (unsigned)(DFF * 2), (unsigned)(DFF * 2), DFF / 64, 128, 8, 1, G, blk};
;           EpiResid E{(const float*)pp->out, hmeta, pp->out, hmeta}; pg8::gemm_phase(lds, S, E, tid); }
.LBB0_1120:
	s_or_b64 exec, exec, s[0:1]
	s_waitcnt lgkmcnt(0)
	s_barrier
	v_mov_b32_e32 v15, v222
	s_mov_b64 s[0:1], s[66:67]
	s_and_b64 vcc, exec, s[6:7]
	v_readfirstlane_b32 s6, v15
	s_cbranch_vccnz .LBB0_1140
	v_lshlrev_b32_e32 v2, 4, v15
	v_add_u32_e32 v3, 0x2000, v2
	v_ashrrev_i32_e32 v0, 31, v3
	v_lshrrev_b32_e32 v0, 22, v0
	v_add_u32_e32 v0, v3, v0
	v_ashrrev_i32_e32 v0, 10, v0
	v_mul_i32_i24_e32 v4, 0x400, v0
	v_sub_u32_e32 v3, v3, v4
	v_lshrrev_b32_e32 v4, 4, v3
	v_bitop3_b32 v3, v4, v3, 32 bitop3:0x6c
	v_ashrrev_i32_e32 v4, 31, v3
	v_lshrrev_b32_e32 v4, 26, v4
	v_add_u32_e32 v4, v3, v4
	v_ashrrev_i32_e32 v10, 6, v4
	v_and_b32_e32 v4, 0xc0, v4
	v_lshlrev_b32_e32 v5, 3, v0
	v_sub_u32_e32 v3, v3, v4
	v_bfe_i32 v4, v15, 27, 1
	v_and_b32_e32 v5, -16, v5
	v_lshrrev_b32_e32 v4, 22, v4
	v_add_u32_e32 v5, v10, v5
	v_add_u32_e32 v4, v2, v4
	s_load_dwordx4 s[8:11], s[0:1], 0xb8
	v_and_b32_e32 v6, 3, v10
	s_mov_b32 s0, 0xffffe0
	v_lshrrev_b32_e32 v7, 2, v5
	v_lshlrev_b32_e32 v8, 1, v5
	v_and_b32_e32 v4, 0xfffffc00, v4
	v_and_or_b32 v6, v5, s0, v6
	v_and_b32_e32 v7, 4, v7
	v_and_b32_e32 v8, 24, v8
	v_sub_u32_e32 v2, v2, v4
	v_or3_b32 v6, v6, v7, v8
	v_lshrrev_b32_e32 v4, 4, v2
	v_ashrrev_i32_e32 v7, 31, v15
	v_bitop3_b32 v2, v4, v2, 32 bitop3:0x6c
	v_lshrrev_b32_e32 v7, 26, v7
	v_ashrrev_i32_e32 v4, 31, v2
	v_add_u32_e32 v7, v15, v7
	v_lshrrev_b32_e32 v4, 26, v4
	v_ashrrev_i32_e32 v13, 6, v7
	s_waitcnt lgkmcnt(0)
	s_add_u32 s20, s10, 0x28030000
	v_add_u32_e32 v4, v2, v4
	v_lshlrev_b32_e32 v7, 3, v13
	s_addc_u32 s21, s11, 0
	v_ashrrev_i32_e32 v12, 6, v4
	v_and_b32_e32 v7, -16, v7
	s_add_u32 s22, s10, 0x8f00000
	v_add_u32_e32 v7, v12, v7
	v_and_b32_e32 v8, 3, v12
	s_addc_u32 s23, s11, 0
	s_ashr_i32 s7, s6, 6
	v_and_or_b32 v8, v7, s0, v8
	v_and_b32_e32 v4, 0xc0, v4
	v_readlane_b32 s0, v254, 16
	s_ashr_i32 s12, s6, 8
	s_lshl_b32 s24, s7, 10
	v_lshrrev_b32_e32 v9, 2, v7
	v_lshlrev_b32_e32 v14, 1, v7
	v_sub_u32_e32 v2, v2, v4
	v_readlane_b32 s1, v254, 17
	s_mov_b32 s14, s0
	s_mul_i32 s0, s0, 0x2b0000
	v_and_b32_e32 v9, 4, v9
	v_and_b32_e32 v14, 24, v14
	v_ashrrev_i16_sdwa v2, v231, sext(v2) dst_sel:DWORD dst_unused:UNUSED_PAD src0_sel:DWORD src1_sel:BYTE_0
	s_add_u32 s4, s20, s0
	s_mul_hi_i32 s0, s14, 0x2b0000
	v_readlane_b32 s1, v254, 15
	v_ashrrev_i16_sdwa v3, v231, sext(v3) dst_sel:DWORD dst_unused:UNUSED_PAD src0_sel:DWORD src1_sel:BYTE_0
	v_or3_b32 v8, v8, v9, v14
	v_bfe_i32 v14, v2, 0, 16
	v_lshlrev_b32_e32 v2, 5, v13
	s_addc_u32 s5, s21, s0
	s_mul_i32 s0, s1, 0x2b0000
	v_bfe_i32 v11, v3, 0, 16
	v_lshlrev_b32_e32 v3, 5, v0
	v_and_b32_e32 v2, 32, v2
	s_add_u32 s16, s22, s0
	s_mul_hi_i32 s0, s1, 0x2b0000
	v_and_b32_e32 v3, 32, v3
	s_addc_u32 s17, s23, s0
	v_add_lshl_u32 v2, v2, v14, 1
	s_add_i32 s25, s24, 0
	v_mad_u64_u32 v[130:131], s[0:1], v7, s65, v[2:3]
	v_mad_u32_u24 v132, v8, s65, v2
	v_add_lshl_u32 v2, v3, v11, 1
	s_add_i32 m0, s25, 0x10000
	v_mad_u64_u32 v[134:135], s[0:1], v5, s65, v[2:3]
	global_load_lds_dwordx4 v132, s[16:17]
	s_add_i32 m0, s25, 0x12000
	v_mad_u32_u24 v136, v6, s65, v2
	s_add_u32 s0, s16, 0x158000
	global_load_lds_dwordx4 v136, s[16:17]
	s_addc_u32 s1, s17, 0
	s_add_i32 m0, s25, 0x14000
	s_add_i32 s30, s25, 0x2000
	global_load_lds_dwordx4 v132, s[0:1]
	s_add_i32 m0, s25, 0x16000
	v_mov_b32_e32 v133, v1
	global_load_lds_dwordx4 v136, s[0:1]
	s_mov_b32 m0, s25
	s_add_u32 s0, s4, 0x158000
	global_load_lds_dwordx4 v130, s[4:5]
	s_mov_b32 m0, s30
	s_addc_u32 s1, s5, 0
	s_add_i32 s35, s25, 0x4000
	global_load_lds_dwordx4 v134, s[4:5]
	s_mov_b32 m0, s35
	s_add_i32 s37, s25, 0x6000
	global_load_lds_dwordx4 v130, s[0:1]
	s_mov_b32 m0, s37
	v_mov_b32_e32 v137, v1
	global_load_lds_dwordx4 v134, s[0:1]
	v_mov_b32_e32 v131, v1
	v_mov_b32_e32 v135, v1
	s_cmp_eq_u32 s12, 1
	v_lshl_add_u64 v[8:9], s[16:17], 0, v[132:133]
	v_lshl_add_u64 v[6:7], s[16:17], 0, v[136:137]
	v_lshl_add_u64 v[2:3], s[4:5], 0, v[130:131]
	s_cselect_b64 s[0:1], -1, 0
	s_cmp_lg_u32 s12, 1
	v_lshl_add_u64 v[4:5], s[4:5], 0, v[134:135]
	s_cbranch_scc1 .LBB0_1123
	s_setprio 1
	s_barrier

; #define PG8_STAGE(bufoff, gbase, rows) do { _Pragma("unroll") for (int _i = 0; _i < 2; ++_i) \
;         __builtin_amdgcn_global_load_lds((const unsigned*)((const char*)(gbase) + (rows)[_i]), (LAS unsigned*)(lds + (bufoff) + ldsw + _i * 8192), 16, 0, 0); } while (0)
; #define PG8_LDA(dst, b, h) do { _Pragma("unroll") for (int m = 0; m < 4; ++m) _Pragma("unroll") for (int k = 0; k < 2; ++k) dst[m][k] = *(const LAS bf16x8*)(lds + PG8_SA(b, h) + aoff + m * 2048 + k * 1024); } while (0)
; #define PG8_LDB(dst, b, h) do { _Pragma("unroll") for (int n = 0; n < 2; ++n) _Pragma("unroll") for (int k = 0; k < 2; ++k) dst[n][k] = *(const LAS bf16x8*)(lds + PG8_SB(b, h) + boff + n * 2048 + k * 1024); } while (0)
; #define PG8_MMA(ai, bj, At, Bt) do { __builtin_amdgcn_s_setprio(1); _Pragma("unroll") for (int m = 0; m < 4; ++m) _Pragma("unroll") for (int n = 0; n < 2; ++n) _Pragma("unroll") for (int k = 0; k < 2; ++k) \
;         acc[ai][bj][m][n] = __builtin_amdgcn_mfma_f32_16x16x32_bf16(Bt[n][k], At[m][k], acc[ai][bj][m][n], 0, 0, 0); __builtin_amdgcn_s_setprio(0); } while (0)
; #define PG8_WAIT_V(n) asm volatile("s_waitcnt vmcnt(" #n ")" ::: "memory")
; #define PG8_WAIT_L(n) asm volatile("s_waitcnt lgkmcnt(" #n ")" ::: "memory")
; #define PG8_BAR __builtin_amdgcn_s_barrier()
; #define PG8_SCHED __builtin_amdgcn_sched_barrier(0)
; template <class Epi, class Sched>
; __device__ __forceinline__ void gemm_phase(LAS unsigned char* lds, const Sched& S, const Epi& E, const int tid) {
;     ...
;         for (int t = 0; t < nt; t += 2) {
;             const bool last = (t == nt - 2);
;             const char* a1 = cA + (size_t)(t + 1) * kstep;
;             const char* a2 = last ? nA : cA + (size_t)(t + 2) * kstep; const char* b2 = last ? nB : cB + (size_t)(t + 2) * kstep;
;             const char* a3 = a2 + kstep; const char* b3 = b2 + kstep;
;             PG8_LDB(B0, 0, 0); PG8_LDB(B1, 0, 1); PG8_SCHED; PG8_LDA(At, 0, 0); PG8_STAGE(PG8_SA(1, 1), a1 + hA, vA);
;             PG8_WAIT_V(8); PG8_WAIT_L(0); PG8_BAR; PG8_MMA(0, 0, At, B0); PG8_MMA(0, 1, At, B1); PG8_BAR; PG8_SCHED;
;             PG8_LDA(At, 0, 1); PG8_STAGE(PG8_SB(0, 0), b2, vB); PG8_STAGE(PG8_SB(0, 1), b2 + hB, vB); PG8_STAGE(PG8_SA(0, 0), a2, vA);
;             PG8_WAIT_V(8); PG8_WAIT_L(0); PG8_BAR; PG8_MMA(1, 0, At, B0); PG8_MMA(1, 1, At, B1); PG8_BAR; PG8_SCHED;
.LBB0_1133:
	s_add_u32 s16, s4, 0xffea8080
	s_addc_u32 s17, s5, -1
	s_add_i32 s50, 0, 0x10000
	s_cmpk_eq_i32 s76, 0x52
	s_cselect_b32 s19, s13, s17
	s_cselect_b32 s18, s12, s16
	v_add_u32_e32 v0, s50, v142
	s_cselect_b32 s17, s15, s64
	s_cselect_b32 s16, s14, s61
	s_add_i32 s51, 0, 0x14000
	ds_read_b128 v[144:147], v0
	ds_read_b128 v[148:151], v0 offset:1024
	ds_read_b128 v[152:155], v0 offset:2048
	ds_read_b128 v[156:159], v0 offset:3072
	v_add_u32_e32 v0, s51, v142
	ds_read_b128 v[160:163], v0
	ds_read_b128 v[164:167], v0 offset:1024
	ds_read_b128 v[168:171], v0 offset:2048
	ds_read_b128 v[172:175], v0 offset:3072
	v_lshl_add_u64 v[208:209], s[4:5], 0, v[138:139]
	s_add_i32 m0, s25, 0xc000
	ds_read_b128 v[176:179], v143
	ds_read_b128 v[180:183], v143 offset:1024
	ds_read_b128 v[184:187], v143 offset:2048
	ds_read_b128 v[188:191], v143 offset:3072
	ds_read_b128 v[192:195], v143 offset:4096
	ds_read_b128 v[196:199], v143 offset:5120
	ds_read_b128 v[200:203], v143 offset:6144
	ds_read_b128 v[204:207], v143 offset:7168
	global_load_lds_dwordx4 v[208:209], off
	v_lshl_add_u64 v[208:209], s[4:5], 0, v[140:141]
	s_add_i32 m0, s25, 0xe000
	s_nop 0
	global_load_lds_dwordx4 v[208:209], off
	s_waitcnt vmcnt(8)
	s_waitcnt lgkmcnt(0)
	s_barrier
	s_waitcnt lgkmcnt(0)
	v_mfma_f32_16x16x32_bf16 v[126:129], v[144:147], v[176:179], v[126:129]
	v_mfma_f32_16x16x32_bf16 v[122:125], v[152:155], v[176:179], v[122:125]
	v_mfma_f32_16x16x32_bf16 v[114:117], v[144:147], v[184:187], v[114:117]
	v_mfma_f32_16x16x32_bf16 v[106:109], v[152:155], v[184:187], v[106:109]
	v_mfma_f32_16x16x32_bf16 v[102:105], v[144:147], v[192:195], v[102:105]
	v_mfma_f32_16x16x32_bf16 v[94:97], v[152:155], v[192:195], v[94:97]
	v_mfma_f32_16x16x32_bf16 v[86:89], v[144:147], v[200:203], v[86:89]
	v_mfma_f32_16x16x32_bf16 v[78:81], v[152:155], v[200:203], v[78:81]
	v_mfma_f32_16x16x32_bf16 v[126:129], v[148:151], v[180:183], v[126:129]
	v_mfma_f32_16x16x32_bf16 v[122:125], v[156:159], v[180:183], v[122:125]
	v_mfma_f32_16x16x32_bf16 v[114:117], v[148:151], v[188:191], v[114:117]
	v_mfma_f32_16x16x32_bf16 v[106:109], v[156:159], v[188:191], v[106:109]
	v_mfma_f32_16x16x32_bf16 v[102:105], v[148:151], v[196:199], v[102:105]
	v_mfma_f32_16x16x32_bf16 v[94:97], v[156:159], v[196:199], v[94:97]
	v_mfma_f32_16x16x32_bf16 v[86:89], v[148:151], v[204:207], v[86:89]
	v_mfma_f32_16x16x32_bf16 v[78:81], v[156:159], v[204:207], v[78:81]
	v_mfma_f32_16x16x32_bf16 v[118:121], v[160:163], v[176:179], v[118:121]
	v_mfma_f32_16x16x32_bf16 v[110:113], v[168:171], v[176:179], v[110:113]
	v_mfma_f32_16x16x32_bf16 v[98:101], v[160:163], v[184:187], v[98:101]
	v_mfma_f32_16x16x32_bf16 v[90:93], v[168:171], v[184:187], v[90:93]
	v_mfma_f32_16x16x32_bf16 v[82:85], v[160:163], v[192:195], v[82:85]
	v_mfma_f32_16x16x32_bf16 v[74:77], v[168:171], v[192:195], v[74:77]
	v_mfma_f32_16x16x32_bf16 v[70:73], v[160:163], v[200:203], v[70:73]
	v_mfma_f32_16x16x32_bf16 v[66:69], v[168:171], v[200:203], v[66:69]
	v_mfma_f32_16x16x32_bf16 v[118:121], v[164:167], v[180:183], v[118:121]
	v_mfma_f32_16x16x32_bf16 v[110:113], v[172:175], v[180:183], v[110:113]
	v_mfma_f32_16x16x32_bf16 v[98:101], v[164:167], v[188:191], v[98:101]
	v_mfma_f32_16x16x32_bf16 v[90:93], v[172:175], v[188:191], v[90:93]
	v_mfma_f32_16x16x32_bf16 v[82:85], v[164:167], v[196:199], v[82:85]
	v_mfma_f32_16x16x32_bf16 v[74:77], v[172:175], v[196:199], v[74:77]
	v_mfma_f32_16x16x32_bf16 v[70:73], v[164:167], v[204:207], v[70:73]
	v_mfma_f32_16x16x32_bf16 v[66:69], v[172:175], v[204:207], v[66:69]
	s_barrier
	s_add_i32 s50, s50, s24
	v_lshl_add_u64 v[208:209], s[16:17], 0, v[132:133]
	s_mov_b32 m0, s50
	ds_read_b128 v[176:179], v143 offset:16384
	ds_read_b128 v[180:183], v143 offset:17408
	ds_read_b128 v[184:187], v143 offset:18432
	ds_read_b128 v[188:191], v143 offset:19456
	ds_read_b128 v[192:195], v143 offset:20480
	ds_read_b128 v[196:199], v143 offset:21504
	ds_read_b128 v[200:203], v143 offset:22528
	ds_read_b128 v[204:207], v143 offset:23552
	global_load_lds_dwordx4 v[208:209], off
	s_add_i32 m0, s50, 0x2000
	s_add_u32 s78, s16, 0x158000
	v_lshl_add_u64 v[210:211], s[16:17], 0, v[136:137]
	s_addc_u32 s79, s17, 0
	s_add_i32 s50, s51, s24
	global_load_lds_dwordx4 v[210:211], off
	v_lshl_add_u64 v[212:213], s[78:79], 0, v[132:133]
	s_mov_b32 m0, s50
	v_lshl_add_u64 v[214:215], s[18:19], 0, v[134:135]
	global_load_lds_dwordx4 v[212:213], off
	v_lshl_add_u64 v[212:213], s[78:79], 0, v[136:137]
	s_add_i32 m0, s50, 0x2000
	s_nop 0
	global_load_lds_dwordx4 v[212:213], off
	v_lshl_add_u64 v[212:213], s[18:19], 0, v[130:131]
	s_mov_b32 m0, s25
	s_nop 0
	global_load_lds_dwordx4 v[212:213], off
	s_mov_b32 m0, s30
	s_nop 0
	global_load_lds_dwordx4 v[214:215], off
	s_waitcnt vmcnt(8)
	s_waitcnt lgkmcnt(0)
	s_barrier
; #define PG8_STAGE(bufoff, gbase, rows) do { _Pragma("unroll") for (int _i = 0; _i < 2; ++_i) \
;         __builtin_amdgcn_global_load_lds((const unsigned*)((const char*)(gbase) + (rows)[_i]), (LAS unsigned*)(lds + (bufoff) + ldsw + _i * 8192), 16, 0, 0); } while (0)
; #define PG8_LDA(dst, b, h) do { _Pragma("unroll") for (int m = 0; m < 4; ++m) _Pragma("unroll") for (int k = 0; k < 2; ++k) dst[m][k] = *(const LAS bf16x8*)(lds + PG8_SA(b, h) + aoff + m * 2048 + k * 1024); } while (0)
; #define PG8_LDB(dst, b, h) do { _Pragma("unroll") for (int n = 0; n < 2; ++n) _Pragma("unroll") for (int k = 0; k < 2; ++k) dst[n][k] = *(const LAS bf16x8*)(lds + PG8_SB(b, h) + boff + n * 2048 + k * 1024); } while (0)
; #define PG8_MMA(ai, bj, At, Bt) do { __builtin_amdgcn_s_setprio(1); _Pragma("unroll") for (int m = 0; m < 4; ++m) _Pragma("unroll") for (int n = 0; n < 2; ++n) _Pragma("unroll") for (int k = 0; k < 2; ++k) \
;         acc[ai][bj][m][n] = __builtin_amdgcn_mfma_f32_16x16x32_bf16(Bt[n][k], At[m][k], acc[ai][bj][m][n], 0, 0, 0); __builtin_amdgcn_s_setprio(0); } while (0)
; #define PG8_WAIT_V(n) asm volatile("s_waitcnt vmcnt(" #n ")" ::: "memory")
; #define PG8_WAIT_L(n) asm volatile("s_waitcnt lgkmcnt(" #n ")" ::: "memory")
; #define PG8_BAR __builtin_amdgcn_s_barrier()
; #define PG8_SCHED __builtin_amdgcn_sched_barrier(0)
; template <class Epi, class Sched>
; __device__ __forceinline__ void gemm_phase(LAS unsigned char* lds, const Sched& S, const Epi& E, const int tid) {
;     ...
;             PG8_WAIT_V(8); PG8_WAIT_L(0); PG8_BAR; PG8_MMA(1, 0, At, B0); PG8_MMA(1, 1, At, B1); PG8_BAR; PG8_SCHED;
;             PG8_LDB(B0, 1, 0); PG8_LDB(B1, 1, 1); PG8_SCHED; PG8_LDA(At, 1, 0); PG8_STAGE(PG8_SA(0, 1), a2 + hA, vA);
;             PG8_WAIT_V(8); PG8_WAIT_L(0); PG8_BAR; PG8_MMA(0, 0, At, B0); PG8_MMA(0, 1, At, B1); PG8_BAR; PG8_SCHED;
	s_waitcnt lgkmcnt(0)
	v_mfma_f32_16x16x32_bf16 v[62:65], v[144:147], v[176:179], v[62:65]
	v_mfma_f32_16x16x32_bf16 v[58:61], v[152:155], v[176:179], v[58:61]
	v_mfma_f32_16x16x32_bf16 v[46:49], v[144:147], v[184:187], v[46:49]
	v_mfma_f32_16x16x32_bf16 v[38:41], v[152:155], v[184:187], v[38:41]
	v_mfma_f32_16x16x32_bf16 v[22:25], v[144:147], v[192:195], v[22:25]
	v_mfma_f32_16x16x32_bf16 v[14:17], v[152:155], v[192:195], v[14:17]
	v_mfma_f32_16x16x32_bf16 v[6:9], v[144:147], v[200:203], v[6:9]
	v_mfma_f32_16x16x32_bf16 v[2:5], v[152:155], v[200:203], v[2:5]
	v_mfma_f32_16x16x32_bf16 v[62:65], v[148:151], v[180:183], v[62:65]
	v_mfma_f32_16x16x32_bf16 v[58:61], v[156:159], v[180:183], v[58:61]
	v_mfma_f32_16x16x32_bf16 v[46:49], v[148:151], v[188:191], v[46:49]
	v_mfma_f32_16x16x32_bf16 v[38:41], v[156:159], v[188:191], v[38:41]
	v_mfma_f32_16x16x32_bf16 v[22:25], v[148:151], v[196:199], v[22:25]
	v_mfma_f32_16x16x32_bf16 v[14:17], v[156:159], v[196:199], v[14:17]
	v_mfma_f32_16x16x32_bf16 v[6:9], v[148:151], v[204:207], v[6:9]
	v_mfma_f32_16x16x32_bf16 v[2:5], v[156:159], v[204:207], v[2:5]
	v_mfma_f32_16x16x32_bf16 v[42:45], v[160:163], v[176:179], v[42:45]
	v_mfma_f32_16x16x32_bf16 v[34:37], v[168:171], v[176:179], v[34:37]
	v_mfma_f32_16x16x32_bf16 v[18:21], v[160:163], v[184:187], v[18:21]
	v_mfma_f32_16x16x32_bf16 v[10:13], v[168:171], v[184:187], v[10:13]
	v_mfma_f32_16x16x32_bf16 v[54:57], v[160:163], v[192:195], v[54:57]
	v_mfma_f32_16x16x32_bf16 v[50:53], v[168:171], v[192:195], v[50:53]
	v_mfma_f32_16x16x32_bf16 v[30:33], v[160:163], v[200:203], v[30:33]
	v_mfma_f32_16x16x32_bf16 v[26:29], v[168:171], v[200:203], v[26:29]
	v_mfma_f32_16x16x32_bf16 v[42:45], v[164:167], v[180:183], v[42:45]
	v_mfma_f32_16x16x32_bf16 v[34:37], v[172:175], v[180:183], v[34:37]
	v_mfma_f32_16x16x32_bf16 v[18:21], v[164:167], v[188:191], v[18:21]
	v_mfma_f32_16x16x32_bf16 v[10:13], v[172:175], v[188:191], v[10:13]
	v_mfma_f32_16x16x32_bf16 v[54:57], v[164:167], v[196:199], v[54:57]
	v_mfma_f32_16x16x32_bf16 v[50:53], v[172:175], v[196:199], v[50:53]
	v_mfma_f32_16x16x32_bf16 v[30:33], v[164:167], v[204:207], v[30:33]
	v_mfma_f32_16x16x32_bf16 v[26:29], v[172:175], v[204:207], v[26:29]
	s_barrier
	s_add_i32 s50, 0, 0x18000
	v_add_u32_e32 v0, s50, v142
	s_add_i32 s51, 0, 0x1c000
	ds_read_b128 v[144:147], v0
	ds_read_b128 v[148:151], v0 offset:1024
	ds_read_b128 v[152:155], v0 offset:2048
	ds_read_b128 v[156:159], v0 offset:3072
	v_add_u32_e32 v0, s51, v142
	ds_read_b128 v[160:163], v0
	ds_read_b128 v[164:167], v0 offset:1024
	ds_read_b128 v[168:171], v0 offset:2048
	ds_read_b128 v[172:175], v0 offset:3072
	s_add_u32 s18, s18, 0x158000
	s_addc_u32 s19, s19, 0
	s_mov_b32 m0, s35
	v_lshl_add_u64 v[216:217], s[18:19], 0, v[130:131]
	ds_read_b128 v[176:179], v143 offset:32768
	ds_read_b128 v[180:183], v143 offset:33792
	ds_read_b128 v[184:187], v143 offset:34816
	ds_read_b128 v[188:191], v143 offset:35840
	ds_read_b128 v[192:195], v143 offset:36864
	ds_read_b128 v[196:199], v143 offset:37888
	ds_read_b128 v[200:203], v143 offset:38912
	ds_read_b128 v[204:207], v143 offset:39936
	global_load_lds_dwordx4 v[216:217], off
	v_lshl_add_u64 v[216:217], s[18:19], 0, v[134:135]
	s_mov_b32 m0, s37
	s_nop 0
	global_load_lds_dwordx4 v[216:217], off
	s_waitcnt vmcnt(8)
	s_waitcnt lgkmcnt(0)
	s_barrier
	s_waitcnt lgkmcnt(0)
	v_mfma_f32_16x16x32_bf16 v[126:129], v[144:147], v[176:179], v[126:129]
	v_mfma_f32_16x16x32_bf16 v[122:125], v[152:155], v[176:179], v[122:125]
	v_mfma_f32_16x16x32_bf16 v[114:117], v[144:147], v[184:187], v[114:117]
	v_mfma_f32_16x16x32_bf16 v[106:109], v[152:155], v[184:187], v[106:109]
	v_mfma_f32_16x16x32_bf16 v[102:105], v[144:147], v[192:195], v[102:105]
	v_mfma_f32_16x16x32_bf16 v[94:97], v[152:155], v[192:195], v[94:97]
	v_mfma_f32_16x16x32_bf16 v[86:89], v[144:147], v[200:203], v[86:89]
	v_mfma_f32_16x16x32_bf16 v[78:81], v[152:155], v[200:203], v[78:81]
	v_mfma_f32_16x16x32_bf16 v[126:129], v[148:151], v[180:183], v[126:129]
	v_mfma_f32_16x16x32_bf16 v[122:125], v[156:159], v[180:183], v[122:125]
	v_mfma_f32_16x16x32_bf16 v[114:117], v[148:151], v[188:191], v[114:117]
	v_mfma_f32_16x16x32_bf16 v[106:109], v[156:159], v[188:191], v[106:109]
	v_mfma_f32_16x16x32_bf16 v[102:105], v[148:151], v[196:199], v[102:105]
	v_mfma_f32_16x16x32_bf16 v[94:97], v[156:159], v[196:199], v[94:97]
	v_mfma_f32_16x16x32_bf16 v[86:89], v[148:151], v[204:207], v[86:89]
	v_mfma_f32_16x16x32_bf16 v[78:81], v[156:159], v[204:207], v[78:81]
	v_mfma_f32_16x16x32_bf16 v[118:121], v[160:163], v[176:179], v[118:121]
	v_mfma_f32_16x16x32_bf16 v[110:113], v[168:171], v[176:179], v[110:113]
	v_mfma_f32_16x16x32_bf16 v[98:101], v[160:163], v[184:187], v[98:101]
	v_mfma_f32_16x16x32_bf16 v[90:93], v[168:171], v[184:187], v[90:93]
	v_mfma_f32_16x16x32_bf16 v[82:85], v[160:163], v[192:195], v[82:85]
	v_mfma_f32_16x16x32_bf16 v[74:77], v[168:171], v[192:195], v[74:77]
	v_mfma_f32_16x16x32_bf16 v[70:73], v[160:163], v[200:203], v[70:73]
	v_mfma_f32_16x16x32_bf16 v[66:69], v[168:171], v[200:203], v[66:69]
	v_mfma_f32_16x16x32_bf16 v[118:121], v[164:167], v[180:183], v[118:121]
	v_mfma_f32_16x16x32_bf16 v[110:113], v[172:175], v[180:183], v[110:113]
	v_mfma_f32_16x16x32_bf16 v[98:101], v[164:167], v[188:191], v[98:101]
	v_mfma_f32_16x16x32_bf16 v[90:93], v[172:175], v[188:191], v[90:93]
	v_mfma_f32_16x16x32_bf16 v[82:85], v[164:167], v[196:199], v[82:85]
	v_mfma_f32_16x16x32_bf16 v[74:77], v[172:175], v[196:199], v[74:77]
	v_mfma_f32_16x16x32_bf16 v[70:73], v[164:167], v[204:207], v[70:73]
	v_mfma_f32_16x16x32_bf16 v[66:69], v[172:175], v[204:207], v[66:69]
	s_barrier
; #define PG8_STAGE(bufoff, gbase, rows) do { _Pragma("unroll") for (int _i = 0; _i < 2; ++_i) \
;         __builtin_amdgcn_global_load_lds((const unsigned*)((const char*)(gbase) + (rows)[_i]), (LAS unsigned*)(lds + (bufoff) + ldsw + _i * 8192), 16, 0, 0); } while (0)
; #define PG8_LDA(dst, b, h) do { _Pragma("unroll") for (int m = 0; m < 4; ++m) _Pragma("unroll") for (int k = 0; k < 2; ++k) dst[m][k] = *(const LAS bf16x8*)(lds + PG8_SA(b, h) + aoff + m * 2048 + k * 1024); } while (0)
; #define PG8_MMA(ai, bj, At, Bt) do { __builtin_amdgcn_s_setprio(1); _Pragma("unroll") for (int m = 0; m < 4; ++m) _Pragma("unroll") for (int n = 0; n < 2; ++n) _Pragma("unroll") for (int k = 0; k < 2; ++k) \
;         acc[ai][bj][m][n] = __builtin_amdgcn_mfma_f32_16x16x32_bf16(Bt[n][k], At[m][k], acc[ai][bj][m][n], 0, 0, 0); __builtin_amdgcn_s_setprio(0); } while (0)
; #define PG8_WAIT_V(n) asm volatile("s_waitcnt vmcnt(" #n ")" ::: "memory")
; #define PG8_WAIT_L(n) asm volatile("s_waitcnt lgkmcnt(" #n ")" ::: "memory")
; #define PG8_BAR __builtin_amdgcn_s_barrier()
; #define PG8_SCHED __builtin_amdgcn_sched_barrier(0)
; template <class Epi, class Sched>
; __device__ __forceinline__ void gemm_phase(LAS unsigned char* lds, const Sched& S, const Epi& E, const int tid) {
;     ...
;             PG8_LDA(At, 1, 1); PG8_STAGE(PG8_SB(1, 0), b3, vB); PG8_STAGE(PG8_SB(1, 1), b3 + hB, vB); PG8_STAGE(PG8_SA(1, 0), a3, vA);
;             PG8_WAIT_V(8); PG8_WAIT_L(0); PG8_BAR; PG8_MMA(1, 0, At, B0); PG8_MMA(1, 1, At, B1); PG8_BAR; PG8_SCHED;
;         }
;         if (wr == 0) PG8_BAR;
	s_add_i32 s18, s50, s24
	v_lshl_add_u64 v[208:209], v[208:209], 0, s[82:83]
	s_mov_b32 m0, s18
	ds_read_b128 v[176:179], v143 offset:49152
	ds_read_b128 v[180:183], v143 offset:50176
	ds_read_b128 v[184:187], v143 offset:51200
	ds_read_b128 v[188:191], v143 offset:52224
	ds_read_b128 v[192:195], v143 offset:53248
	ds_read_b128 v[196:199], v143 offset:54272
	ds_read_b128 v[200:203], v143 offset:55296
	ds_read_b128 v[204:207], v143 offset:56320
	global_load_lds_dwordx4 v[208:209], off
	s_add_i32 m0, s18, 0x2000
	s_add_u32 s16, s16, 0x158080
	v_lshl_add_u64 v[208:209], v[210:211], 0, s[82:83]
	s_addc_u32 s17, s17, 0
	s_add_i32 s18, s51, s24
	global_load_lds_dwordx4 v[208:209], off
	v_lshl_add_u64 v[208:209], s[16:17], 0, v[132:133]
	s_mov_b32 m0, s18
	s_nop 0
	global_load_lds_dwordx4 v[208:209], off
	v_lshl_add_u64 v[208:209], s[16:17], 0, v[136:137]
	s_add_i32 m0, s18, 0x2000
	s_nop 0
	global_load_lds_dwordx4 v[208:209], off
	v_lshl_add_u64 v[208:209], v[212:213], 0, s[82:83]
	s_mov_b32 m0, s40
	s_nop 0
	global_load_lds_dwordx4 v[208:209], off
	v_lshl_add_u64 v[208:209], v[214:215], 0, s[82:83]
	s_mov_b32 m0, s41
	s_nop 0
	global_load_lds_dwordx4 v[208:209], off
	s_waitcnt vmcnt(8)
	s_waitcnt lgkmcnt(0)
	s_barrier
	s_waitcnt lgkmcnt(0)
	v_mfma_f32_16x16x32_bf16 v[62:65], v[144:147], v[176:179], v[62:65]
	v_mfma_f32_16x16x32_bf16 v[58:61], v[152:155], v[176:179], v[58:61]
	v_mfma_f32_16x16x32_bf16 v[46:49], v[144:147], v[184:187], v[46:49]
	v_mfma_f32_16x16x32_bf16 v[38:41], v[152:155], v[184:187], v[38:41]
	v_mfma_f32_16x16x32_bf16 v[22:25], v[144:147], v[192:195], v[22:25]
	v_mfma_f32_16x16x32_bf16 v[14:17], v[152:155], v[192:195], v[14:17]
	v_mfma_f32_16x16x32_bf16 v[6:9], v[144:147], v[200:203], v[6:9]
	v_mfma_f32_16x16x32_bf16 v[2:5], v[152:155], v[200:203], v[2:5]
	v_mfma_f32_16x16x32_bf16 v[62:65], v[148:151], v[180:183], v[62:65]
	v_mfma_f32_16x16x32_bf16 v[58:61], v[156:159], v[180:183], v[58:61]
	v_mfma_f32_16x16x32_bf16 v[46:49], v[148:151], v[188:191], v[46:49]
	v_mfma_f32_16x16x32_bf16 v[38:41], v[156:159], v[188:191], v[38:41]
	v_mfma_f32_16x16x32_bf16 v[22:25], v[148:151], v[196:199], v[22:25]
	v_mfma_f32_16x16x32_bf16 v[14:17], v[156:159], v[196:199], v[14:17]
	v_mfma_f32_16x16x32_bf16 v[6:9], v[148:151], v[204:207], v[6:9]
	v_mfma_f32_16x16x32_bf16 v[2:5], v[156:159], v[204:207], v[2:5]
	v_mfma_f32_16x16x32_bf16 v[42:45], v[160:163], v[176:179], v[42:45]
	v_mfma_f32_16x16x32_bf16 v[34:37], v[168:171], v[176:179], v[34:37]
	v_mfma_f32_16x16x32_bf16 v[18:21], v[160:163], v[184:187], v[18:21]
	v_mfma_f32_16x16x32_bf16 v[10:13], v[168:171], v[184:187], v[10:13]
	v_mfma_f32_16x16x32_bf16 v[54:57], v[160:163], v[192:195], v[54:57]
	v_mfma_f32_16x16x32_bf16 v[50:53], v[168:171], v[192:195], v[50:53]
	v_mfma_f32_16x16x32_bf16 v[30:33], v[160:163], v[200:203], v[30:33]
	v_mfma_f32_16x16x32_bf16 v[26:29], v[168:171], v[200:203], v[26:29]
	v_mfma_f32_16x16x32_bf16 v[42:45], v[164:167], v[180:183], v[42:45]
	v_mfma_f32_16x16x32_bf16 v[34:37], v[172:175], v[180:183], v[34:37]
	v_mfma_f32_16x16x32_bf16 v[18:21], v[164:167], v[188:191], v[18:21]
	v_mfma_f32_16x16x32_bf16 v[10:13], v[172:175], v[188:191], v[10:13]
	v_mfma_f32_16x16x32_bf16 v[54:57], v[164:167], v[196:199], v[54:57]
	v_mfma_f32_16x16x32_bf16 v[50:53], v[172:175], v[196:199], v[50:53]
	v_mfma_f32_16x16x32_bf16 v[30:33], v[164:167], v[204:207], v[30:33]
	v_mfma_f32_16x16x32_bf16 v[26:29], v[172:175], v[204:207], v[26:29]
	s_barrier
	s_add_i32 s76, s76, 2
	s_add_u32 s4, s4, 0x100
	s_addc_u32 s5, s5, 0
	s_add_u32 s61, s61, 0x100
	s_addc_u32 s64, s64, 0
	s_cmpk_gt_u32 s76, 0x53
	s_cbranch_scc0 .LBB0_1133
	s_and_b64 vcc, exec, s[6:7]
	s_cbranch_vccz .LBB0_1136
	s_barrier

; #define GRID_SYNC() do { asm volatile("s_waitcnt vmcnt(0) lgkmcnt(0)" ::: "memory"); { XcdBarrier xb_; xb_.bar = (unsigned*)(get_params()->ws + WS_CTL) + CW_BAR; xb_.x = xb_xcc_id(); xb_.st = (volatile LAS unsigned*)(lds + 131072 + 64); xcd_barrier(xb_); } asm volatile("" ::: "memory"); } while (0)
; __device__ __forceinline__ void xcd_barrier(const XcdBarrier& b) {
;     asm volatile("s_waitcnt vmcnt(0)" ::: "memory");
;     __syncthreads();
;     if (threadIdx.x == 0) {
;         unsigned* bar = b.bar;
;         __builtin_amdgcn_s_waitcnt(0);
;         unsigned nloc = b.st[0], nx = b.st[1];
;         if (nloc == 0u) { xcd_barrier_complete(bar, b.x, nloc, nx); b.st[0] = nloc; b.st[1] = nx; }
; __global__ void __launch_bounds__(512) fwd_kernel(Params p_unused) {
;     ...
;         if (layer == 0) {
;             GRID_SYNC();
.LBB0_1140:
	v_readlane_b32 s0, v254, 62
	v_readlane_b32 s1, v254, 63
	s_and_b64 vcc, exec, s[0:1]
	s_mov_b64 s[0:1], -1
	s_cbranch_vccnz .LBB0_20
	s_mov_b64 s[4:5], s[66:67]
	s_waitcnt vmcnt(0) lgkmcnt(0)
	s_setprio 0
	s_getreg_b32 s6, hwreg(HW_REG_XCC_ID, 0, 4)
	s_waitcnt vmcnt(0)
	s_waitcnt lgkmcnt(0)
	s_barrier
	s_and_saveexec_b64 s[0:1], s[26:27]
	s_cbranch_execz .LBB0_1193
	v_mov_b32_e32 v0, s96
	s_load_dwordx2 s[4:5], s[4:5], 0xc0
	s_waitcnt vmcnt(0) expcnt(0) lgkmcnt(0)
	ds_read_b32 v3, v0
	v_mov_b32_e32 v0, s97
	ds_read_b32 v2, v0
	s_and_b32 s30, s6, 15
	s_waitcnt lgkmcnt(1)
	v_cmp_ne_u32_e32 vcc, 0, v3
	s_cbranch_vccnz .LBB0_1157
	s_add_u32 s6, s4, 0x1200
	s_addc_u32 s7, s5, 0
	s_add_u32 s8, s4, 0x1400
	s_addc_u32 s9, s5, 0
	s_add_u32 s10, s4, 0x1500
	s_addc_u32 s11, s5, 0
	s_add_u32 s12, s4, 0x1600
	s_addc_u32 s13, s5, 0
	s_add_u32 s14, s4, 0x1700
	s_addc_u32 s15, s5, 0
	s_add_u32 s16, s4, 0x1800
	s_addc_u32 s17, s5, 0
	s_add_u32 s18, s4, 0x1900
	s_addc_u32 s19, s5, 0
	s_add_u32 s20, s4, 0x1a00
	s_addc_u32 s21, s5, 0
	s_add_u32 s22, s4, 0x1b00
	s_addc_u32 s23, s5, 0
	s_add_u32 s24, s4, 0x1c00
	s_addc_u32 s25, s5, 0
	s_add_u32 s38, s4, 0x1d00
	s_addc_u32 s39, s5, 0
	s_add_u32 s48, s4, 0x1e00
	s_addc_u32 s49, s5, 0
	s_add_u32 s52, s4, 0x1f00
	s_addc_u32 s53, s5, 0
	s_add_u32 s60, s4, 0x2000
	s_addc_u32 s61, s5, 0
	s_add_u32 s76, s4, 0x2100
	s_addc_u32 s77, s5, 0
	s_add_u32 s78, s4, 0x2200
	s_addc_u32 s79, s5, 0
	s_add_u32 s80, s4, 0x2300
	s_addc_u32 s81, s5, 0
	s_mov_b32 s35, 1
	s_branch .LBB0_1145

; #define PG8_STAGE(bufoff, gbase, rows) do { _Pragma("unroll") for (int _i = 0; _i < 2; ++_i) \
;         __builtin_amdgcn_global_load_lds((const unsigned*)((const char*)(gbase) + (rows)[_i]), (LAS unsigned*)(lds + (bufoff) + ldsw + _i * 8192), 16, 0, 0); } while (0)
; #define PG8_BAR __builtin_amdgcn_s_barrier()
; template <class Epi, class Sched>
; __device__ __forceinline__ void gemm_phase(LAS unsigned char* lds, const Sched& S, const Epi& E, const int tid) {
;     const int wid = __builtin_amdgcn_readfirstlane(tid >> 6), lane = tid & 63, wr = wid >> 2, wc = wid & 3, fr = lane & 15, fq = lane >> 4;
;     int sR[2], sC[2], sRbi[2];
; #pragma unroll
;     for (int i = 0; i < 2; ++i) { stage_rc(tid * 16 + i * 8192, sR[i], sC[i]); sRbi[i] = (sR[i] & ~31) + perm32(sR[i] & 31); }
;     const unsigned ldsw = (unsigned)wid * 1024u;
;     const int aoff = lds_byte(wr * 64 + fr, fq * 8), boff = lds_byte(wc * 32 + fr, fq * 8);
;     ...
;     GUnit cur, nxt; int ui = 0;
;     if (!S.next(0, cur)) return;
;     f32x4 acc[2][2][4][2];
; #pragma unroll
;     for (int a = 0; a < 2; ++a)
; #pragma unroll
;         for (int b = 0; b < 2; ++b)
; #pragma unroll
;             for (int m = 0; m < 4; ++m)
; #pragma unroll
;                 for (int n = 0; n < 2; ++n) acc[a][b][m][n] = (f32x4){0.f, 0.f, 0.f, 0.f};
;     bf16x8 At[4][2], B0[2][2], B1[2][2];
;     const char* cA = cur.A; const char* cB = cur.B;
;     constexpr unsigned kstep = (unsigned)(BK * 2);
;     const unsigned lda = cur.lda, ldb = cur.ldb, hA = HALF * lda, hB = HALF * ldb;
;     unsigned vA[2], vB[2];
; #pragma unroll
;     for (int i = 0; i < 2; ++i) { vA[i] = (unsigned)sR[i] * lda + (unsigned)sC[i] * 2u; vB[i] = (unsigned)sRbi[i] * ldb + (unsigned)sC[i] * 2u; }
;     PG8_STAGE(PG8_SB(0, 0), cB, vB); PG8_STAGE(PG8_SB(0, 1), cB + hB, vB); PG8_STAGE(PG8_SA(0, 0), cA, vA); PG8_STAGE(PG8_SA(0, 1), cA + hA, vA);
;     if (wr == 1) PG8_BAR;
.LBB0_1239:
	s_andn2_b64 vcc, exec, s[4:5]
	s_cbranch_vccnz .LBB0_1255
	v_bfe_i32 v3, v19, 27, 1
	v_lshlrev_b32_e32 v2, 4, v19
	v_lshrrev_b32_e32 v3, 22, v3
	v_add_u32_e32 v3, v2, v3
	v_and_b32_e32 v3, 0xfffffc00, v3
	v_sub_u32_e32 v3, v2, v3
	v_lshrrev_b32_e32 v4, 4, v3
	v_ashrrev_i32_e32 v0, 31, v19
	v_bitop3_b32 v3, v4, v3, 32 bitop3:0x6c
	v_lshrrev_b32_e32 v0, 26, v0
	v_ashrrev_i32_e32 v5, 31, v3
	v_add_u32_e32 v0, v19, v0
	v_lshrrev_b32_e32 v5, 26, v5
	v_ashrrev_i32_e32 v0, 6, v0
	v_add_u32_e32 v5, v3, v5
	v_lshlrev_b32_e32 v4, 3, v0
	v_ashrrev_i32_e32 v10, 6, v5
	v_and_b32_e32 v5, 0xc0, v5
	v_and_b32_e32 v4, -16, v4
	v_sub_u32_e32 v3, v3, v5
	v_add_u32_e32 v4, v10, v4
	v_ashrrev_i16_sdwa v3, v231, sext(v3) dst_sel:DWORD dst_unused:UNUSED_PAD src0_sel:DWORD src1_sel:BYTE_0
	s_load_dwordx4 s[4:7], s[0:1], 0xb8
	v_bfe_i32 v11, v3, 0, 16
	v_lshlrev_b32_e32 v3, 1, v4
	v_lshrrev_b32_e32 v5, 2, v4
	v_and_b32_e32 v7, 3, v10
	s_mov_b32 s0, 0xffffe0
	v_and_b32_e32 v3, 24, v3
	v_and_b32_e32 v5, 4, v5
	v_and_or_b32 v7, v4, s0, v7
	v_add_u32_e32 v2, 0x2000, v2
	v_or3_b32 v3, v7, v5, v3
	v_ashrrev_i32_e32 v5, 31, v2
	v_lshrrev_b32_e32 v5, 22, v5
	v_add_u32_e32 v5, v2, v5
	v_ashrrev_i32_e32 v12, 10, v5
	v_mul_i32_i24_e32 v5, 0x400, v12
	v_sub_u32_e32 v2, v2, v5
	v_lshrrev_b32_e32 v5, 4, v2
	v_bitop3_b32 v2, v5, v2, 32 bitop3:0x6c
	v_ashrrev_i32_e32 v7, 31, v2
	v_lshrrev_b32_e32 v7, 26, v7
	s_waitcnt lgkmcnt(0)
	s_add_u32 s20, s6, 0x28030000
	v_lshlrev_b32_e32 v5, 3, v12
	v_add_u32_e32 v7, v2, v7
	s_addc_u32 s21, s7, 0
	v_and_b32_e32 v5, -16, v5
	v_ashrrev_i32_e32 v13, 6, v7
	v_readfirstlane_b32 s8, v19
	s_add_u32 s22, s6, 0x8f00000
	v_add_u32_e32 v5, v13, v5
	v_and_b32_e32 v9, 3, v13
	s_addc_u32 s23, s7, 0
	v_and_b32_e32 v7, 0xc0, v7
	v_and_or_b32 v9, v5, s0, v9
	s_ashr_i32 s10, s8, 6
	v_readlane_b32 s0, v254, 32
	s_ashr_i32 s9, s8, 8
	v_sub_u32_e32 v2, v2, v7
	s_lshl_b32 s24, s10, 10
	s_mov_b32 s12, s0
	s_mul_i32 s0, s0, 0x2b0000
	v_ashrrev_i16_sdwa v2, v231, sext(v2) dst_sel:DWORD dst_unused:UNUSED_PAD src0_sel:DWORD src1_sel:BYTE_0
	s_add_u32 s14, s20, s0
	s_mul_hi_i32 s0, s12, 0x2b0000
	v_lshlrev_b32_e32 v6, 5, v0
	v_bfe_i32 v14, v2, 0, 16
	v_lshlrev_b32_e32 v2, 1, v5
	v_lshrrev_b32_e32 v7, 2, v5
	s_addc_u32 s15, s21, s0
	v_readlane_b32 s0, v254, 41
	v_and_b32_e32 v6, 32, v6
	v_lshlrev_b32_e32 v8, 5, v12
	v_and_b32_e32 v2, 24, v2
	v_and_b32_e32 v7, 4, v7
	s_add_u32 s16, s22, s0
	v_readlane_b32 s0, v254, 40
	v_and_b32_e32 v8, 32, v8
	v_or3_b32 v7, v9, v7, v2
	v_readlane_b32 s1, v254, 33
	s_addc_u32 s17, s23, s0
	v_add_lshl_u32 v2, v6, v11, 1
	s_add_i32 s25, s24, 0
	v_mad_u64_u32 v[130:131], s[0:1], v4, s65, v[2:3]
	v_mad_u32_u24 v132, v3, s65, v2
	v_add_lshl_u32 v2, v8, v14, 1
	s_add_i32 m0, s25, 0x10000
	v_mad_u64_u32 v[134:135], s[0:1], v5, s65, v[2:3]
	global_load_lds_dwordx4 v132, s[16:17]
	s_add_i32 m0, s25, 0x12000
	v_mad_u32_u24 v136, v7, s65, v2
	s_add_u32 s0, s16, 0x158000
	global_load_lds_dwordx4 v136, s[16:17]
	s_addc_u32 s1, s17, 0
	s_add_i32 m0, s25, 0x14000
	s_add_i32 s30, s25, 0x2000
	global_load_lds_dwordx4 v132, s[0:1]
	s_add_i32 m0, s25, 0x16000
	v_mov_b32_e32 v133, v1
	global_load_lds_dwordx4 v136, s[0:1]
	s_mov_b32 m0, s25
	s_add_u32 s0, s14, 0x158000
	global_load_lds_dwordx4 v130, s[14:15]
	s_mov_b32 m0, s30
	s_addc_u32 s1, s15, 0
	s_add_i32 s35, s25, 0x4000
	global_load_lds_dwordx4 v134, s[14:15]
	s_mov_b32 m0, s35
	s_add_i32 s37, s25, 0x6000
	global_load_lds_dwordx4 v130, s[0:1]
	s_mov_b32 m0, s37
	v_mov_b32_e32 v137, v1
	global_load_lds_dwordx4 v134, s[0:1]
	v_mov_b32_e32 v131, v1
	v_mov_b32_e32 v135, v1
	s_cmp_eq_u32 s9, 1
	v_lshl_add_u64 v[8:9], s[16:17], 0, v[132:133]
	v_lshl_add_u64 v[6:7], s[16:17], 0, v[136:137]
	v_lshl_add_u64 v[2:3], s[14:15], 0, v[130:131]
	s_cselect_b64 s[0:1], -1, 0
	s_cmp_lg_u32 s9, 1
	v_lshl_add_u64 v[4:5], s[14:15], 0, v[134:135]
	s_cbranch_scc1 .LBB0_1242
	s_setprio 1
	s_barrier

; #define PG8_STAGE(bufoff, gbase, rows) do { _Pragma("unroll") for (int _i = 0; _i < 2; ++_i) \
;         __builtin_amdgcn_global_load_lds((const unsigned*)((const char*)(gbase) + (rows)[_i]), (LAS unsigned*)(lds + (bufoff) + ldsw + _i * 8192), 16, 0, 0); } while (0)
; #define PG8_LDA(dst, b, h) do { _Pragma("unroll") for (int m = 0; m < 4; ++m) _Pragma("unroll") for (int k = 0; k < 2; ++k) dst[m][k] = *(const LAS bf16x8*)(lds + PG8_SA(b, h) + aoff + m * 2048 + k * 1024); } while (0)
; #define PG8_LDB(dst, b, h) do { _Pragma("unroll") for (int n = 0; n < 2; ++n) _Pragma("unroll") for (int k = 0; k < 2; ++k) dst[n][k] = *(const LAS bf16x8*)(lds + PG8_SB(b, h) + boff + n * 2048 + k * 1024); } while (0)
; #define PG8_MMA(ai, bj, At, Bt) do { __builtin_amdgcn_s_setprio(1); _Pragma("unroll") for (int m = 0; m < 4; ++m) _Pragma("unroll") for (int n = 0; n < 2; ++n) _Pragma("unroll") for (int k = 0; k < 2; ++k) \
;         acc[ai][bj][m][n] = __builtin_amdgcn_mfma_f32_16x16x32_bf16(Bt[n][k], At[m][k], acc[ai][bj][m][n], 0, 0, 0); __builtin_amdgcn_s_setprio(0); } while (0)
; #define PG8_WAIT_V(n) asm volatile("s_waitcnt vmcnt(" #n ")" ::: "memory")
; #define PG8_WAIT_L(n) asm volatile("s_waitcnt lgkmcnt(" #n ")" ::: "memory")
; #define PG8_BAR __builtin_amdgcn_s_barrier()
; #define PG8_SCHED __builtin_amdgcn_sched_barrier(0)
; template <class Epi, class Sched>
; __device__ __forceinline__ void gemm_phase(LAS unsigned char* lds, const Sched& S, const Epi& E, const int tid) {
;     ...
;             const bool last = (t == nt - 2);
;             const char* a1 = cA + (size_t)(t + 1) * kstep;
;             const char* a2 = last ? nA : cA + (size_t)(t + 2) * kstep; const char* b2 = last ? nB : cB + (size_t)(t + 2) * kstep;
;             const char* a3 = a2 + kstep; const char* b3 = b2 + kstep;
;             PG8_LDB(B0, 0, 0); PG8_LDB(B1, 0, 1); PG8_SCHED; PG8_LDA(At, 0, 0); PG8_STAGE(PG8_SA(1, 1), a1 + hA, vA);
;             PG8_WAIT_V(8); PG8_WAIT_L(0); PG8_BAR; PG8_MMA(0, 0, At, B0); PG8_MMA(0, 1, At, B1); PG8_BAR; PG8_SCHED;
;             PG8_LDA(At, 0, 1); PG8_STAGE(PG8_SB(0, 0), b2, vB); PG8_STAGE(PG8_SB(0, 1), b2 + hB, vB); PG8_STAGE(PG8_SA(0, 0), a2, vA);
;             PG8_WAIT_V(8); PG8_WAIT_L(0); PG8_BAR; PG8_MMA(1, 0, At, B0); PG8_MMA(1, 1, At, B1); PG8_BAR; PG8_SCHED;
.LBB0_1248:
	s_add_u32 s16, s14, 0xffea8080
	s_addc_u32 s17, s15, -1
	s_add_i32 s50, 0, 0x10000
	s_cmpk_eq_i32 s76, 0x52
	s_cselect_b32 s19, s9, s17
	s_cselect_b32 s18, s8, s16
	v_add_u32_e32 v0, s50, v142
	s_cselect_b32 s17, s13, s64
	s_cselect_b32 s16, s12, s61
	s_add_i32 s51, 0, 0x14000
	ds_read_b128 v[144:147], v0
	ds_read_b128 v[148:151], v0 offset:1024
	ds_read_b128 v[152:155], v0 offset:2048
	ds_read_b128 v[156:159], v0 offset:3072
	v_add_u32_e32 v0, s51, v142
	ds_read_b128 v[160:163], v0
	ds_read_b128 v[164:167], v0 offset:1024
	ds_read_b128 v[168:171], v0 offset:2048
	ds_read_b128 v[172:175], v0 offset:3072
	v_lshl_add_u64 v[208:209], s[14:15], 0, v[138:139]
	s_add_i32 m0, s25, 0xc000
	ds_read_b128 v[176:179], v143
	ds_read_b128 v[180:183], v143 offset:1024
	ds_read_b128 v[184:187], v143 offset:2048
	ds_read_b128 v[188:191], v143 offset:3072
	ds_read_b128 v[192:195], v143 offset:4096
	ds_read_b128 v[196:199], v143 offset:5120
	ds_read_b128 v[200:203], v143 offset:6144
	ds_read_b128 v[204:207], v143 offset:7168
	global_load_lds_dwordx4 v[208:209], off
	v_lshl_add_u64 v[208:209], s[14:15], 0, v[140:141]
	s_add_i32 m0, s25, 0xe000
	s_nop 0
	global_load_lds_dwordx4 v[208:209], off
	s_waitcnt vmcnt(8)
	s_waitcnt lgkmcnt(0)
	s_barrier
	s_waitcnt lgkmcnt(0)
	v_mfma_f32_16x16x32_bf16 v[126:129], v[144:147], v[176:179], v[126:129]
	v_mfma_f32_16x16x32_bf16 v[122:125], v[152:155], v[176:179], v[122:125]
	v_mfma_f32_16x16x32_bf16 v[114:117], v[144:147], v[184:187], v[114:117]
	v_mfma_f32_16x16x32_bf16 v[106:109], v[152:155], v[184:187], v[106:109]
	v_mfma_f32_16x16x32_bf16 v[102:105], v[144:147], v[192:195], v[102:105]
	v_mfma_f32_16x16x32_bf16 v[94:97], v[152:155], v[192:195], v[94:97]
	v_mfma_f32_16x16x32_bf16 v[86:89], v[144:147], v[200:203], v[86:89]
	v_mfma_f32_16x16x32_bf16 v[78:81], v[152:155], v[200:203], v[78:81]
	v_mfma_f32_16x16x32_bf16 v[126:129], v[148:151], v[180:183], v[126:129]
	v_mfma_f32_16x16x32_bf16 v[122:125], v[156:159], v[180:183], v[122:125]
	v_mfma_f32_16x16x32_bf16 v[114:117], v[148:151], v[188:191], v[114:117]
	v_mfma_f32_16x16x32_bf16 v[106:109], v[156:159], v[188:191], v[106:109]
	v_mfma_f32_16x16x32_bf16 v[102:105], v[148:151], v[196:199], v[102:105]
	v_mfma_f32_16x16x32_bf16 v[94:97], v[156:159], v[196:199], v[94:97]
	v_mfma_f32_16x16x32_bf16 v[86:89], v[148:151], v[204:207], v[86:89]
	v_mfma_f32_16x16x32_bf16 v[78:81], v[156:159], v[204:207], v[78:81]
	v_mfma_f32_16x16x32_bf16 v[118:121], v[160:163], v[176:179], v[118:121]
	v_mfma_f32_16x16x32_bf16 v[110:113], v[168:171], v[176:179], v[110:113]
	v_mfma_f32_16x16x32_bf16 v[98:101], v[160:163], v[184:187], v[98:101]
	v_mfma_f32_16x16x32_bf16 v[90:93], v[168:171], v[184:187], v[90:93]
	v_mfma_f32_16x16x32_bf16 v[82:85], v[160:163], v[192:195], v[82:85]
	v_mfma_f32_16x16x32_bf16 v[74:77], v[168:171], v[192:195], v[74:77]
	v_mfma_f32_16x16x32_bf16 v[70:73], v[160:163], v[200:203], v[70:73]
	v_mfma_f32_16x16x32_bf16 v[66:69], v[168:171], v[200:203], v[66:69]
	v_mfma_f32_16x16x32_bf16 v[118:121], v[164:167], v[180:183], v[118:121]
	v_mfma_f32_16x16x32_bf16 v[110:113], v[172:175], v[180:183], v[110:113]
	v_mfma_f32_16x16x32_bf16 v[98:101], v[164:167], v[188:191], v[98:101]
	v_mfma_f32_16x16x32_bf16 v[90:93], v[172:175], v[188:191], v[90:93]
	v_mfma_f32_16x16x32_bf16 v[82:85], v[164:167], v[196:199], v[82:85]
	v_mfma_f32_16x16x32_bf16 v[74:77], v[172:175], v[196:199], v[74:77]
	v_mfma_f32_16x16x32_bf16 v[70:73], v[164:167], v[204:207], v[70:73]
	v_mfma_f32_16x16x32_bf16 v[66:69], v[172:175], v[204:207], v[66:69]
	s_barrier
	s_add_i32 s50, s50, s24
	v_lshl_add_u64 v[208:209], s[16:17], 0, v[132:133]
	s_mov_b32 m0, s50
	ds_read_b128 v[176:179], v143 offset:16384
	ds_read_b128 v[180:183], v143 offset:17408
	ds_read_b128 v[184:187], v143 offset:18432
	ds_read_b128 v[188:191], v143 offset:19456
	ds_read_b128 v[192:195], v143 offset:20480
	ds_read_b128 v[196:199], v143 offset:21504
	ds_read_b128 v[200:203], v143 offset:22528
	ds_read_b128 v[204:207], v143 offset:23552
	global_load_lds_dwordx4 v[208:209], off
	s_add_i32 m0, s50, 0x2000
	s_add_u32 s78, s16, 0x158000
	v_lshl_add_u64 v[210:211], s[16:17], 0, v[136:137]
	s_addc_u32 s79, s17, 0
	s_add_i32 s50, s51, s24
	global_load_lds_dwordx4 v[210:211], off
	v_lshl_add_u64 v[212:213], s[78:79], 0, v[132:133]
	s_mov_b32 m0, s50
	v_lshl_add_u64 v[214:215], s[18:19], 0, v[134:135]
	global_load_lds_dwordx4 v[212:213], off
	v_lshl_add_u64 v[212:213], s[78:79], 0, v[136:137]
	s_add_i32 m0, s50, 0x2000
	s_nop 0
	global_load_lds_dwordx4 v[212:213], off
	v_lshl_add_u64 v[212:213], s[18:19], 0, v[130:131]
	s_mov_b32 m0, s25
	s_nop 0
	global_load_lds_dwordx4 v[212:213], off
	s_mov_b32 m0, s30
	s_nop 0
	global_load_lds_dwordx4 v[214:215], off
	s_waitcnt vmcnt(8)
	s_waitcnt lgkmcnt(0)
	s_barrier
; #define PG8_STAGE(bufoff, gbase, rows) do { _Pragma("unroll") for (int _i = 0; _i < 2; ++_i) \
;         __builtin_amdgcn_global_load_lds((const unsigned*)((const char*)(gbase) + (rows)[_i]), (LAS unsigned*)(lds + (bufoff) + ldsw + _i * 8192), 16, 0, 0); } while (0)
; #define PG8_LDA(dst, b, h) do { _Pragma("unroll") for (int m = 0; m < 4; ++m) _Pragma("unroll") for (int k = 0; k < 2; ++k) dst[m][k] = *(const LAS bf16x8*)(lds + PG8_SA(b, h) + aoff + m * 2048 + k * 1024); } while (0)
; #define PG8_LDB(dst, b, h) do { _Pragma("unroll") for (int n = 0; n < 2; ++n) _Pragma("unroll") for (int k = 0; k < 2; ++k) dst[n][k] = *(const LAS bf16x8*)(lds + PG8_SB(b, h) + boff + n * 2048 + k * 1024); } while (0)
; #define PG8_MMA(ai, bj, At, Bt) do { __builtin_amdgcn_s_setprio(1); _Pragma("unroll") for (int m = 0; m < 4; ++m) _Pragma("unroll") for (int n = 0; n < 2; ++n) _Pragma("unroll") for (int k = 0; k < 2; ++k) \
;         acc[ai][bj][m][n] = __builtin_amdgcn_mfma_f32_16x16x32_bf16(Bt[n][k], At[m][k], acc[ai][bj][m][n], 0, 0, 0); __builtin_amdgcn_s_setprio(0); } while (0)
; #define PG8_WAIT_V(n) asm volatile("s_waitcnt vmcnt(" #n ")" ::: "memory")
; #define PG8_WAIT_L(n) asm volatile("s_waitcnt lgkmcnt(" #n ")" ::: "memory")
; #define PG8_BAR __builtin_amdgcn_s_barrier()
; #define PG8_SCHED __builtin_amdgcn_sched_barrier(0)
; template <class Epi, class Sched>
; __device__ __forceinline__ void gemm_phase(LAS unsigned char* lds, const Sched& S, const Epi& E, const int tid) {
;     ...
;             PG8_WAIT_V(8); PG8_WAIT_L(0); PG8_BAR; PG8_MMA(1, 0, At, B0); PG8_MMA(1, 1, At, B1); PG8_BAR; PG8_SCHED;
;             PG8_LDB(B0, 1, 0); PG8_LDB(B1, 1, 1); PG8_SCHED; PG8_LDA(At, 1, 0); PG8_STAGE(PG8_SA(0, 1), a2 + hA, vA);
;             PG8_WAIT_V(8); PG8_WAIT_L(0); PG8_BAR; PG8_MMA(0, 0, At, B0); PG8_MMA(0, 1, At, B1); PG8_BAR; PG8_SCHED;
	s_waitcnt lgkmcnt(0)
	v_mfma_f32_16x16x32_bf16 v[62:65], v[144:147], v[176:179], v[62:65]
	v_mfma_f32_16x16x32_bf16 v[58:61], v[152:155], v[176:179], v[58:61]
	v_mfma_f32_16x16x32_bf16 v[46:49], v[144:147], v[184:187], v[46:49]
	v_mfma_f32_16x16x32_bf16 v[38:41], v[152:155], v[184:187], v[38:41]
	v_mfma_f32_16x16x32_bf16 v[22:25], v[144:147], v[192:195], v[22:25]
	v_mfma_f32_16x16x32_bf16 v[14:17], v[152:155], v[192:195], v[14:17]
	v_mfma_f32_16x16x32_bf16 v[6:9], v[144:147], v[200:203], v[6:9]
	v_mfma_f32_16x16x32_bf16 v[2:5], v[152:155], v[200:203], v[2:5]
	v_mfma_f32_16x16x32_bf16 v[62:65], v[148:151], v[180:183], v[62:65]
	v_mfma_f32_16x16x32_bf16 v[58:61], v[156:159], v[180:183], v[58:61]
	v_mfma_f32_16x16x32_bf16 v[46:49], v[148:151], v[188:191], v[46:49]
	v_mfma_f32_16x16x32_bf16 v[38:41], v[156:159], v[188:191], v[38:41]
	v_mfma_f32_16x16x32_bf16 v[22:25], v[148:151], v[196:199], v[22:25]
	v_mfma_f32_16x16x32_bf16 v[14:17], v[156:159], v[196:199], v[14:17]
	v_mfma_f32_16x16x32_bf16 v[6:9], v[148:151], v[204:207], v[6:9]
	v_mfma_f32_16x16x32_bf16 v[2:5], v[156:159], v[204:207], v[2:5]
	v_mfma_f32_16x16x32_bf16 v[42:45], v[160:163], v[176:179], v[42:45]
	v_mfma_f32_16x16x32_bf16 v[34:37], v[168:171], v[176:179], v[34:37]
	v_mfma_f32_16x16x32_bf16 v[18:21], v[160:163], v[184:187], v[18:21]
	v_mfma_f32_16x16x32_bf16 v[10:13], v[168:171], v[184:187], v[10:13]
	v_mfma_f32_16x16x32_bf16 v[54:57], v[160:163], v[192:195], v[54:57]
	v_mfma_f32_16x16x32_bf16 v[50:53], v[168:171], v[192:195], v[50:53]
	v_mfma_f32_16x16x32_bf16 v[30:33], v[160:163], v[200:203], v[30:33]
	v_mfma_f32_16x16x32_bf16 v[26:29], v[168:171], v[200:203], v[26:29]
	v_mfma_f32_16x16x32_bf16 v[42:45], v[164:167], v[180:183], v[42:45]
	v_mfma_f32_16x16x32_bf16 v[34:37], v[172:175], v[180:183], v[34:37]
	v_mfma_f32_16x16x32_bf16 v[18:21], v[164:167], v[188:191], v[18:21]
	v_mfma_f32_16x16x32_bf16 v[10:13], v[172:175], v[188:191], v[10:13]
	v_mfma_f32_16x16x32_bf16 v[54:57], v[164:167], v[196:199], v[54:57]
	v_mfma_f32_16x16x32_bf16 v[50:53], v[172:175], v[196:199], v[50:53]
	v_mfma_f32_16x16x32_bf16 v[30:33], v[164:167], v[204:207], v[30:33]
	v_mfma_f32_16x16x32_bf16 v[26:29], v[172:175], v[204:207], v[26:29]
	s_barrier
	s_add_i32 s50, 0, 0x18000
	v_add_u32_e32 v0, s50, v142
	s_add_i32 s51, 0, 0x1c000
	ds_read_b128 v[144:147], v0
	ds_read_b128 v[148:151], v0 offset:1024
	ds_read_b128 v[152:155], v0 offset:2048
	ds_read_b128 v[156:159], v0 offset:3072
	v_add_u32_e32 v0, s51, v142
	ds_read_b128 v[160:163], v0
	ds_read_b128 v[164:167], v0 offset:1024
	ds_read_b128 v[168:171], v0 offset:2048
	ds_read_b128 v[172:175], v0 offset:3072
	s_add_u32 s18, s18, 0x158000
	s_addc_u32 s19, s19, 0
	s_mov_b32 m0, s35
	v_lshl_add_u64 v[216:217], s[18:19], 0, v[130:131]
	ds_read_b128 v[176:179], v143 offset:32768
	ds_read_b128 v[180:183], v143 offset:33792
	ds_read_b128 v[184:187], v143 offset:34816
	ds_read_b128 v[188:191], v143 offset:35840
	ds_read_b128 v[192:195], v143 offset:36864
	ds_read_b128 v[196:199], v143 offset:37888
	ds_read_b128 v[200:203], v143 offset:38912
	ds_read_b128 v[204:207], v143 offset:39936
	global_load_lds_dwordx4 v[216:217], off
	v_lshl_add_u64 v[216:217], s[18:19], 0, v[134:135]
	s_mov_b32 m0, s37
	s_nop 0
	global_load_lds_dwordx4 v[216:217], off
	s_waitcnt vmcnt(8)
	s_waitcnt lgkmcnt(0)
	s_barrier
	s_waitcnt lgkmcnt(0)
	v_mfma_f32_16x16x32_bf16 v[126:129], v[144:147], v[176:179], v[126:129]
	v_mfma_f32_16x16x32_bf16 v[122:125], v[152:155], v[176:179], v[122:125]
	v_mfma_f32_16x16x32_bf16 v[114:117], v[144:147], v[184:187], v[114:117]
	v_mfma_f32_16x16x32_bf16 v[106:109], v[152:155], v[184:187], v[106:109]
	v_mfma_f32_16x16x32_bf16 v[102:105], v[144:147], v[192:195], v[102:105]
	v_mfma_f32_16x16x32_bf16 v[94:97], v[152:155], v[192:195], v[94:97]
	v_mfma_f32_16x16x32_bf16 v[86:89], v[144:147], v[200:203], v[86:89]
	v_mfma_f32_16x16x32_bf16 v[78:81], v[152:155], v[200:203], v[78:81]
	v_mfma_f32_16x16x32_bf16 v[126:129], v[148:151], v[180:183], v[126:129]
	v_mfma_f32_16x16x32_bf16 v[122:125], v[156:159], v[180:183], v[122:125]
	v_mfma_f32_16x16x32_bf16 v[114:117], v[148:151], v[188:191], v[114:117]
	v_mfma_f32_16x16x32_bf16 v[106:109], v[156:159], v[188:191], v[106:109]
	v_mfma_f32_16x16x32_bf16 v[102:105], v[148:151], v[196:199], v[102:105]
	v_mfma_f32_16x16x32_bf16 v[94:97], v[156:159], v[196:199], v[94:97]
	v_mfma_f32_16x16x32_bf16 v[86:89], v[148:151], v[204:207], v[86:89]
	v_mfma_f32_16x16x32_bf16 v[78:81], v[156:159], v[204:207], v[78:81]
	v_mfma_f32_16x16x32_bf16 v[118:121], v[160:163], v[176:179], v[118:121]
	v_mfma_f32_16x16x32_bf16 v[110:113], v[168:171], v[176:179], v[110:113]
	v_mfma_f32_16x16x32_bf16 v[98:101], v[160:163], v[184:187], v[98:101]
	v_mfma_f32_16x16x32_bf16 v[90:93], v[168:171], v[184:187], v[90:93]
	v_mfma_f32_16x16x32_bf16 v[82:85], v[160:163], v[192:195], v[82:85]
	v_mfma_f32_16x16x32_bf16 v[74:77], v[168:171], v[192:195], v[74:77]
	v_mfma_f32_16x16x32_bf16 v[70:73], v[160:163], v[200:203], v[70:73]
	v_mfma_f32_16x16x32_bf16 v[66:69], v[168:171], v[200:203], v[66:69]
	v_mfma_f32_16x16x32_bf16 v[118:121], v[164:167], v[180:183], v[118:121]
	v_mfma_f32_16x16x32_bf16 v[110:113], v[172:175], v[180:183], v[110:113]
	v_mfma_f32_16x16x32_bf16 v[98:101], v[164:167], v[188:191], v[98:101]
	v_mfma_f32_16x16x32_bf16 v[90:93], v[172:175], v[188:191], v[90:93]
	v_mfma_f32_16x16x32_bf16 v[82:85], v[164:167], v[196:199], v[82:85]
	v_mfma_f32_16x16x32_bf16 v[74:77], v[172:175], v[196:199], v[74:77]
	v_mfma_f32_16x16x32_bf16 v[70:73], v[164:167], v[204:207], v[70:73]
	v_mfma_f32_16x16x32_bf16 v[66:69], v[172:175], v[204:207], v[66:69]
	s_barrier
; #define PG8_STAGE(bufoff, gbase, rows) do { _Pragma("unroll") for (int _i = 0; _i < 2; ++_i) \
;         __builtin_amdgcn_global_load_lds((const unsigned*)((const char*)(gbase) + (rows)[_i]), (LAS unsigned*)(lds + (bufoff) + ldsw + _i * 8192), 16, 0, 0); } while (0)
; #define PG8_LDA(dst, b, h) do { _Pragma("unroll") for (int m = 0; m < 4; ++m) _Pragma("unroll") for (int k = 0; k < 2; ++k) dst[m][k] = *(const LAS bf16x8*)(lds + PG8_SA(b, h) + aoff + m * 2048 + k * 1024); } while (0)
; #define PG8_MMA(ai, bj, At, Bt) do { __builtin_amdgcn_s_setprio(1); _Pragma("unroll") for (int m = 0; m < 4; ++m) _Pragma("unroll") for (int n = 0; n < 2; ++n) _Pragma("unroll") for (int k = 0; k < 2; ++k) \
;         acc[ai][bj][m][n] = __builtin_amdgcn_mfma_f32_16x16x32_bf16(Bt[n][k], At[m][k], acc[ai][bj][m][n], 0, 0, 0); __builtin_amdgcn_s_setprio(0); } while (0)
; #define PG8_WAIT_V(n) asm volatile("s_waitcnt vmcnt(" #n ")" ::: "memory")
; #define PG8_WAIT_L(n) asm volatile("s_waitcnt lgkmcnt(" #n ")" ::: "memory")
; #define PG8_BAR __builtin_amdgcn_s_barrier()
; #define PG8_SCHED __builtin_amdgcn_sched_barrier(0)
; template <class Epi, class Sched>
; __device__ __forceinline__ void gemm_phase(LAS unsigned char* lds, const Sched& S, const Epi& E, const int tid) {
;     ...
;             PG8_LDA(At, 1, 1); PG8_STAGE(PG8_SB(1, 0), b3, vB); PG8_STAGE(PG8_SB(1, 1), b3 + hB, vB); PG8_STAGE(PG8_SA(1, 0), a3, vA);
;             PG8_WAIT_V(8); PG8_WAIT_L(0); PG8_BAR; PG8_MMA(1, 0, At, B0); PG8_MMA(1, 1, At, B1); PG8_BAR; PG8_SCHED;
;         }
;         if (wr == 0) PG8_BAR;
	s_add_i32 s18, s50, s24
	v_lshl_add_u64 v[208:209], v[208:209], 0, s[82:83]
	s_mov_b32 m0, s18
	ds_read_b128 v[176:179], v143 offset:49152
	ds_read_b128 v[180:183], v143 offset:50176
	ds_read_b128 v[184:187], v143 offset:51200
	ds_read_b128 v[188:191], v143 offset:52224
	ds_read_b128 v[192:195], v143 offset:53248
	ds_read_b128 v[196:199], v143 offset:54272
	ds_read_b128 v[200:203], v143 offset:55296
	ds_read_b128 v[204:207], v143 offset:56320
	global_load_lds_dwordx4 v[208:209], off
	s_add_i32 m0, s18, 0x2000
	s_add_u32 s16, s16, 0x158080
	v_lshl_add_u64 v[208:209], v[210:211], 0, s[82:83]
	s_addc_u32 s17, s17, 0
	s_add_i32 s18, s51, s24
	global_load_lds_dwordx4 v[208:209], off
	v_lshl_add_u64 v[208:209], s[16:17], 0, v[132:133]
	s_mov_b32 m0, s18
	s_nop 0
	global_load_lds_dwordx4 v[208:209], off
	v_lshl_add_u64 v[208:209], s[16:17], 0, v[136:137]
	s_add_i32 m0, s18, 0x2000
	s_nop 0
	global_load_lds_dwordx4 v[208:209], off
	v_lshl_add_u64 v[208:209], v[212:213], 0, s[82:83]
	s_mov_b32 m0, s40
	s_nop 0
	global_load_lds_dwordx4 v[208:209], off
	v_lshl_add_u64 v[208:209], v[214:215], 0, s[82:83]
	s_mov_b32 m0, s41
	s_nop 0
	global_load_lds_dwordx4 v[208:209], off
	s_waitcnt vmcnt(8)
	s_waitcnt lgkmcnt(0)
	s_barrier
	s_waitcnt lgkmcnt(0)
	v_mfma_f32_16x16x32_bf16 v[62:65], v[144:147], v[176:179], v[62:65]
	v_mfma_f32_16x16x32_bf16 v[58:61], v[152:155], v[176:179], v[58:61]
	v_mfma_f32_16x16x32_bf16 v[46:49], v[144:147], v[184:187], v[46:49]
	v_mfma_f32_16x16x32_bf16 v[38:41], v[152:155], v[184:187], v[38:41]
	v_mfma_f32_16x16x32_bf16 v[22:25], v[144:147], v[192:195], v[22:25]
	v_mfma_f32_16x16x32_bf16 v[14:17], v[152:155], v[192:195], v[14:17]
	v_mfma_f32_16x16x32_bf16 v[6:9], v[144:147], v[200:203], v[6:9]
	v_mfma_f32_16x16x32_bf16 v[2:5], v[152:155], v[200:203], v[2:5]
	v_mfma_f32_16x16x32_bf16 v[62:65], v[148:151], v[180:183], v[62:65]
	v_mfma_f32_16x16x32_bf16 v[58:61], v[156:159], v[180:183], v[58:61]
	v_mfma_f32_16x16x32_bf16 v[46:49], v[148:151], v[188:191], v[46:49]
	v_mfma_f32_16x16x32_bf16 v[38:41], v[156:159], v[188:191], v[38:41]
	v_mfma_f32_16x16x32_bf16 v[22:25], v[148:151], v[196:199], v[22:25]
	v_mfma_f32_16x16x32_bf16 v[14:17], v[156:159], v[196:199], v[14:17]
	v_mfma_f32_16x16x32_bf16 v[6:9], v[148:151], v[204:207], v[6:9]
	v_mfma_f32_16x16x32_bf16 v[2:5], v[156:159], v[204:207], v[2:5]
	v_mfma_f32_16x16x32_bf16 v[42:45], v[160:163], v[176:179], v[42:45]
	v_mfma_f32_16x16x32_bf16 v[34:37], v[168:171], v[176:179], v[34:37]
	v_mfma_f32_16x16x32_bf16 v[18:21], v[160:163], v[184:187], v[18:21]
	v_mfma_f32_16x16x32_bf16 v[10:13], v[168:171], v[184:187], v[10:13]
	v_mfma_f32_16x16x32_bf16 v[54:57], v[160:163], v[192:195], v[54:57]
	v_mfma_f32_16x16x32_bf16 v[50:53], v[168:171], v[192:195], v[50:53]
	v_mfma_f32_16x16x32_bf16 v[30:33], v[160:163], v[200:203], v[30:33]
	v_mfma_f32_16x16x32_bf16 v[26:29], v[168:171], v[200:203], v[26:29]
	v_mfma_f32_16x16x32_bf16 v[42:45], v[164:167], v[180:183], v[42:45]
	v_mfma_f32_16x16x32_bf16 v[34:37], v[172:175], v[180:183], v[34:37]
	v_mfma_f32_16x16x32_bf16 v[18:21], v[164:167], v[188:191], v[18:21]
	v_mfma_f32_16x16x32_bf16 v[10:13], v[172:175], v[188:191], v[10:13]
	v_mfma_f32_16x16x32_bf16 v[54:57], v[164:167], v[196:199], v[54:57]
	v_mfma_f32_16x16x32_bf16 v[50:53], v[172:175], v[196:199], v[50:53]
	v_mfma_f32_16x16x32_bf16 v[30:33], v[164:167], v[204:207], v[30:33]
	v_mfma_f32_16x16x32_bf16 v[26:29], v[172:175], v[204:207], v[26:29]
	s_barrier
	s_add_i32 s76, s76, 2
	s_add_u32 s14, s14, 0x100
	s_addc_u32 s15, s15, 0
	s_add_u32 s61, s61, 0x100
	s_addc_u32 s64, s64, 0
	s_cmpk_gt_u32 s76, 0x53
	s_cbranch_scc0 .LBB0_1248
	s_and_b64 vcc, exec, s[6:7]
	s_cbranch_vccz .LBB0_1251
	s_barrier

; #define PG8_WAIT_V(n) asm volatile("s_waitcnt vmcnt(" #n ")" ::: "memory")
; #define PG8_BAR __builtin_amdgcn_s_barrier()
; template <class Epi, class Sched>
; __device__ __forceinline__ void gemm_phase(LAS unsigned char* lds, const Sched& S, const Epi& E, const int tid) {
;     ...
;     PG8_WAIT_V(0);
;     PG8_BAR;
; __device__ __forceinline__ void xcd_barrier(const XcdBarrier& b) {
;     asm volatile("s_waitcnt vmcnt(0)" ::: "memory");
;     __syncthreads();
;     if (threadIdx.x == 0) {
.LBB0_1255:
	s_mov_b64 s[4:5], s[66:67]
	s_waitcnt vmcnt(0) lgkmcnt(0)
	s_setprio 0
	s_getreg_b32 s6, hwreg(HW_REG_XCC_ID, 0, 4)
	s_waitcnt vmcnt(0)
	s_waitcnt lgkmcnt(0)
	s_barrier
	s_and_saveexec_b64 s[0:1], s[26:27]
	s_cbranch_execnz .LBB0_1256
	s_getpc_b64 s[98:99]
